# first two DMA waits after each GEMM epilogue leave the epilogue stores in flight (counted vmcnt across the unit boundary); the phase's first unit keeps the original head and unpeeled loop
# baseline (speedup 1.0000x reference)
.LBB0_211:
	s_lshl_b32 s10, s10, 5
	s_and_b32 s16, s10, 0x60
	s_mov_b64 s[10:11], 0x80
	s_add_i32 m0, s23, 0x18000
	v_lshl_add_u64 v[6:7], v[6:7], 0, s[10:11]
	s_ashr_i32 s38, s86, 31
	s_lshl_b32 s13, s12, 13
	s_lshl_b32 s17, s16, 7
	s_waitcnt vmcnt(2)
	s_barrier
	global_load_lds_dwordx4 v[6:7], off
	v_lshl_add_u64 v[4:5], v[4:5], 0, s[10:11]
	s_add_i32 m0, s23, 0x1a000
	s_add_i32 s39, s23, 0x8000
	s_add_i32 s40, s23, 0xa000
	global_load_lds_dwordx4 v[4:5], off
	v_lshl_add_u64 v[0:1], v[0:1], 0, s[10:11]
	s_mov_b32 m0, s39
	s_add_u32 s14, s26, 0x40080
	global_load_lds_dwordx4 v[0:1], off
	v_lshl_add_u64 v[0:1], v[2:3], 0, s[10:11]
	s_mov_b32 m0, s40
	s_addc_u32 s15, s27, 0
	global_load_lds_dwordx4 v[0:1], off
	s_add_i32 m0, s23, 0x1c000
	v_lshl_add_u64 v[0:1], s[14:15], 0, v[132:133]
	global_load_lds_dwordx4 v[0:1], off
	v_lshl_add_u64 v[0:1], s[14:15], 0, v[128:129]
	s_add_i32 m0, s23, 0x1e000
	s_cmpk_lt_u32 s7, 0x100
	global_load_lds_dwordx4 v[0:1], off
	v_lshrrev_b32_e32 v1, 1, v9
	v_and_b32_e32 v1, 24, v1
	v_and_b32_e32 v0, 15, v9
	v_lshlrev_b32_e32 v2, 1, v1
	v_lshl_or_b32 v148, s12, 6, v0
	v_lshl_or_b32 v0, v0, 6, v2
	v_lshlrev_b32_e32 v2, 2, v9
	v_and_b32_e32 v2, 32, v2
	v_bitop3_b32 v3, v0, s13, v2 bitop3:0xde
	v_bitop3_b32 v149, v0, s17, v2 bitop3:0xde
	v_lshlrev_b32_e32 v0, 14, v13
	v_and_b32_e32 v0, 0xffff8000, v0
	v_or_b32_e32 v150, s16, v1
	v_lshl_add_u32 v0, v12, 11, v0
	v_and_b32_e32 v1, 1, v13
	v_lshl_or_b32 v0, v1, 6, v0
	v_lshl_add_u32 v136, v14, 1, v0
	v_lshlrev_b32_e32 v0, 14, v8
	v_and_b32_e32 v0, 0xffff8000, v0
	s_waitcnt vmcnt(6)
	v_lshl_add_u32 v0, v10, 11, v0
	v_and_b32_e32 v1, 1, v8
	s_cselect_b64 s[12:13], -1, 0
	v_lshl_or_b32 v0, v1, 6, v0
	s_add_i32 s42, 0, 0x10000
	s_add_i32 s43, 0, 0x14000
	s_sext_i32_i16 s45, s6
	s_mov_b32 s41, s86
	v_mov_b32_e32 v137, v133
	v_lshl_add_u32 v138, v11, 1, v0
	v_mov_b32_e32 v139, v133
	v_mov_b64_e32 v[140:141], 0xb00
	v_mov_b64_e32 v[142:143], 0xaff
	v_add_u32_e32 v151, s42, v149
	v_add_u32_e32 v152, s43, v149
	v_add_u32_e32 v153, 0, v3
	s_movk_i32 s44, 0x1600
	s_barrier
	v_sub_u32_e32 v136, v136, v252
	v_add_u32_e32 v136, v136, v134
	v_sub_u32_e32 v138, v138, v253
	v_add_u32_e32 v138, v138, v130
	v_and_b32_e32 v250, 63, v236
	v_and_b32_e32 v251, 15, v250
	v_lshrrev_b32_e32 v252, 4, v250
	v_and_b32_e32 v253, 7, v251
	v_xor_b32_e32 v252, v252, v253
	v_lshlrev_b32_e32 v252, 4, v252
	v_lshl_add_u32 v252, v251, 7, v252
	v_lshrrev_b32_e32 v250, 6, v236
	v_lshrrev_b32_e32 v251, 2, v250
	v_lshl_add_u32 v153, v251, 13, v252
	v_and_b32_e32 v251, 3, v250
	v_lshl_add_u32 v149, v251, 12, v252
	v_add_u32_e32 v151, s42, v149
	v_add_u32_e32 v152, s43, v149
	s_add_i32 s37, s37, 1
	s_mul_i32 s6, s37, s38
	s_mul_hi_u32 s7, s37, s41
	s_add_i32 s7, s7, s6
	s_mul_i32 s6, s37, s41
	s_add_u32 s18, s6, s96
	s_addc_u32 s19, s7, s31
	v_cmp_gt_i64_e32 vcc, s[18:19], v[142:143]
	v_cmp_lt_i64_e64 s[6:7], s[18:19], v[140:141]
	s_cbranch_vccnz .Lfu_216
	s_ashr_i32 s14, s18, 31
	s_lshr_b32 s14, s14, 29
	s_add_i32 s14, s18, s14
	s_ashr_i32 s15, s14, 3
	s_and_b32 s14, s14, -8
	s_sub_i32 s14, s18, s14
	s_cmp_lt_i32 s14, 0
	s_cselect_b32 s16, s33, 0x160
	s_mul_i32 s14, s14, s16
	s_add_i32 s14, s14, s15
	s_mul_hi_i32 s15, s14, 0x2e8ba2e9
	s_lshr_b32 s16, s15, 31
	s_ashr_i32 s15, s15, 5
	s_add_i32 s15, s15, s16
	s_lshl_b32 s16, s15, 3
	s_sub_i32 s17, 0x80, s16
	s_min_i32 s17, s17, 8
	s_abs_i32 s18, s17
	v_cvt_f32_u32_e32 v0, s18
	s_sub_i32 s20, 0, s18
	s_mulk_i32 s15, 0xb0
	s_sub_i32 s15, s14, s15
	v_rcp_iflag_f32_e32 v0, v0
	s_abs_i32 s14, s15
	s_xor_b32 s19, s15, s17
	s_ashr_i32 s19, s19, 31
	v_mul_f32_e32 v0, 0x4f7ffffe, v0
	v_cvt_u32_f32_e32 v0, v0
	s_nop 0
	v_readfirstlane_b32 s21, v0
	s_mul_i32 s20, s20, s21
	s_mul_hi_u32 s20, s21, s20
	s_add_i32 s21, s21, s20
	s_mul_hi_u32 s20, s14, s21
	s_mul_i32 s21, s20, s18
	s_sub_i32 s14, s14, s21
	s_add_i32 s28, s20, 1
	s_sub_i32 s21, s14, s18
	s_cmp_ge_u32 s14, s18
	s_cselect_b32 s20, s28, s20
	s_cselect_b32 s14, s21, s14
	s_add_i32 s21, s20, 1
	s_cmp_ge_u32 s14, s18
	s_cselect_b32 s14, s21, s20
	s_xor_b32 s14, s14, s19
	s_sub_i32 s14, s14, s19
	s_mul_i32 s17, s14, s17
	s_sub_i32 s15, s15, s17
	s_add_i32 s16, s16, s15
.Lfu_216:
	s_ashr_i32 s17, s16, 31
	s_lshl_b64 s[18:19], s[16:17], 19
	s_add_u32 s18, s90, s18
	s_addc_u32 s19, s91, s19
	s_and_b64 s[20:21], s[6:7], exec
	s_cselect_b32 s17, s19, s25
	s_cselect_b32 s46, s18, s24
	s_ashr_i32 s15, s14, 31
	s_lshl_b64 s[20:21], s[14:15], 19
	s_add_u32 s20, s2, s20
	s_addc_u32 s21, s3, s21
	s_and_b64 s[28:29], s[6:7], exec
	s_cselect_b32 s15, s21, s27
	s_cselect_b32 s47, s20, s26
	s_add_u32 s24, s24, 0x40080
	s_addc_u32 s25, s25, 0
	s_add_u32 s48, s26, 0x100
	v_mov_b32_e32 v0, 0
	s_addc_u32 s49, s27, 0
	s_mov_b32 s50, -2
	v_mov_b32_e32 v1, v0
	v_mov_b32_e32 v2, v0
	v_mov_b32_e32 v3, v0
	v_mov_b32_e32 v4, v0
	v_mov_b32_e32 v5, v0
	v_mov_b32_e32 v6, v0
	v_mov_b32_e32 v7, v0
	v_mov_b32_e32 v16, v0
	v_mov_b32_e32 v17, v0
	v_mov_b32_e32 v18, v0
	v_mov_b32_e32 v19, v0
	v_mov_b32_e32 v20, v0
	v_mov_b32_e32 v21, v0
	v_mov_b32_e32 v22, v0
	v_mov_b32_e32 v23, v0
	v_mov_b32_e32 v32, v0
	v_mov_b32_e32 v33, v0
	s_waitcnt lgkmcnt(0)
	v_mov_b32_e32 v34, v0
	v_mov_b32_e32 v35, v0
	v_mov_b32_e32 v36, v0
	v_mov_b32_e32 v37, v0
	v_mov_b32_e32 v38, v0
	v_mov_b32_e32 v39, v0
	v_mov_b32_e32 v48, v0
	v_mov_b32_e32 v49, v0
	v_mov_b32_e32 v50, v0
	v_mov_b32_e32 v51, v0
	v_mov_b32_e32 v52, v0
	v_mov_b32_e32 v53, v0
	v_mov_b32_e32 v54, v0
	v_mov_b32_e32 v55, v0
	v_mov_b32_e32 v8, v0
	v_mov_b32_e32 v9, v0
	v_mov_b32_e32 v10, v0
	v_mov_b32_e32 v11, v0
	v_mov_b32_e32 v12, v0
	v_mov_b32_e32 v13, v0
	v_mov_b32_e32 v14, v0
	v_mov_b32_e32 v15, v0
	v_mov_b32_e32 v24, v0
	v_mov_b32_e32 v25, v0
	v_mov_b32_e32 v26, v0
	v_mov_b32_e32 v27, v0
	v_mov_b32_e32 v28, v0
	v_mov_b32_e32 v29, v0
	v_mov_b32_e32 v30, v0
	v_mov_b32_e32 v31, v0
	v_mov_b32_e32 v40, v0
	v_mov_b32_e32 v41, v0
	v_mov_b32_e32 v42, v0
	v_mov_b32_e32 v43, v0
	v_mov_b32_e32 v44, v0
	v_mov_b32_e32 v45, v0
	v_mov_b32_e32 v46, v0
	v_mov_b32_e32 v47, v0
	v_mov_b32_e32 v56, v0
	v_mov_b32_e32 v57, v0
	v_mov_b32_e32 v58, v0
	v_mov_b32_e32 v59, v0
	v_mov_b32_e32 v60, v0
	v_mov_b32_e32 v61, v0
	v_mov_b32_e32 v62, v0
	v_mov_b32_e32 v63, v0
	v_mov_b32_e32 v64, v0
	v_mov_b32_e32 v65, v0
	v_mov_b32_e32 v66, v0
	v_mov_b32_e32 v67, v0
	v_mov_b32_e32 v68, v0
	v_mov_b32_e32 v69, v0
	v_mov_b32_e32 v70, v0
	v_mov_b32_e32 v71, v0
	v_mov_b32_e32 v80, v0
	v_mov_b32_e32 v81, v0
	v_mov_b32_e32 v82, v0
	v_mov_b32_e32 v83, v0
	v_mov_b32_e32 v84, v0
	v_mov_b32_e32 v85, v0
	v_mov_b32_e32 v86, v0
	v_mov_b32_e32 v87, v0
	v_mov_b32_e32 v96, v0
	v_mov_b32_e32 v97, v0
	v_mov_b32_e32 v98, v0
	v_mov_b32_e32 v99, v0
	v_mov_b32_e32 v100, v0
	v_mov_b32_e32 v101, v0
	v_mov_b32_e32 v102, v0
	v_mov_b32_e32 v103, v0
	v_mov_b32_e32 v112, v0
	v_mov_b32_e32 v113, v0
	v_mov_b32_e32 v114, v0
	v_mov_b32_e32 v115, v0
	v_mov_b32_e32 v116, v0
	v_mov_b32_e32 v117, v0
	v_mov_b32_e32 v118, v0
	v_mov_b32_e32 v119, v0
	v_mov_b32_e32 v72, v0
	v_mov_b32_e32 v73, v0
	v_mov_b32_e32 v74, v0
	v_mov_b32_e32 v75, v0
	v_mov_b32_e32 v76, v0
	v_mov_b32_e32 v77, v0
	v_mov_b32_e32 v78, v0
	v_mov_b32_e32 v79, v0
	v_mov_b32_e32 v88, v0
	v_mov_b32_e32 v89, v0
	v_mov_b32_e32 v90, v0
	v_mov_b32_e32 v91, v0
	v_mov_b32_e32 v92, v0
	v_mov_b32_e32 v93, v0
	v_mov_b32_e32 v94, v0
	v_mov_b32_e32 v95, v0
	v_mov_b32_e32 v104, v0
	v_mov_b32_e32 v105, v0
	v_mov_b32_e32 v106, v0
	v_mov_b32_e32 v107, v0
	v_mov_b32_e32 v108, v0
	v_mov_b32_e32 v109, v0
	v_mov_b32_e32 v110, v0
	v_mov_b32_e32 v111, v0
	v_mov_b32_e32 v120, v0
	v_mov_b32_e32 v121, v0
	v_mov_b32_e32 v122, v0
	v_mov_b32_e32 v123, v0
	v_mov_b32_e32 v124, v0
	v_mov_b32_e32 v125, v0
	v_mov_b32_e32 v126, v0
	v_mov_b32_e32 v127, v0
	v_xor_b32_e32 v246, 64, v153
	v_xor_b32_e32 v247, 64, v149
	v_add_u32_e32 v248, s42, v247
	v_add_u32_e32 v249, s43, v247
	s_branch .LBB0_217

.LBB0_214:
	s_add_u32 s24, s24, 0x40080
	s_addc_u32 s25, s25, 0
	s_add_u32 s48, s26, 0x100
	s_addc_u32 s49, s27, 0
	s_mov_b32 s50, -2
	s_waitcnt lgkmcnt(0)
	v_xor_b32_e32 v246, 64, v153
	v_xor_b32_e32 v247, 64, v149
	v_add_u32_e32 v248, s42, v247
	v_add_u32_e32 v249, s43, v247
	ds_read_b128 v[144:147], v151
	ds_read_b128 v[154:157], v248
	ds_read_b128 v[158:161], v151 offset:2048
	ds_read_b128 v[162:165], v248 offset:2048
	ds_read_b128 v[166:169], v152
	ds_read_b128 v[170:173], v249
	ds_read_b128 v[174:177], v152 offset:2048
	ds_read_b128 v[178:181], v249 offset:2048
	s_add_u32 s26, s24, 0xfffc0080
	s_addc_u32 s27, s25, -1
	s_cmp_eq_u32 s50, 12
	s_cselect_b32 s29, s17, s27
	s_cselect_b32 s28, s46, s26
	s_cselect_b32 s27, s15, s49
	s_cselect_b32 s26, s47, s48
	v_lshl_add_u64 v[214:215], s[24:25], 0, v[136:137]
	s_add_i32 m0, s23, 0xc000
	ds_read_b128 v[182:185], v153
	ds_read_b128 v[186:189], v246
	ds_read_b128 v[190:193], v153 offset:2048
	ds_read_b128 v[194:197], v246 offset:2048
	ds_read_b128 v[198:201], v153 offset:4096
	ds_read_b128 v[202:205], v246 offset:4096
	ds_read_b128 v[206:209], v153 offset:6144
	ds_read_b128 v[210:213], v246 offset:6144
	global_load_lds_dwordx4 v[214:215], off
	v_lshl_add_u64 v[214:215], s[24:25], 0, v[138:139]
	s_add_i32 m0, s23, 0xe000
	s_nop 0
	global_load_lds_dwordx4 v[214:215], off
	s_waitcnt vmcnt(16)
	s_waitcnt lgkmcnt(0)
	s_barrier
	s_setprio 0
	s_waitcnt lgkmcnt(0)
	v_mfma_f32_16x16x32_bf16 v[124:127], v[144:147], v[182:185], 0
	s_add_i32 s37, s37, 1
	s_mul_i32 s6, s37, s38
	s_mul_hi_u32 s7, s37, s41
	v_mfma_f32_16x16x32_bf16 v[120:123], v[158:161], v[182:185], 0
	s_add_i32 s7, s7, s6
	s_mul_i32 s6, s37, s41
	s_add_u32 s18, s6, s96
	v_mfma_f32_16x16x32_bf16 v[108:111], v[144:147], v[190:193], 0
	s_addc_u32 s19, s7, s31
	v_cmp_lt_i64_e64 s[6:7], s[18:19], v[140:141]
	s_ashr_i32 s14, s18, 31
	v_mfma_f32_16x16x32_bf16 v[104:107], v[158:161], v[190:193], 0
	s_lshr_b32 s14, s14, 29
	s_add_i32 s14, s18, s14
	s_ashr_i32 s15, s14, 3
	v_mfma_f32_16x16x32_bf16 v[92:95], v[144:147], v[198:201], 0
	s_and_b32 s14, s14, -8
	s_sub_i32 s14, s18, s14
	s_cmp_lt_i32 s14, 0
	v_mfma_f32_16x16x32_bf16 v[88:91], v[158:161], v[198:201], 0
	s_cselect_b32 s16, s33, 0x160
	s_mul_i32 s14, s14, s16
	s_add_i32 s14, s14, s15
	v_mfma_f32_16x16x32_bf16 v[76:79], v[144:147], v[206:209], 0
	s_mul_hi_i32 s15, s14, 0x2e8ba2e9
	s_lshr_b32 s16, s15, 31
	s_ashr_i32 s15, s15, 5
	v_mfma_f32_16x16x32_bf16 v[72:75], v[158:161], v[206:209], 0
	s_add_i32 s15, s15, s16
	s_lshl_b32 s16, s15, 3
	s_sub_i32 s17, 0x80, s16
	v_mfma_f32_16x16x32_bf16 v[124:127], v[154:157], v[186:189], v[124:127]
	s_min_i32 s17, s17, 8
	s_abs_i32 s18, s17
	v_cvt_f32_u32_e32 v252, s18
	v_mfma_f32_16x16x32_bf16 v[120:123], v[162:165], v[186:189], v[120:123]
	s_sub_i32 s20, 0, s18
	s_mulk_i32 s15, 0xb0
	s_sub_i32 s15, s14, s15
	v_mfma_f32_16x16x32_bf16 v[108:111], v[154:157], v[194:197], v[108:111]
	v_rcp_iflag_f32_e32 v252, v252
	s_abs_i32 s14, s15
	s_xor_b32 s19, s15, s17
	v_mfma_f32_16x16x32_bf16 v[104:107], v[162:165], v[194:197], v[104:107]
	s_ashr_i32 s19, s19, 31
	v_mul_f32_e32 v252, 0x4f7ffffe, v252
	v_cvt_u32_f32_e32 v252, v252
	v_mfma_f32_16x16x32_bf16 v[92:95], v[154:157], v[202:205], v[92:95]
	s_nop 0
	v_readfirstlane_b32 s21, v252
	s_mul_i32 s20, s20, s21
	v_mfma_f32_16x16x32_bf16 v[88:91], v[162:165], v[202:205], v[88:91]
	s_mul_hi_u32 s20, s21, s20
	s_add_i32 s21, s21, s20
	s_mul_hi_u32 s20, s14, s21
	v_mfma_f32_16x16x32_bf16 v[76:79], v[154:157], v[210:213], v[76:79]
	s_mul_i32 s21, s20, s18
	s_sub_i32 s14, s14, s21
	s_add_i32 s98, s20, 1
	v_mfma_f32_16x16x32_bf16 v[72:75], v[162:165], v[210:213], v[72:75]
	s_sub_i32 s21, s14, s18
	s_cmp_ge_u32 s14, s18
	s_cselect_b32 s20, s98, s20
	s_setprio 0
	s_setprio 0
	v_mfma_f32_16x16x32_bf16 v[116:119], v[166:169], v[182:185], 0
	s_cselect_b32 s14, s21, s14
	s_add_i32 s21, s20, 1
	s_cmp_ge_u32 s14, s18
	v_mfma_f32_16x16x32_bf16 v[112:115], v[174:177], v[182:185], 0
	s_cselect_b32 s14, s21, s20
	s_xor_b32 s14, s14, s19
	s_sub_i32 s14, s14, s19
	v_mfma_f32_16x16x32_bf16 v[100:103], v[166:169], v[190:193], 0
	s_mul_i32 s17, s14, s17
	s_sub_i32 s15, s15, s17
	s_add_i32 s16, s16, s15
	v_mfma_f32_16x16x32_bf16 v[96:99], v[174:177], v[190:193], 0
	s_ashr_i32 s17, s16, 31
	s_lshl_b64 s[18:19], s[16:17], 19
	s_add_u32 s18, s90, s18
	v_mfma_f32_16x16x32_bf16 v[84:87], v[166:169], v[198:201], 0
	s_addc_u32 s19, s91, s19
	s_and_b64 s[20:21], s[6:7], exec
	s_cselect_b32 s17, s19, s25
	v_mfma_f32_16x16x32_bf16 v[80:83], v[174:177], v[198:201], 0
	s_cselect_b32 s46, s18, s24
	s_ashr_i32 s15, s14, 31
	s_lshl_b64 s[20:21], s[14:15], 19
	v_mfma_f32_16x16x32_bf16 v[68:71], v[166:169], v[206:209], 0
	s_add_u32 s20, s2, s20
	s_addc_u32 s21, s3, s21
	s_and_b64 s[98:99], s[6:7], exec
	v_mfma_f32_16x16x32_bf16 v[64:67], v[174:177], v[206:209], 0
	s_cselect_b32 s15, s21, s27
	s_cselect_b32 s47, s20, s26
	v_mfma_f32_16x16x32_bf16 v[116:119], v[170:173], v[186:189], v[116:119]
	v_mfma_f32_16x16x32_bf16 v[112:115], v[178:181], v[186:189], v[112:115]
	v_mfma_f32_16x16x32_bf16 v[100:103], v[170:173], v[194:197], v[100:103]
	v_mfma_f32_16x16x32_bf16 v[96:99], v[178:181], v[194:197], v[96:99]
	v_mfma_f32_16x16x32_bf16 v[84:87], v[170:173], v[202:205], v[84:87]
	v_mfma_f32_16x16x32_bf16 v[80:83], v[178:181], v[202:205], v[80:83]
	v_mfma_f32_16x16x32_bf16 v[68:71], v[170:173], v[210:213], v[68:71]
	v_mfma_f32_16x16x32_bf16 v[64:67], v[178:181], v[210:213], v[64:67]
	s_setprio 0
	s_barrier
	s_add_i32 s51, s42, s30
	v_lshl_add_u64 v[214:215], s[26:27], 0, v[132:133]
	s_mov_b32 m0, s51
	ds_read_b128 v[182:185], v153 offset:16384
	ds_read_b128 v[186:189], v246 offset:16384
	ds_read_b128 v[190:193], v153 offset:18432
	ds_read_b128 v[194:197], v246 offset:18432
	ds_read_b128 v[198:201], v153 offset:20480
	ds_read_b128 v[202:205], v246 offset:20480
	ds_read_b128 v[206:209], v153 offset:22528
	ds_read_b128 v[210:213], v246 offset:22528
	global_load_lds_dwordx4 v[214:215], off
	s_add_i32 m0, s51, 0x2000
	s_add_u32 s52, s26, 0x40000
	v_lshl_add_u64 v[216:217], s[26:27], 0, v[128:129]
	s_addc_u32 s53, s27, 0
	s_add_i32 s51, s43, s30
	global_load_lds_dwordx4 v[216:217], off
	v_lshl_add_u64 v[218:219], s[52:53], 0, v[132:133]
	s_mov_b32 m0, s51
	v_lshl_add_u64 v[220:221], s[28:29], 0, v[130:131]
	global_load_lds_dwordx4 v[218:219], off
	v_lshl_add_u64 v[218:219], s[52:53], 0, v[128:129]
	s_add_i32 m0, s51, 0x2000
	s_nop 0
	global_load_lds_dwordx4 v[218:219], off
	v_lshl_add_u64 v[218:219], s[28:29], 0, v[134:135]
	s_mov_b32 m0, s23
	s_nop 0
	global_load_lds_dwordx4 v[218:219], off
	s_mov_b32 m0, s34
	s_nop 0
	global_load_lds_dwordx4 v[220:221], off
	s_waitcnt vmcnt(16)
	s_waitcnt lgkmcnt(0)
	s_barrier
	s_setprio 0
	s_waitcnt lgkmcnt(0)
	v_mfma_f32_16x16x32_bf16 v[60:63], v[144:147], v[182:185], 0
	v_mfma_f32_16x16x32_bf16 v[56:59], v[158:161], v[182:185], 0
	v_mfma_f32_16x16x32_bf16 v[44:47], v[144:147], v[190:193], 0
	v_mfma_f32_16x16x32_bf16 v[40:43], v[158:161], v[190:193], 0
	v_mfma_f32_16x16x32_bf16 v[28:31], v[144:147], v[198:201], 0
	v_mfma_f32_16x16x32_bf16 v[24:27], v[158:161], v[198:201], 0
	v_mfma_f32_16x16x32_bf16 v[12:15], v[144:147], v[206:209], 0
	v_mfma_f32_16x16x32_bf16 v[8:11], v[158:161], v[206:209], 0
	v_mfma_f32_16x16x32_bf16 v[60:63], v[154:157], v[186:189], v[60:63]
	v_mfma_f32_16x16x32_bf16 v[56:59], v[162:165], v[186:189], v[56:59]
	v_mfma_f32_16x16x32_bf16 v[44:47], v[154:157], v[194:197], v[44:47]
	v_mfma_f32_16x16x32_bf16 v[40:43], v[162:165], v[194:197], v[40:43]
	v_mfma_f32_16x16x32_bf16 v[28:31], v[154:157], v[202:205], v[28:31]
	v_mfma_f32_16x16x32_bf16 v[24:27], v[162:165], v[202:205], v[24:27]
	v_mfma_f32_16x16x32_bf16 v[12:15], v[154:157], v[210:213], v[12:15]
	v_mfma_f32_16x16x32_bf16 v[8:11], v[162:165], v[210:213], v[8:11]
	s_setprio 0
	s_setprio 0
	v_mfma_f32_16x16x32_bf16 v[52:55], v[166:169], v[182:185], 0
	v_mfma_f32_16x16x32_bf16 v[48:51], v[174:177], v[182:185], 0
	v_mfma_f32_16x16x32_bf16 v[36:39], v[166:169], v[190:193], 0
	v_mfma_f32_16x16x32_bf16 v[32:35], v[174:177], v[190:193], 0
	v_mfma_f32_16x16x32_bf16 v[20:23], v[166:169], v[198:201], 0
	v_mfma_f32_16x16x32_bf16 v[16:19], v[174:177], v[198:201], 0
	v_mfma_f32_16x16x32_bf16 v[4:7], v[166:169], v[206:209], 0
	v_mfma_f32_16x16x32_bf16 v[0:3], v[174:177], v[206:209], 0
	v_mfma_f32_16x16x32_bf16 v[52:55], v[170:173], v[186:189], v[52:55]
	v_mfma_f32_16x16x32_bf16 v[48:51], v[178:181], v[186:189], v[48:51]
	v_mfma_f32_16x16x32_bf16 v[36:39], v[170:173], v[194:197], v[36:39]
	v_mfma_f32_16x16x32_bf16 v[32:35], v[178:181], v[194:197], v[32:35]
	v_mfma_f32_16x16x32_bf16 v[20:23], v[170:173], v[202:205], v[20:23]
	v_mfma_f32_16x16x32_bf16 v[16:19], v[178:181], v[202:205], v[16:19]
	v_mfma_f32_16x16x32_bf16 v[4:7], v[170:173], v[210:213], v[4:7]
	v_mfma_f32_16x16x32_bf16 v[0:3], v[178:181], v[210:213], v[0:3]
	s_setprio 0
	s_barrier
	s_add_i32 s51, 0, 0x18000
	s_add_i32 s52, 0, 0x1c000
	v_add_u32_e32 v162, s51, v149
	v_add_u32_e32 v250, s51, v247
	v_add_u32_e32 v178, s52, v149
	v_add_u32_e32 v251, s52, v247
	ds_read_b128 v[144:147], v162
	ds_read_b128 v[154:157], v250
	ds_read_b128 v[158:161], v162 offset:2048
	ds_read_b128 v[162:165], v250 offset:2048
	ds_read_b128 v[166:169], v178
	ds_read_b128 v[170:173], v251
	ds_read_b128 v[174:177], v178 offset:2048
	ds_read_b128 v[178:181], v251 offset:2048
	s_add_u32 s28, s28, 0x40000
	s_addc_u32 s29, s29, 0
	s_mov_b32 m0, s35
	v_lshl_add_u64 v[222:223], s[28:29], 0, v[134:135]
	ds_read_b128 v[182:185], v153 offset:32768
	ds_read_b128 v[186:189], v246 offset:32768
	ds_read_b128 v[190:193], v153 offset:34816
	ds_read_b128 v[194:197], v246 offset:34816
	ds_read_b128 v[198:201], v153 offset:36864
	ds_read_b128 v[202:205], v246 offset:36864
	ds_read_b128 v[206:209], v153 offset:38912
	ds_read_b128 v[210:213], v246 offset:38912
	global_load_lds_dwordx4 v[222:223], off
	v_lshl_add_u64 v[222:223], s[28:29], 0, v[130:131]
	s_mov_b32 m0, s36
	s_nop 0
	global_load_lds_dwordx4 v[222:223], off
	s_waitcnt vmcnt(8)
	s_waitcnt lgkmcnt(0)
	s_barrier
	s_setprio 0
	s_waitcnt lgkmcnt(0)
	v_mfma_f32_16x16x32_bf16 v[124:127], v[144:147], v[182:185], v[124:127]
	v_mfma_f32_16x16x32_bf16 v[120:123], v[158:161], v[182:185], v[120:123]
	v_mfma_f32_16x16x32_bf16 v[108:111], v[144:147], v[190:193], v[108:111]
	v_mfma_f32_16x16x32_bf16 v[104:107], v[158:161], v[190:193], v[104:107]
	v_mfma_f32_16x16x32_bf16 v[92:95], v[144:147], v[198:201], v[92:95]
	v_mfma_f32_16x16x32_bf16 v[88:91], v[158:161], v[198:201], v[88:91]
	v_mfma_f32_16x16x32_bf16 v[76:79], v[144:147], v[206:209], v[76:79]
	v_mfma_f32_16x16x32_bf16 v[72:75], v[158:161], v[206:209], v[72:75]
	v_mfma_f32_16x16x32_bf16 v[124:127], v[154:157], v[186:189], v[124:127]
	v_mfma_f32_16x16x32_bf16 v[120:123], v[162:165], v[186:189], v[120:123]
	v_mfma_f32_16x16x32_bf16 v[108:111], v[154:157], v[194:197], v[108:111]
	v_mfma_f32_16x16x32_bf16 v[104:107], v[162:165], v[194:197], v[104:107]
	v_mfma_f32_16x16x32_bf16 v[92:95], v[154:157], v[202:205], v[92:95]
	v_mfma_f32_16x16x32_bf16 v[88:91], v[162:165], v[202:205], v[88:91]
	v_mfma_f32_16x16x32_bf16 v[76:79], v[154:157], v[210:213], v[76:79]
	v_mfma_f32_16x16x32_bf16 v[72:75], v[162:165], v[210:213], v[72:75]
	s_setprio 0
	s_setprio 0
	v_mfma_f32_16x16x32_bf16 v[116:119], v[166:169], v[182:185], v[116:119]
	v_mfma_f32_16x16x32_bf16 v[112:115], v[174:177], v[182:185], v[112:115]
	v_mfma_f32_16x16x32_bf16 v[100:103], v[166:169], v[190:193], v[100:103]
	v_mfma_f32_16x16x32_bf16 v[96:99], v[174:177], v[190:193], v[96:99]
	v_mfma_f32_16x16x32_bf16 v[84:87], v[166:169], v[198:201], v[84:87]
	v_mfma_f32_16x16x32_bf16 v[80:83], v[174:177], v[198:201], v[80:83]
	v_mfma_f32_16x16x32_bf16 v[68:71], v[166:169], v[206:209], v[68:71]
	v_mfma_f32_16x16x32_bf16 v[64:67], v[174:177], v[206:209], v[64:67]
	v_mfma_f32_16x16x32_bf16 v[116:119], v[170:173], v[186:189], v[116:119]
	v_mfma_f32_16x16x32_bf16 v[112:115], v[178:181], v[186:189], v[112:115]
	v_mfma_f32_16x16x32_bf16 v[100:103], v[170:173], v[194:197], v[100:103]
	v_mfma_f32_16x16x32_bf16 v[96:99], v[178:181], v[194:197], v[96:99]
	v_mfma_f32_16x16x32_bf16 v[84:87], v[170:173], v[202:205], v[84:87]
	v_mfma_f32_16x16x32_bf16 v[80:83], v[178:181], v[202:205], v[80:83]
	v_mfma_f32_16x16x32_bf16 v[68:71], v[170:173], v[210:213], v[68:71]
	v_mfma_f32_16x16x32_bf16 v[64:67], v[178:181], v[210:213], v[64:67]
	s_setprio 0
	s_barrier
	s_add_i32 s28, s51, s30
	v_lshl_add_u64 v[214:215], v[214:215], 0, s[10:11]
	s_mov_b32 m0, s28
	ds_read_b128 v[182:185], v153 offset:49152
	ds_read_b128 v[186:189], v246 offset:49152
	ds_read_b128 v[190:193], v153 offset:51200
	ds_read_b128 v[194:197], v246 offset:51200
	ds_read_b128 v[198:201], v153 offset:53248
	ds_read_b128 v[202:205], v246 offset:53248
	ds_read_b128 v[206:209], v153 offset:55296
	ds_read_b128 v[210:213], v246 offset:55296
	global_load_lds_dwordx4 v[214:215], off
	s_add_i32 m0, s28, 0x2000
	s_add_u32 s26, s26, 0x40080
	v_lshl_add_u64 v[214:215], v[216:217], 0, s[10:11]
	s_addc_u32 s27, s27, 0
	s_add_i32 s28, s52, s30
	global_load_lds_dwordx4 v[214:215], off
	v_lshl_add_u64 v[214:215], s[26:27], 0, v[132:133]
	s_mov_b32 m0, s28
	s_nop 0
	global_load_lds_dwordx4 v[214:215], off
	v_lshl_add_u64 v[214:215], s[26:27], 0, v[128:129]
	s_add_i32 m0, s28, 0x2000
	s_nop 0
	global_load_lds_dwordx4 v[214:215], off
	v_lshl_add_u64 v[214:215], v[218:219], 0, s[10:11]
	s_mov_b32 m0, s39
	s_nop 0
	global_load_lds_dwordx4 v[214:215], off
	v_lshl_add_u64 v[214:215], v[220:221], 0, s[10:11]
	s_mov_b32 m0, s40
	s_nop 0
	global_load_lds_dwordx4 v[214:215], off
	s_waitcnt vmcnt(8)
	s_waitcnt lgkmcnt(0)
	s_barrier
	s_setprio 0
	s_waitcnt lgkmcnt(0)
	v_mfma_f32_16x16x32_bf16 v[60:63], v[144:147], v[182:185], v[60:63]
	v_mfma_f32_16x16x32_bf16 v[56:59], v[158:161], v[182:185], v[56:59]
	v_mfma_f32_16x16x32_bf16 v[44:47], v[144:147], v[190:193], v[44:47]
	v_mfma_f32_16x16x32_bf16 v[40:43], v[158:161], v[190:193], v[40:43]
	v_mfma_f32_16x16x32_bf16 v[28:31], v[144:147], v[198:201], v[28:31]
	v_mfma_f32_16x16x32_bf16 v[24:27], v[158:161], v[198:201], v[24:27]
	v_mfma_f32_16x16x32_bf16 v[12:15], v[144:147], v[206:209], v[12:15]
	v_mfma_f32_16x16x32_bf16 v[8:11], v[158:161], v[206:209], v[8:11]
	v_mfma_f32_16x16x32_bf16 v[60:63], v[154:157], v[186:189], v[60:63]
	v_mfma_f32_16x16x32_bf16 v[56:59], v[162:165], v[186:189], v[56:59]
	v_mfma_f32_16x16x32_bf16 v[44:47], v[154:157], v[194:197], v[44:47]
	v_mfma_f32_16x16x32_bf16 v[40:43], v[162:165], v[194:197], v[40:43]
	v_mfma_f32_16x16x32_bf16 v[28:31], v[154:157], v[202:205], v[28:31]
	v_mfma_f32_16x16x32_bf16 v[24:27], v[162:165], v[202:205], v[24:27]
	v_mfma_f32_16x16x32_bf16 v[12:15], v[154:157], v[210:213], v[12:15]
	v_mfma_f32_16x16x32_bf16 v[8:11], v[162:165], v[210:213], v[8:11]
	s_setprio 0
	s_setprio 0
	v_mfma_f32_16x16x32_bf16 v[52:55], v[166:169], v[182:185], v[52:55]
	v_mfma_f32_16x16x32_bf16 v[48:51], v[174:177], v[182:185], v[48:51]
	v_mfma_f32_16x16x32_bf16 v[36:39], v[166:169], v[190:193], v[36:39]
	v_mfma_f32_16x16x32_bf16 v[32:35], v[174:177], v[190:193], v[32:35]
	v_mfma_f32_16x16x32_bf16 v[20:23], v[166:169], v[198:201], v[20:23]
	v_mfma_f32_16x16x32_bf16 v[16:19], v[174:177], v[198:201], v[16:19]
	v_mfma_f32_16x16x32_bf16 v[4:7], v[166:169], v[206:209], v[4:7]
	v_mfma_f32_16x16x32_bf16 v[0:3], v[174:177], v[206:209], v[0:3]
	v_mfma_f32_16x16x32_bf16 v[52:55], v[170:173], v[186:189], v[52:55]
	v_mfma_f32_16x16x32_bf16 v[48:51], v[178:181], v[186:189], v[48:51]
	v_mfma_f32_16x16x32_bf16 v[36:39], v[170:173], v[194:197], v[36:39]
	v_mfma_f32_16x16x32_bf16 v[32:35], v[178:181], v[194:197], v[32:35]
	v_mfma_f32_16x16x32_bf16 v[20:23], v[170:173], v[202:205], v[20:23]
	v_mfma_f32_16x16x32_bf16 v[16:19], v[178:181], v[202:205], v[16:19]
	v_mfma_f32_16x16x32_bf16 v[4:7], v[170:173], v[210:213], v[4:7]
	v_mfma_f32_16x16x32_bf16 v[0:3], v[178:181], v[210:213], v[0:3]
	s_setprio 0
	s_barrier
	s_add_i32 s50, s50, 2
	s_add_u32 s24, s24, 0x100
	s_addc_u32 s25, s25, 0
	s_add_u32 s48, s48, 0x100
	s_addc_u32 s49, s49, 0
	s_cmp_gt_u32 s50, 13

.LBB0_282:
	s_add_u32 s34, s82, 0x12000
	s_addc_u32 s35, s83, 0
	s_lshl_b32 s9, s9, 5
	s_mov_b64 s[12:13], 0x80
	s_and_b32 s9, s9, 0x60
	s_add_i32 m0, s28, 0x18000
	v_lshl_add_u64 v[6:7], v[6:7], 0, s[12:13]
	s_ashr_i32 s36, s86, 31
	s_lshl_b32 s15, s7, 13
	s_lshl_b32 s22, s9, 7
	s_waitcnt vmcnt(2)
	s_barrier
	global_load_lds_dwordx4 v[6:7], off
	v_lshl_add_u64 v[4:5], v[4:5], 0, s[12:13]
	s_add_i32 m0, s28, 0x1a000
	s_add_i32 s37, s28, 0x8000
	s_add_i32 s38, s28, 0xa000
	global_load_lds_dwordx4 v[4:5], off
	v_lshl_add_u64 v[0:1], v[0:1], 0, s[12:13]
	s_mov_b32 m0, s37
	s_add_u32 s16, s20, 0xb0080
	global_load_lds_dwordx4 v[0:1], off
	v_lshl_add_u64 v[0:1], v[2:3], 0, s[12:13]
	s_mov_b32 m0, s38
	s_addc_u32 s17, s21, 0
	global_load_lds_dwordx4 v[0:1], off
	s_add_i32 m0, s28, 0x1c000
	v_lshl_add_u64 v[0:1], s[16:17], 0, v[132:133]
	global_load_lds_dwordx4 v[0:1], off
	v_lshl_add_u64 v[0:1], s[16:17], 0, v[128:129]
	s_add_i32 m0, s28, 0x1e000
	s_cmpk_lt_u32 s6, 0x100
	global_load_lds_dwordx4 v[0:1], off
	v_lshrrev_b32_e32 v1, 1, v9
	v_and_b32_e32 v1, 24, v1
	v_and_b32_e32 v0, 15, v9
	v_lshlrev_b32_e32 v2, 1, v1
	v_lshl_or_b32 v166, s7, 6, v0
	v_lshl_or_b32 v0, v0, 6, v2
	v_lshlrev_b32_e32 v2, 2, v9
	v_and_b32_e32 v2, 32, v2
	v_bitop3_b32 v3, v0, s15, v2 bitop3:0xde
	v_bitop3_b32 v167, v0, s22, v2 bitop3:0xde
	v_or_b32_e32 v168, s9, v1
	v_lshrrev_b32_e32 v1, 1, v14
	v_mul_lo_u32 v0, v13, s8
	s_mov_b32 s9, 0xb000
	v_mad_u64_u32 v[0:1], s[6:7], v1, s9, v[0:1]
	v_or_b32_e32 v0, v0, v15
	s_mov_b64 s[16:17], 0xb0080
	v_add_lshl_u32 v0, v0, v16, 1
	v_mov_b32_e32 v1, v133
	v_lshl_add_u64 v[136:137], v[0:1], 0, s[16:17]
	v_lshrrev_b32_e32 v1, 1, v8
	v_mul_lo_u32 v0, v10, s8
	v_mad_u64_u32 v[0:1], s[6:7], v1, s9, v[0:1]
	s_waitcnt vmcnt(6)
	v_or_b32_e32 v0, v0, v11
	s_sext_i32_i8 s45, s14
	s_cselect_b64 s[14:15], -1, 0
	v_add_lshl_u32 v0, v0, v12, 1
	v_mov_b32_e32 v1, v133
	s_add_i32 s40, 0, 0x10000
	s_add_i32 s41, 0, 0x14000
	s_mov_b32 s39, s86
	v_lshl_add_u64 v[138:139], v[0:1], 0, s[16:17]
	v_mov_b64_e32 v[140:141], 0x200
	v_mov_b64_e32 v[142:143], 0x1ff
	v_add_u32_e32 v169, s40, v167
	v_add_u32_e32 v170, s41, v167
	v_add_u32_e32 v171, 0, v3
	s_barrier
	v_sub_u32_e32 v136, v136, v252
	v_add_u32_e32 v136, v136, v134
	v_sub_u32_e32 v138, v138, v253
	v_add_u32_e32 v138, v138, v130
	v_and_b32_e32 v250, 63, v236
	v_and_b32_e32 v251, 15, v250
	v_lshrrev_b32_e32 v252, 4, v250
	v_and_b32_e32 v253, 7, v251
	v_xor_b32_e32 v252, v252, v253
	v_lshlrev_b32_e32 v252, 4, v252
	v_lshl_add_u32 v252, v251, 7, v252
	v_lshrrev_b32_e32 v250, 6, v236
	v_lshrrev_b32_e32 v251, 2, v250
	v_lshl_add_u32 v171, v251, 13, v252
	v_and_b32_e32 v251, 3, v250
	v_lshl_add_u32 v167, v251, 12, v252
	v_add_u32_e32 v169, s40, v167
	v_add_u32_e32 v170, s41, v167
	s_add_i32 s33, s33, 1
	s_mul_i32 s6, s33, s36
	s_mul_hi_u32 s7, s33, s39
	s_add_i32 s7, s7, s6
	s_mul_i32 s6, s33, s39
	s_add_u32 s6, s6, s96
	s_addc_u32 s7, s7, s27
	v_cmp_gt_i64_e32 vcc, s[6:7], v[142:143]
	v_cmp_lt_i64_e64 s[8:9], s[6:7], v[140:141]
	s_cbranch_vccnz .Lfu_291
	s_ashr_i32 s7, s6, 31
	s_lshr_b32 s7, s7, 29
	s_add_i32 s16, s6, s7
	s_and_b32 s7, s16, -8
	s_sub_i32 s17, s6, s7
	s_cmp_gt_i32 s17, -1
	s_mov_b64 s[6:7], -1
	s_cbranch_scc0 .Lfu_288
	s_lshl_b32 s22, s17, 6
	s_mov_b64 s[6:7], 0

.Lfu_295:
	s_add_u32 s46, s20, 0x100
	v_mov_b32_e32 v0, 0
	s_addc_u32 s47, s21, 0
	s_mov_b32 s48, -2
	v_mov_b32_e32 v1, v0
	v_mov_b32_e32 v2, v0
	v_mov_b32_e32 v3, v0
	v_mov_b32_e32 v4, v0
	v_mov_b32_e32 v5, v0
	v_mov_b32_e32 v6, v0
	v_mov_b32_e32 v7, v0
	v_mov_b32_e32 v12, v0
	v_mov_b32_e32 v13, v0
	v_mov_b32_e32 v14, v0
	v_mov_b32_e32 v15, v0
	v_mov_b32_e32 v20, v0
	v_mov_b32_e32 v21, v0
	v_mov_b32_e32 v22, v0
	v_mov_b32_e32 v23, v0
	v_mov_b32_e32 v28, v0
	v_mov_b32_e32 v29, v0
	v_mov_b32_e32 v30, v0
	v_mov_b32_e32 v31, v0
	v_mov_b32_e32 v36, v0
	v_mov_b32_e32 v37, v0
	v_mov_b32_e32 v38, v0
	v_mov_b32_e32 v39, v0
	v_mov_b32_e32 v44, v0
	v_mov_b32_e32 v45, v0
	v_mov_b32_e32 v46, v0
	v_mov_b32_e32 v47, v0
	v_mov_b32_e32 v52, v0
	v_mov_b32_e32 v53, v0
	v_mov_b32_e32 v54, v0
	v_mov_b32_e32 v55, v0
	v_mov_b32_e32 v8, v0
	v_mov_b32_e32 v9, v0
	v_mov_b32_e32 v10, v0
	v_mov_b32_e32 v11, v0
	v_mov_b32_e32 v16, v0
	v_mov_b32_e32 v17, v0
	v_mov_b32_e32 v18, v0
	v_mov_b32_e32 v19, v0
	v_mov_b32_e32 v24, v0
	v_mov_b32_e32 v25, v0
	v_mov_b32_e32 v26, v0
	v_mov_b32_e32 v27, v0
	v_mov_b32_e32 v32, v0
	v_mov_b32_e32 v33, v0
	s_waitcnt lgkmcnt(0)
	v_mov_b32_e32 v34, v0
	v_mov_b32_e32 v35, v0
	v_mov_b32_e32 v40, v0
	v_mov_b32_e32 v41, v0
	v_mov_b32_e32 v42, v0
	v_mov_b32_e32 v43, v0
	v_mov_b32_e32 v48, v0
	v_mov_b32_e32 v49, v0
	v_mov_b32_e32 v50, v0
	v_mov_b32_e32 v51, v0
	v_mov_b32_e32 v56, v0
	v_mov_b32_e32 v57, v0
	v_mov_b32_e32 v58, v0
	v_mov_b32_e32 v59, v0
	v_mov_b32_e32 v60, v0
	v_mov_b32_e32 v61, v0
	v_mov_b32_e32 v62, v0
	v_mov_b32_e32 v63, v0
	v_mov_b32_e32 v64, v0
	v_mov_b32_e32 v65, v0
	v_mov_b32_e32 v66, v0
	v_mov_b32_e32 v67, v0
	v_mov_b32_e32 v68, v0
	v_mov_b32_e32 v69, v0
	v_mov_b32_e32 v70, v0
	v_mov_b32_e32 v71, v0
	v_mov_b32_e32 v76, v0
	v_mov_b32_e32 v77, v0
	v_mov_b32_e32 v78, v0
	v_mov_b32_e32 v79, v0
	v_mov_b32_e32 v84, v0
	v_mov_b32_e32 v85, v0
	v_mov_b32_e32 v86, v0
	v_mov_b32_e32 v87, v0
	v_mov_b32_e32 v92, v0
	v_mov_b32_e32 v93, v0
	v_mov_b32_e32 v94, v0
	v_mov_b32_e32 v95, v0
	v_mov_b32_e32 v100, v0
	v_mov_b32_e32 v101, v0
	v_mov_b32_e32 v102, v0
	v_mov_b32_e32 v103, v0
	v_mov_b32_e32 v104, v0
	v_mov_b32_e32 v105, v0
	v_mov_b32_e32 v106, v0
	v_mov_b32_e32 v107, v0
	v_mov_b32_e32 v108, v0
	v_mov_b32_e32 v109, v0
	v_mov_b32_e32 v110, v0
	v_mov_b32_e32 v111, v0
	v_mov_b32_e32 v72, v0
	v_mov_b32_e32 v73, v0
	v_mov_b32_e32 v74, v0
	v_mov_b32_e32 v75, v0
	v_mov_b32_e32 v80, v0
	v_mov_b32_e32 v81, v0
	v_mov_b32_e32 v82, v0
	v_mov_b32_e32 v83, v0
	v_mov_b32_e32 v88, v0
	v_mov_b32_e32 v89, v0
	v_mov_b32_e32 v90, v0
	v_mov_b32_e32 v91, v0
	v_mov_b32_e32 v96, v0
	v_mov_b32_e32 v97, v0
	v_mov_b32_e32 v98, v0
	v_mov_b32_e32 v99, v0
	v_mov_b32_e32 v112, v0
	v_mov_b32_e32 v113, v0
	v_mov_b32_e32 v114, v0
	v_mov_b32_e32 v115, v0
	v_mov_b32_e32 v116, v0
	v_mov_b32_e32 v117, v0
	v_mov_b32_e32 v118, v0
	v_mov_b32_e32 v119, v0
	v_mov_b32_e32 v120, v0
	v_mov_b32_e32 v121, v0
	v_mov_b32_e32 v122, v0
	v_mov_b32_e32 v123, v0
	v_mov_b32_e32 v124, v0
	v_mov_b32_e32 v125, v0
	v_mov_b32_e32 v126, v0
	v_mov_b32_e32 v127, v0
	v_xor_b32_e32 v246, 64, v171
	v_xor_b32_e32 v247, 64, v167
	v_add_u32_e32 v248, s40, v247
	v_add_u32_e32 v249, s41, v247
	s_branch .LBB0_296

.LBB0_295:
	s_add_u32 s46, s20, 0x100
	s_addc_u32 s47, s21, 0
	s_mov_b32 s48, -2
	s_waitcnt lgkmcnt(0)
	v_xor_b32_e32 v246, 64, v171
	v_xor_b32_e32 v247, 64, v167
	v_add_u32_e32 v248, s40, v247
	v_add_u32_e32 v249, s41, v247
	ds_read_b128 v[144:147], v169
	ds_read_b128 v[148:151], v248
	ds_read_b128 v[152:155], v169 offset:2048
	ds_read_b128 v[156:159], v248 offset:2048
	ds_read_b128 v[160:163], v170
	ds_read_b128 v[172:175], v249
	ds_read_b128 v[176:179], v170 offset:2048
	ds_read_b128 v[180:183], v249 offset:2048
	s_add_u32 s20, s18, 0x100
	s_addc_u32 s21, s19, 0
	s_cmp_eq_u32 s48, 40
	s_cselect_b32 s25, s9, s21
	s_cselect_b32 s24, s8, s20
	s_cselect_b32 s23, s17, s47
	s_cselect_b32 s22, s16, s46
	v_lshl_add_u64 v[164:165], s[18:19], 0, v[136:137]
	s_add_i32 m0, s28, 0xc000
	ds_read_b128 v[184:187], v171
	ds_read_b128 v[188:191], v246
	ds_read_b128 v[192:195], v171 offset:2048
	ds_read_b128 v[196:199], v246 offset:2048
	ds_read_b128 v[200:203], v171 offset:4096
	ds_read_b128 v[204:207], v246 offset:4096
	ds_read_b128 v[208:211], v171 offset:6144
	ds_read_b128 v[212:215], v246 offset:6144
	global_load_lds_dwordx4 v[164:165], off
	v_lshl_add_u64 v[164:165], s[18:19], 0, v[138:139]
	s_add_i32 m0, s28, 0xe000
	s_nop 0
	global_load_lds_dwordx4 v[164:165], off
	s_waitcnt vmcnt(24)
	s_waitcnt lgkmcnt(0)
	s_barrier
	s_setprio 0
	s_waitcnt lgkmcnt(0)
	v_mfma_f32_16x16x32_bf16 v[124:127], v[144:147], v[184:187], 0
	v_mfma_f32_16x16x32_bf16 v[120:123], v[152:155], v[184:187], 0
	v_mfma_f32_16x16x32_bf16 v[116:119], v[144:147], v[192:195], 0
	v_mfma_f32_16x16x32_bf16 v[112:115], v[152:155], v[192:195], 0
	v_mfma_f32_16x16x32_bf16 v[96:99], v[144:147], v[200:203], 0
	v_mfma_f32_16x16x32_bf16 v[88:91], v[152:155], v[200:203], 0
	v_mfma_f32_16x16x32_bf16 v[80:83], v[144:147], v[208:211], 0
	v_mfma_f32_16x16x32_bf16 v[72:75], v[152:155], v[208:211], 0
	v_mfma_f32_16x16x32_bf16 v[124:127], v[148:151], v[188:191], v[124:127]
	v_mfma_f32_16x16x32_bf16 v[120:123], v[156:159], v[188:191], v[120:123]
	v_mfma_f32_16x16x32_bf16 v[116:119], v[148:151], v[196:199], v[116:119]
	v_mfma_f32_16x16x32_bf16 v[112:115], v[156:159], v[196:199], v[112:115]
	v_mfma_f32_16x16x32_bf16 v[96:99], v[148:151], v[204:207], v[96:99]
	v_mfma_f32_16x16x32_bf16 v[88:91], v[156:159], v[204:207], v[88:91]
	v_mfma_f32_16x16x32_bf16 v[80:83], v[148:151], v[212:215], v[80:83]
	v_mfma_f32_16x16x32_bf16 v[72:75], v[156:159], v[212:215], v[72:75]
	s_setprio 0
	s_setprio 0
	v_mfma_f32_16x16x32_bf16 v[108:111], v[160:163], v[184:187], 0
	v_mfma_f32_16x16x32_bf16 v[104:107], v[176:179], v[184:187], 0
	v_mfma_f32_16x16x32_bf16 v[100:103], v[160:163], v[192:195], 0
	v_mfma_f32_16x16x32_bf16 v[92:95], v[176:179], v[192:195], 0
	v_mfma_f32_16x16x32_bf16 v[84:87], v[160:163], v[200:203], 0
	v_mfma_f32_16x16x32_bf16 v[76:79], v[176:179], v[200:203], 0
	v_mfma_f32_16x16x32_bf16 v[68:71], v[160:163], v[208:211], 0
	v_mfma_f32_16x16x32_bf16 v[64:67], v[176:179], v[208:211], 0
	v_mfma_f32_16x16x32_bf16 v[108:111], v[172:175], v[188:191], v[108:111]
	v_mfma_f32_16x16x32_bf16 v[104:107], v[180:183], v[188:191], v[104:107]
	v_mfma_f32_16x16x32_bf16 v[100:103], v[172:175], v[196:199], v[100:103]
	v_mfma_f32_16x16x32_bf16 v[92:95], v[180:183], v[196:199], v[92:95]
	v_mfma_f32_16x16x32_bf16 v[84:87], v[172:175], v[204:207], v[84:87]
	v_mfma_f32_16x16x32_bf16 v[76:79], v[180:183], v[204:207], v[76:79]
	v_mfma_f32_16x16x32_bf16 v[68:71], v[172:175], v[212:215], v[68:71]
	v_mfma_f32_16x16x32_bf16 v[64:67], v[180:183], v[212:215], v[64:67]
	s_setprio 0
	s_barrier
	s_add_i32 s18, s40, s26
	v_lshl_add_u64 v[164:165], s[22:23], 0, v[132:133]
	s_mov_b32 m0, s18
	ds_read_b128 v[184:187], v171 offset:16384
	ds_read_b128 v[188:191], v246 offset:16384
	ds_read_b128 v[192:195], v171 offset:18432
	ds_read_b128 v[196:199], v246 offset:18432
	ds_read_b128 v[200:203], v171 offset:20480
	ds_read_b128 v[204:207], v246 offset:20480
	ds_read_b128 v[208:211], v171 offset:22528
	ds_read_b128 v[212:215], v246 offset:22528
	global_load_lds_dwordx4 v[164:165], off
	s_add_i32 m0, s18, 0x2000
	s_add_u32 s18, s22, 0xb0000
	v_lshl_add_u64 v[216:217], s[22:23], 0, v[128:129]
	s_addc_u32 s19, s23, 0
	s_add_i32 s49, s41, s26
	global_load_lds_dwordx4 v[216:217], off
	v_lshl_add_u64 v[218:219], s[18:19], 0, v[132:133]
	s_mov_b32 m0, s49
	v_lshl_add_u64 v[220:221], s[24:25], 0, v[130:131]
	global_load_lds_dwordx4 v[218:219], off
	v_lshl_add_u64 v[218:219], s[18:19], 0, v[128:129]
	s_add_i32 m0, s49, 0x2000
	s_nop 0
	global_load_lds_dwordx4 v[218:219], off
	v_lshl_add_u64 v[218:219], s[24:25], 0, v[134:135]
	s_mov_b32 m0, s28
	s_nop 0
	global_load_lds_dwordx4 v[218:219], off
	s_mov_b32 m0, s29
	s_nop 0
	global_load_lds_dwordx4 v[220:221], off
	s_waitcnt vmcnt(24)
	s_waitcnt lgkmcnt(0)
	s_barrier
	s_setprio 0
	s_waitcnt lgkmcnt(0)
	v_mfma_f32_16x16x32_bf16 v[60:63], v[144:147], v[184:187], 0
	v_mfma_f32_16x16x32_bf16 v[56:59], v[152:155], v[184:187], 0
	v_mfma_f32_16x16x32_bf16 v[48:51], v[144:147], v[192:195], 0
	v_mfma_f32_16x16x32_bf16 v[40:43], v[152:155], v[192:195], 0
	v_mfma_f32_16x16x32_bf16 v[32:35], v[144:147], v[200:203], 0
	v_mfma_f32_16x16x32_bf16 v[24:27], v[152:155], v[200:203], 0
	v_mfma_f32_16x16x32_bf16 v[16:19], v[144:147], v[208:211], 0
	v_mfma_f32_16x16x32_bf16 v[8:11], v[152:155], v[208:211], 0
	v_mfma_f32_16x16x32_bf16 v[60:63], v[148:151], v[188:191], v[60:63]
	v_mfma_f32_16x16x32_bf16 v[56:59], v[156:159], v[188:191], v[56:59]
	v_mfma_f32_16x16x32_bf16 v[48:51], v[148:151], v[196:199], v[48:51]
	v_mfma_f32_16x16x32_bf16 v[40:43], v[156:159], v[196:199], v[40:43]
	v_mfma_f32_16x16x32_bf16 v[32:35], v[148:151], v[204:207], v[32:35]
	v_mfma_f32_16x16x32_bf16 v[24:27], v[156:159], v[204:207], v[24:27]
	v_mfma_f32_16x16x32_bf16 v[16:19], v[148:151], v[212:215], v[16:19]
	v_mfma_f32_16x16x32_bf16 v[8:11], v[156:159], v[212:215], v[8:11]
	s_setprio 0
	s_setprio 0
	v_mfma_f32_16x16x32_bf16 v[52:55], v[160:163], v[184:187], 0
	v_mfma_f32_16x16x32_bf16 v[44:47], v[176:179], v[184:187], 0
	v_mfma_f32_16x16x32_bf16 v[36:39], v[160:163], v[192:195], 0
	v_mfma_f32_16x16x32_bf16 v[28:31], v[176:179], v[192:195], 0
	v_mfma_f32_16x16x32_bf16 v[20:23], v[160:163], v[200:203], 0
	v_mfma_f32_16x16x32_bf16 v[12:15], v[176:179], v[200:203], 0
	v_mfma_f32_16x16x32_bf16 v[4:7], v[160:163], v[208:211], 0
	v_mfma_f32_16x16x32_bf16 v[0:3], v[176:179], v[208:211], 0
	v_mfma_f32_16x16x32_bf16 v[52:55], v[172:175], v[188:191], v[52:55]
	v_mfma_f32_16x16x32_bf16 v[44:47], v[180:183], v[188:191], v[44:47]
	v_mfma_f32_16x16x32_bf16 v[36:39], v[172:175], v[196:199], v[36:39]
	v_mfma_f32_16x16x32_bf16 v[28:31], v[180:183], v[196:199], v[28:31]
	v_mfma_f32_16x16x32_bf16 v[20:23], v[172:175], v[204:207], v[20:23]
	v_mfma_f32_16x16x32_bf16 v[12:15], v[180:183], v[204:207], v[12:15]
	v_mfma_f32_16x16x32_bf16 v[4:7], v[172:175], v[212:215], v[4:7]
	v_mfma_f32_16x16x32_bf16 v[0:3], v[180:183], v[212:215], v[0:3]
	s_setprio 0
	s_barrier
	s_add_i32 s49, 0, 0x18000
	s_add_i32 s50, 0, 0x1c000
	v_add_u32_e32 v156, s49, v167
	v_add_u32_e32 v250, s49, v247
	v_add_u32_e32 v180, s50, v167
	v_add_u32_e32 v251, s50, v247
	ds_read_b128 v[144:147], v156
	ds_read_b128 v[148:151], v250
	ds_read_b128 v[152:155], v156 offset:2048
	ds_read_b128 v[156:159], v250 offset:2048
	ds_read_b128 v[160:163], v180
	ds_read_b128 v[172:175], v251
	ds_read_b128 v[176:179], v180 offset:2048
	ds_read_b128 v[180:183], v251 offset:2048
	s_add_u32 s18, s24, 0xb0000
	s_addc_u32 s19, s25, 0
	s_mov_b32 m0, s30
	v_lshl_add_u64 v[222:223], s[18:19], 0, v[134:135]
	ds_read_b128 v[184:187], v171 offset:32768
	ds_read_b128 v[188:191], v246 offset:32768
	ds_read_b128 v[192:195], v171 offset:34816
	ds_read_b128 v[196:199], v246 offset:34816
	ds_read_b128 v[200:203], v171 offset:36864
	ds_read_b128 v[204:207], v246 offset:36864
	ds_read_b128 v[208:211], v171 offset:38912
	ds_read_b128 v[212:215], v246 offset:38912
	global_load_lds_dwordx4 v[222:223], off
	v_lshl_add_u64 v[222:223], s[18:19], 0, v[130:131]
	s_mov_b32 m0, s31
	s_nop 0
	global_load_lds_dwordx4 v[222:223], off
	s_waitcnt vmcnt(8)
	s_waitcnt lgkmcnt(0)
	s_barrier
	s_setprio 0
	s_waitcnt lgkmcnt(0)
	v_mfma_f32_16x16x32_bf16 v[124:127], v[144:147], v[184:187], v[124:127]
	v_mfma_f32_16x16x32_bf16 v[120:123], v[152:155], v[184:187], v[120:123]
	v_mfma_f32_16x16x32_bf16 v[116:119], v[144:147], v[192:195], v[116:119]
	v_mfma_f32_16x16x32_bf16 v[112:115], v[152:155], v[192:195], v[112:115]
	v_mfma_f32_16x16x32_bf16 v[96:99], v[144:147], v[200:203], v[96:99]
	v_mfma_f32_16x16x32_bf16 v[88:91], v[152:155], v[200:203], v[88:91]
	v_mfma_f32_16x16x32_bf16 v[80:83], v[144:147], v[208:211], v[80:83]
	v_mfma_f32_16x16x32_bf16 v[72:75], v[152:155], v[208:211], v[72:75]
	v_mfma_f32_16x16x32_bf16 v[124:127], v[148:151], v[188:191], v[124:127]
	v_mfma_f32_16x16x32_bf16 v[120:123], v[156:159], v[188:191], v[120:123]
	v_mfma_f32_16x16x32_bf16 v[116:119], v[148:151], v[196:199], v[116:119]
	v_mfma_f32_16x16x32_bf16 v[112:115], v[156:159], v[196:199], v[112:115]
	v_mfma_f32_16x16x32_bf16 v[96:99], v[148:151], v[204:207], v[96:99]
	v_mfma_f32_16x16x32_bf16 v[88:91], v[156:159], v[204:207], v[88:91]
	v_mfma_f32_16x16x32_bf16 v[80:83], v[148:151], v[212:215], v[80:83]
	v_mfma_f32_16x16x32_bf16 v[72:75], v[156:159], v[212:215], v[72:75]
	s_setprio 0
	s_setprio 0
	v_mfma_f32_16x16x32_bf16 v[108:111], v[160:163], v[184:187], v[108:111]
	v_mfma_f32_16x16x32_bf16 v[104:107], v[176:179], v[184:187], v[104:107]
	v_mfma_f32_16x16x32_bf16 v[100:103], v[160:163], v[192:195], v[100:103]
	v_mfma_f32_16x16x32_bf16 v[92:95], v[176:179], v[192:195], v[92:95]
	v_mfma_f32_16x16x32_bf16 v[84:87], v[160:163], v[200:203], v[84:87]
	v_mfma_f32_16x16x32_bf16 v[76:79], v[176:179], v[200:203], v[76:79]
	v_mfma_f32_16x16x32_bf16 v[68:71], v[160:163], v[208:211], v[68:71]
	v_mfma_f32_16x16x32_bf16 v[64:67], v[176:179], v[208:211], v[64:67]
	v_mfma_f32_16x16x32_bf16 v[108:111], v[172:175], v[188:191], v[108:111]
	v_mfma_f32_16x16x32_bf16 v[104:107], v[180:183], v[188:191], v[104:107]
	v_mfma_f32_16x16x32_bf16 v[100:103], v[172:175], v[196:199], v[100:103]
	v_mfma_f32_16x16x32_bf16 v[92:95], v[180:183], v[196:199], v[92:95]
	v_mfma_f32_16x16x32_bf16 v[84:87], v[172:175], v[204:207], v[84:87]
	v_mfma_f32_16x16x32_bf16 v[76:79], v[180:183], v[204:207], v[76:79]
	v_mfma_f32_16x16x32_bf16 v[68:71], v[172:175], v[212:215], v[68:71]
	v_mfma_f32_16x16x32_bf16 v[64:67], v[180:183], v[212:215], v[64:67]
	s_setprio 0
	s_barrier
	s_add_i32 s18, s49, s26
	v_lshl_add_u64 v[164:165], v[164:165], 0, s[12:13]
	s_mov_b32 m0, s18
	ds_read_b128 v[184:187], v171 offset:49152
	ds_read_b128 v[188:191], v246 offset:49152
	ds_read_b128 v[192:195], v171 offset:51200
	ds_read_b128 v[196:199], v246 offset:51200
	ds_read_b128 v[200:203], v171 offset:53248
	ds_read_b128 v[204:207], v246 offset:53248
	ds_read_b128 v[208:211], v171 offset:55296
	ds_read_b128 v[212:215], v246 offset:55296
	global_load_lds_dwordx4 v[164:165], off
	s_add_i32 m0, s18, 0x2000
	s_add_u32 s18, s22, 0xb0080
	v_lshl_add_u64 v[164:165], v[216:217], 0, s[12:13]
	s_addc_u32 s19, s23, 0
	s_add_i32 s22, s50, s26
	global_load_lds_dwordx4 v[164:165], off
	v_lshl_add_u64 v[164:165], s[18:19], 0, v[132:133]
	s_mov_b32 m0, s22
	s_nop 0
	global_load_lds_dwordx4 v[164:165], off
	v_lshl_add_u64 v[164:165], s[18:19], 0, v[128:129]
	s_add_i32 m0, s22, 0x2000
	s_nop 0
	global_load_lds_dwordx4 v[164:165], off
	v_lshl_add_u64 v[164:165], v[218:219], 0, s[12:13]
	s_mov_b32 m0, s37
	s_nop 0
	global_load_lds_dwordx4 v[164:165], off
	v_lshl_add_u64 v[164:165], v[220:221], 0, s[12:13]
	s_mov_b32 m0, s38
	s_nop 0
	global_load_lds_dwordx4 v[164:165], off
	s_waitcnt vmcnt(8)
	s_waitcnt lgkmcnt(0)
	s_barrier
	s_setprio 0
	s_waitcnt lgkmcnt(0)
	v_mfma_f32_16x16x32_bf16 v[60:63], v[144:147], v[184:187], v[60:63]
	v_mfma_f32_16x16x32_bf16 v[56:59], v[152:155], v[184:187], v[56:59]
	v_mfma_f32_16x16x32_bf16 v[48:51], v[144:147], v[192:195], v[48:51]
	v_mfma_f32_16x16x32_bf16 v[40:43], v[152:155], v[192:195], v[40:43]
	v_mfma_f32_16x16x32_bf16 v[32:35], v[144:147], v[200:203], v[32:35]
	v_mfma_f32_16x16x32_bf16 v[24:27], v[152:155], v[200:203], v[24:27]
	v_mfma_f32_16x16x32_bf16 v[16:19], v[144:147], v[208:211], v[16:19]
	v_mfma_f32_16x16x32_bf16 v[8:11], v[152:155], v[208:211], v[8:11]
	v_mfma_f32_16x16x32_bf16 v[60:63], v[148:151], v[188:191], v[60:63]
	v_mfma_f32_16x16x32_bf16 v[56:59], v[156:159], v[188:191], v[56:59]
	v_mfma_f32_16x16x32_bf16 v[48:51], v[148:151], v[196:199], v[48:51]
	v_mfma_f32_16x16x32_bf16 v[40:43], v[156:159], v[196:199], v[40:43]
	v_mfma_f32_16x16x32_bf16 v[32:35], v[148:151], v[204:207], v[32:35]
	v_mfma_f32_16x16x32_bf16 v[24:27], v[156:159], v[204:207], v[24:27]
	v_mfma_f32_16x16x32_bf16 v[16:19], v[148:151], v[212:215], v[16:19]
	v_mfma_f32_16x16x32_bf16 v[8:11], v[156:159], v[212:215], v[8:11]
	s_setprio 0
	s_setprio 0
	v_mfma_f32_16x16x32_bf16 v[52:55], v[160:163], v[184:187], v[52:55]
	v_mfma_f32_16x16x32_bf16 v[44:47], v[176:179], v[184:187], v[44:47]
	v_mfma_f32_16x16x32_bf16 v[36:39], v[160:163], v[192:195], v[36:39]
	v_mfma_f32_16x16x32_bf16 v[28:31], v[176:179], v[192:195], v[28:31]
	v_mfma_f32_16x16x32_bf16 v[20:23], v[160:163], v[200:203], v[20:23]
	v_mfma_f32_16x16x32_bf16 v[12:15], v[176:179], v[200:203], v[12:15]
	v_mfma_f32_16x16x32_bf16 v[4:7], v[160:163], v[208:211], v[4:7]
	v_mfma_f32_16x16x32_bf16 v[0:3], v[176:179], v[208:211], v[0:3]
	v_mfma_f32_16x16x32_bf16 v[52:55], v[172:175], v[188:191], v[52:55]
	v_mfma_f32_16x16x32_bf16 v[44:47], v[180:183], v[188:191], v[44:47]
	v_mfma_f32_16x16x32_bf16 v[36:39], v[172:175], v[196:199], v[36:39]
	v_mfma_f32_16x16x32_bf16 v[28:31], v[180:183], v[196:199], v[28:31]
	v_mfma_f32_16x16x32_bf16 v[20:23], v[172:175], v[204:207], v[20:23]
	v_mfma_f32_16x16x32_bf16 v[12:15], v[180:183], v[204:207], v[12:15]
	v_mfma_f32_16x16x32_bf16 v[4:7], v[172:175], v[212:215], v[4:7]
	v_mfma_f32_16x16x32_bf16 v[0:3], v[180:183], v[212:215], v[0:3]
	s_setprio 0
	s_barrier
	s_add_i32 s48, s48, 2
	s_add_u32 s46, s46, 0x100
	s_addc_u32 s47, s47, 0
	s_cmp_gt_u32 s48, 41
	s_mov_b64 s[18:19], s[20:21]

.LBB0_427:
	s_add_u32 s40, s82, 0x9000000
	s_addc_u32 s41, s83, 0
	s_add_u32 s42, s82, 0x14000000
	s_addc_u32 s43, s83, 0
	s_add_u32 s14, s82, 0x80000
	s_mov_b64 s[16:17], 0x80
	s_addc_u32 s15, s83, 0
	s_and_b32 s46, s0, 3
	s_add_i32 m0, s36, 0x18000
	v_lshl_add_u64 v[6:7], v[6:7], 0, s[16:17]
	s_ashr_i32 s44, s86, 31
	s_ashr_i32 s45, s96, 31
	s_lshl_b32 s0, s1, 13
	s_lshl_b32 s7, s46, 12
	s_waitcnt vmcnt(2)
	s_barrier
	global_load_lds_dwordx4 v[6:7], off
	v_lshl_add_u64 v[4:5], v[4:5], 0, s[16:17]
	s_add_i32 m0, s36, 0x1a000
	s_add_i32 s47, s36, 0x8000
	s_add_i32 s48, s36, 0xa000
	global_load_lds_dwordx4 v[4:5], off
	v_lshl_add_u64 v[0:1], v[0:1], 0, s[16:17]
	s_mov_b32 m0, s47
	s_add_u32 s18, s30, 0x40080
	global_load_lds_dwordx4 v[0:1], off
	v_lshl_add_u64 v[0:1], v[2:3], 0, s[16:17]
	s_mov_b32 m0, s48
	s_addc_u32 s19, s31, 0
	global_load_lds_dwordx4 v[0:1], off
	s_add_i32 m0, s36, 0x1c000
	v_lshl_add_u64 v[0:1], s[18:19], 0, v[212:213]
	global_load_lds_dwordx4 v[0:1], off
	v_lshl_add_u64 v[0:1], s[18:19], 0, v[216:217]
	s_add_i32 m0, s36, 0x1e000
	s_cmpk_lt_u32 s6, 0x100
	global_load_lds_dwordx4 v[0:1], off
	v_bfe_u32 v1, v8, 4, 2
	v_and_b32_e32 v0, 15, v8
	v_lshlrev_b32_e32 v2, 4, v1
	v_lshl_or_b32 v221, s1, 6, v0
	v_lshl_or_b32 v0, v0, 6, v2
	v_lshlrev_b32_e32 v2, 2, v8
	v_and_b32_e32 v2, 32, v2
	v_lshlrev_b32_e32 v220, 3, v1
	v_bitop3_b32 v3, v0, s0, v2 bitop3:0xde
	v_cmp_gt_u32_e64 s[0:1], 2, v1
	v_cmp_eq_u32_e32 vcc, 0, v1
	v_lshlrev_b32_e32 v1, 14, v9
	v_and_b32_e32 v1, 0xffff8000, v1
	v_bitop3_b32 v237, v0, s7, v2 bitop3:0xde
	v_lshl_add_u32 v1, v10, 11, v1
	v_and_b32_e32 v2, 1, v9
	v_lshl_or_b32 v1, v2, 6, v1
	v_lshl_add_u32 v222, v11, 1, v1
	v_lshlrev_b32_e32 v1, 14, v12
	v_and_b32_e32 v1, 0xffff8000, v1
	s_waitcnt vmcnt(6)
	v_lshl_or_b32 v0, s46, 6, v220
	v_lshl_add_u32 v1, v13, 11, v1
	v_and_b32_e32 v2, 1, v12
	s_cselect_b64 s[18:19], -1, 0
	v_lshl_or_b32 v1, v2, 6, v1
	s_add_i32 s50, 0, 0x10000
	s_add_i32 s51, 0, 0x14000
	v_lshlrev_b32_e32 v230, 1, v0
	v_mbcnt_lo_u32_b32 v0, -1, 0
	s_mov_b32 s49, s86
	v_cndmask_b32_e64 v238, 1.0, -1.0, vcc
	v_mov_b32_e32 v223, v219
	v_lshl_add_u32 v224, v14, 1, v1
	v_mov_b32_e32 v225, v219
	v_mov_b64_e32 v[226:227], 0x700
	v_mov_b64_e32 v[228:229], 0x6ff
	v_add_u32_e32 v239, s50, v237
	v_add_u32_e32 v240, s51, v237
	v_add_u32_e32 v241, 0, v3
	v_mov_b32_e32 v242, 0x358637bd
	s_mov_b32 s52, 0xf800000
	v_mov_b32_e32 v243, 0x260
	s_mov_b32 s53, 0x2c000
	v_mov_b32_e32 v244, 0x3e38aa3b
	v_mbcnt_hi_u32_b32 v245, -1, v0
	s_mov_b32 s54, 0
	s_barrier
	v_sub_u32_e32 v222, v222, v252
	v_add_u32_e32 v222, v222, v210
	v_sub_u32_e32 v224, v224, v253
	v_add_u32_e32 v224, v224, v214
	v_and_b32_e32 v250, 63, v236
	v_and_b32_e32 v251, 15, v250
	v_lshrrev_b32_e32 v252, 4, v250
	v_and_b32_e32 v253, 7, v251
	v_xor_b32_e32 v252, v252, v253
	v_lshlrev_b32_e32 v252, 4, v252
	v_lshl_add_u32 v252, v251, 7, v252
	v_lshrrev_b32_e32 v250, 6, v236
	v_lshrrev_b32_e32 v251, 2, v250
	v_lshl_add_u32 v241, v251, 13, v252
	v_and_b32_e32 v251, 3, v250
	v_lshl_add_u32 v237, v251, 12, v252
	v_add_u32_e32 v239, s50, v237
	v_add_u32_e32 v240, s51, v237
	s_add_i32 s54, s54, 1
	s_mul_i32 s6, s54, s44
	s_mul_hi_u32 s7, s54, s49
	s_add_i32 s7, s7, s6
	s_mul_i32 s6, s54, s49
	s_add_u32 s24, s6, s96
	s_addc_u32 s25, s7, s45
	v_cmp_gt_i64_e32 vcc, s[24:25], v[228:229]
	v_cmp_lt_i64_e64 s[6:7], s[24:25], v[226:227]
	s_cbranch_vccnz .Lfu_432
	s_ashr_i32 s9, s24, 31
	s_lshr_b32 s9, s9, 29
	s_add_i32 s9, s24, s9
	s_ashr_i32 s20, s9, 3
	s_and_b32 s9, s9, -8
	s_sub_i32 s9, s24, s9
	s_cmp_lt_i32 s9, 0
	s_movk_i32 s21, 0xe1
	s_cselect_b32 s21, s21, 0xe0
	s_mul_i32 s9, s9, s21
	s_add_i32 s9, s9, s20
	s_mul_hi_i32 s20, s9, 0x92492493
	s_add_i32 s20, s20, s9
	s_lshr_b32 s21, s20, 31
	s_ashr_i32 s20, s20, 6
	s_add_i32 s20, s20, s21
	s_lshl_b32 s21, s20, 3
	s_sub_i32 s22, 0x80, s21
	s_min_i32 s22, s22, 8
	s_abs_i32 s23, s22
	v_cvt_f32_u32_e32 v0, s23
	s_sub_i32 s25, 0, s23
	s_mulk_i32 s20, 0x70
	s_sub_i32 s9, s9, s20
	v_rcp_iflag_f32_e32 v0, v0
	s_abs_i32 s20, s9
	s_xor_b32 s24, s9, s22
	s_ashr_i32 s24, s24, 31
	v_mul_f32_e32 v0, 0x4f7ffffe, v0
	v_cvt_u32_f32_e32 v0, v0
	s_nop 0
	v_readfirstlane_b32 s26, v0
	s_mul_i32 s25, s25, s26
	s_mul_hi_u32 s25, s26, s25
	s_add_i32 s26, s26, s25
	s_mul_hi_u32 s25, s20, s26
	s_mul_i32 s26, s25, s23
	s_sub_i32 s20, s20, s26
	s_add_i32 s27, s25, 1
	s_sub_i32 s26, s20, s23
	s_cmp_ge_u32 s20, s23
	s_cselect_b32 s25, s27, s25
	s_cselect_b32 s20, s26, s20
	s_add_i32 s26, s25, 1
	s_cmp_ge_u32 s20, s23
	s_cselect_b32 s20, s26, s25
	s_xor_b32 s20, s20, s24
	s_sub_i32 s20, s20, s24
	s_mul_i32 s22, s20, s22
	s_sub_i32 s9, s9, s22
	s_add_i32 s22, s21, s9
.Lfu_432:
	s_ashr_i32 s23, s22, 31
	s_lshl_b64 s[24:25], s[22:23], 19
	s_add_u32 s24, s90, s24
	s_addc_u32 s25, s91, s25
	s_and_b64 s[26:27], s[6:7], exec
	s_cselect_b32 s9, s25, s29
	s_cselect_b32 s23, s24, s28
	s_ashr_i32 s21, s20, 31
	s_lshl_b64 s[26:27], s[20:21], 19
	s_add_u32 s26, s2, s26
	s_addc_u32 s27, s3, s27
	s_and_b64 s[34:35], s[6:7], exec
	s_cselect_b32 s21, s27, s31
	s_cselect_b32 s55, s26, s30
	s_add_u32 s28, s28, 0x40080
	s_addc_u32 s29, s29, 0
	s_add_u32 s56, s30, 0x100
	v_mov_b32_e32 v0, 0
	s_addc_u32 s57, s31, 0
	s_mov_b32 s58, -2
	v_mov_b32_e32 v1, v0
	v_mov_b32_e32 v2, v0
	v_mov_b32_e32 v3, v0
	v_mov_b32_e32 v4, v0
	v_mov_b32_e32 v5, v0
	v_mov_b32_e32 v6, v0
	v_mov_b32_e32 v7, v0
	v_mov_b32_e32 v16, v0
	v_mov_b32_e32 v17, v0
	v_mov_b32_e32 v18, v0
	v_mov_b32_e32 v19, v0
	v_mov_b32_e32 v20, v0
	v_mov_b32_e32 v21, v0
	v_mov_b32_e32 v22, v0
	v_mov_b32_e32 v23, v0
	v_mov_b32_e32 v32, v0
	v_mov_b32_e32 v33, v0
	v_mov_b32_e32 v34, v0
	v_mov_b32_e32 v35, v0
	v_mov_b32_e32 v36, v0
	v_mov_b32_e32 v37, v0
	v_mov_b32_e32 v38, v0
	v_mov_b32_e32 v39, v0
	v_mov_b32_e32 v48, v0
	v_mov_b32_e32 v49, v0
	v_mov_b32_e32 v50, v0
	v_mov_b32_e32 v51, v0
	v_mov_b32_e32 v52, v0
	v_mov_b32_e32 v53, v0
	v_mov_b32_e32 v54, v0
	v_mov_b32_e32 v55, v0
	v_mov_b32_e32 v8, v0
	v_mov_b32_e32 v9, v0
	v_mov_b32_e32 v10, v0
	v_mov_b32_e32 v11, v0
	v_mov_b32_e32 v12, v0
	v_mov_b32_e32 v13, v0
	v_mov_b32_e32 v14, v0
	v_mov_b32_e32 v15, v0
	v_mov_b32_e32 v24, v0
	v_mov_b32_e32 v25, v0
	v_mov_b32_e32 v26, v0
	v_mov_b32_e32 v27, v0
	v_mov_b32_e32 v28, v0
	v_mov_b32_e32 v29, v0
	v_mov_b32_e32 v30, v0
	v_mov_b32_e32 v31, v0
	v_mov_b32_e32 v40, v0
	v_mov_b32_e32 v41, v0
	v_mov_b32_e32 v42, v0
	v_mov_b32_e32 v43, v0
	v_mov_b32_e32 v44, v0
	v_mov_b32_e32 v45, v0
	v_mov_b32_e32 v46, v0
	v_mov_b32_e32 v47, v0
	v_mov_b32_e32 v56, v0
	v_mov_b32_e32 v57, v0
	v_mov_b32_e32 v58, v0
	v_mov_b32_e32 v59, v0
	v_mov_b32_e32 v60, v0
	v_mov_b32_e32 v61, v0
	v_mov_b32_e32 v62, v0
	v_mov_b32_e32 v63, v0
	v_mov_b32_e32 v64, v0
	v_mov_b32_e32 v65, v0
	v_mov_b32_e32 v66, v0
	v_mov_b32_e32 v67, v0
	v_mov_b32_e32 v68, v0
	v_mov_b32_e32 v69, v0
	v_mov_b32_e32 v70, v0
	v_mov_b32_e32 v71, v0
	v_mov_b32_e32 v82, v0
	v_mov_b32_e32 v83, v0
	v_mov_b32_e32 v84, v0
	v_mov_b32_e32 v85, v0
	v_mov_b32_e32 v86, v0
	v_mov_b32_e32 v87, v0
	v_mov_b32_e32 v88, v0
	v_mov_b32_e32 v89, v0
	v_mov_b32_e32 v98, v0
	v_mov_b32_e32 v99, v0
	v_mov_b32_e32 v100, v0
	v_mov_b32_e32 v101, v0
	v_mov_b32_e32 v102, v0
	v_mov_b32_e32 v103, v0
	v_mov_b32_e32 v104, v0
	v_mov_b32_e32 v105, v0
	v_mov_b32_e32 v114, v0
	v_mov_b32_e32 v115, v0
	v_mov_b32_e32 v116, v0
	v_mov_b32_e32 v117, v0
	v_mov_b32_e32 v118, v0
	v_mov_b32_e32 v119, v0
	v_mov_b32_e32 v120, v0
	v_mov_b32_e32 v121, v0
	v_mov_b32_e32 v72, v0
	v_mov_b32_e32 v73, v0
	v_mov_b32_e32 v74, v0
	v_mov_b32_e32 v75, v0
	v_mov_b32_e32 v76, v0
	v_mov_b32_e32 v77, v0
	v_mov_b32_e32 v78, v0
	v_mov_b32_e32 v79, v0
	v_mov_b32_e32 v90, v0
	v_mov_b32_e32 v91, v0
	v_mov_b32_e32 v92, v0
	v_mov_b32_e32 v93, v0
	v_mov_b32_e32 v94, v0
	v_mov_b32_e32 v95, v0
	v_mov_b32_e32 v96, v0
	v_mov_b32_e32 v97, v0
	v_mov_b32_e32 v106, v0
	v_mov_b32_e32 v107, v0
	v_mov_b32_e32 v108, v0
	v_mov_b32_e32 v109, v0
	v_mov_b32_e32 v110, v0
	v_mov_b32_e32 v111, v0
	v_mov_b32_e32 v112, v0
	v_mov_b32_e32 v113, v0
	v_mov_b32_e32 v122, v0
	v_mov_b32_e32 v123, v0
	v_mov_b32_e32 v124, v0
	v_mov_b32_e32 v125, v0
	v_mov_b32_e32 v126, v0
	v_mov_b32_e32 v127, v0
	v_mov_b32_e32 v128, v0
	v_mov_b32_e32 v129, v0
	v_xor_b32_e32 v246, 64, v241
	v_xor_b32_e32 v247, 64, v237
	v_add_u32_e32 v248, s50, v247
	v_add_u32_e32 v249, s51, v247
	s_branch .LBB0_433

.LBB0_430:
	s_add_u32 s28, s28, 0x40080
	s_addc_u32 s29, s29, 0
	s_add_u32 s56, s30, 0x100
	s_addc_u32 s57, s31, 0
	s_mov_b32 s58, -2
	v_xor_b32_e32 v246, 64, v241
	v_xor_b32_e32 v247, 64, v237
	v_add_u32_e32 v248, s50, v247
	v_add_u32_e32 v249, s51, v247
	ds_read_b128 v[130:133], v239
	ds_read_b128 v[134:137], v248
	ds_read_b128 v[138:141], v239 offset:2048
	ds_read_b128 v[142:145], v248 offset:2048
	ds_read_b128 v[146:149], v240
	ds_read_b128 v[150:153], v249
	ds_read_b128 v[154:157], v240 offset:2048
	ds_read_b128 v[158:161], v249 offset:2048
	s_add_u32 s30, s28, 0xfffc0080
	s_addc_u32 s31, s29, -1
	s_cmp_eq_u32 s58, 12
	s_cselect_b32 s35, s9, s31
	s_cselect_b32 s34, s23, s30
	s_cselect_b32 s31, s21, s57
	s_cselect_b32 s30, s55, s56
	v_lshl_add_u64 v[80:81], s[28:29], 0, v[222:223]
	s_add_i32 m0, s36, 0xc000
	ds_read_b128 v[162:165], v241
	ds_read_b128 v[166:169], v246
	ds_read_b128 v[170:173], v241 offset:2048
	ds_read_b128 v[174:177], v246 offset:2048
	ds_read_b128 v[178:181], v241 offset:4096
	ds_read_b128 v[182:185], v246 offset:4096
	ds_read_b128 v[186:189], v241 offset:6144
	ds_read_b128 v[190:193], v246 offset:6144
	global_load_lds_dwordx4 v[80:81], off
	v_lshl_add_u64 v[80:81], s[28:29], 0, v[224:225]
	s_add_i32 m0, s36, 0xe000
	s_nop 0
	global_load_lds_dwordx4 v[80:81], off
	s_waitcnt vmcnt(24)
	s_waitcnt lgkmcnt(0)
	s_barrier
	s_setprio 0
	s_waitcnt lgkmcnt(0)
	v_mfma_f32_16x16x32_bf16 v[126:129], v[130:133], v[162:165], 0
	s_add_i32 s54, s54, 1
	s_mul_i32 s6, s54, s44
	s_mul_hi_u32 s7, s54, s49
	v_mfma_f32_16x16x32_bf16 v[122:125], v[138:141], v[162:165], 0
	s_add_i32 s7, s7, s6
	s_mul_i32 s6, s54, s49
	s_add_u32 s24, s6, s96
	v_mfma_f32_16x16x32_bf16 v[110:113], v[130:133], v[170:173], 0
	s_addc_u32 s25, s7, s45
	v_cmp_lt_i64_e64 s[6:7], s[24:25], v[226:227]
	s_ashr_i32 s9, s24, 31
	v_mfma_f32_16x16x32_bf16 v[106:109], v[138:141], v[170:173], 0
	s_lshr_b32 s9, s9, 29
	s_add_i32 s9, s24, s9
	s_ashr_i32 s20, s9, 3
	v_mfma_f32_16x16x32_bf16 v[94:97], v[130:133], v[178:181], 0
	s_and_b32 s9, s9, -8
	s_sub_i32 s9, s24, s9
	s_cmp_lt_i32 s9, 0
	v_mfma_f32_16x16x32_bf16 v[90:93], v[138:141], v[178:181], 0
	s_movk_i32 s21, 0xe1
	s_cselect_b32 s21, s21, 0xe0
	s_mul_i32 s9, s9, s21
	v_mfma_f32_16x16x32_bf16 v[76:79], v[130:133], v[186:189], 0
	s_add_i32 s9, s9, s20
	s_mul_hi_i32 s20, s9, 0x92492493
	s_add_i32 s20, s20, s9
	v_mfma_f32_16x16x32_bf16 v[72:75], v[138:141], v[186:189], 0
	s_lshr_b32 s21, s20, 31
	s_ashr_i32 s20, s20, 6
	s_add_i32 s20, s20, s21
	v_mfma_f32_16x16x32_bf16 v[126:129], v[134:137], v[166:169], v[126:129]
	s_lshl_b32 s21, s20, 3
	s_sub_i32 s22, 0x80, s21
	s_min_i32 s22, s22, 8
	v_mfma_f32_16x16x32_bf16 v[122:125], v[142:145], v[166:169], v[122:125]
	s_abs_i32 s23, s22
	v_cvt_f32_u32_e32 v252, s23
	s_sub_i32 s25, 0, s23
	v_mfma_f32_16x16x32_bf16 v[110:113], v[134:137], v[174:177], v[110:113]
	s_mulk_i32 s20, 0x70
	s_sub_i32 s9, s9, s20
	v_rcp_iflag_f32_e32 v252, v252
	v_mfma_f32_16x16x32_bf16 v[106:109], v[142:145], v[174:177], v[106:109]
	s_abs_i32 s20, s9
	s_xor_b32 s24, s9, s22
	s_ashr_i32 s24, s24, 31
	v_mfma_f32_16x16x32_bf16 v[94:97], v[134:137], v[182:185], v[94:97]
	v_mul_f32_e32 v252, 0x4f7ffffe, v252
	v_cvt_u32_f32_e32 v252, v252
	s_nop 0
	v_mfma_f32_16x16x32_bf16 v[90:93], v[142:145], v[182:185], v[90:93]
	v_readfirstlane_b32 s26, v252
	s_mul_i32 s25, s25, s26
	s_mul_hi_u32 s25, s26, s25
	v_mfma_f32_16x16x32_bf16 v[76:79], v[134:137], v[190:193], v[76:79]
	s_add_i32 s26, s26, s25
	s_mul_hi_u32 s25, s20, s26
	s_mul_i32 s26, s25, s23
	v_mfma_f32_16x16x32_bf16 v[72:75], v[142:145], v[190:193], v[72:75]
	s_sub_i32 s20, s20, s26
	s_add_i32 s27, s25, 1
	s_sub_i32 s26, s20, s23
	s_setprio 0
	s_setprio 0
	v_mfma_f32_16x16x32_bf16 v[118:121], v[146:149], v[162:165], 0
	s_cmp_ge_u32 s20, s23
	s_cselect_b32 s25, s27, s25
	s_cselect_b32 s20, s26, s20
	v_mfma_f32_16x16x32_bf16 v[114:117], v[154:157], v[162:165], 0
	s_add_i32 s26, s25, 1
	s_cmp_ge_u32 s20, s23
	s_cselect_b32 s20, s26, s25
	v_mfma_f32_16x16x32_bf16 v[102:105], v[146:149], v[170:173], 0
	s_xor_b32 s20, s20, s24
	s_sub_i32 s20, s20, s24
	s_mul_i32 s22, s20, s22
	v_mfma_f32_16x16x32_bf16 v[98:101], v[154:157], v[170:173], 0
	s_sub_i32 s9, s9, s22
	s_add_i32 s22, s21, s9
	s_ashr_i32 s23, s22, 31
	v_mfma_f32_16x16x32_bf16 v[86:89], v[146:149], v[178:181], 0
	s_lshl_b64 s[24:25], s[22:23], 19
	s_add_u32 s24, s90, s24
	s_addc_u32 s25, s91, s25
	v_mfma_f32_16x16x32_bf16 v[80:83], v[154:157], v[178:181], 0
	s_and_b64 s[26:27], s[6:7], exec
	s_cselect_b32 s9, s25, s29
	s_cselect_b32 s23, s24, s28
	v_mfma_f32_16x16x32_bf16 v[68:71], v[146:149], v[186:189], 0
	s_ashr_i32 s21, s20, 31
	s_lshl_b64 s[26:27], s[20:21], 19
	s_add_u32 s26, s2, s26
	v_mfma_f32_16x16x32_bf16 v[64:67], v[154:157], v[186:189], 0
	s_addc_u32 s27, s3, s27
	s_and_b64 s[98:99], s[6:7], exec
	s_cselect_b32 s21, s27, s31
	v_mfma_f32_16x16x32_bf16 v[118:121], v[150:153], v[166:169], v[118:121]
	s_cselect_b32 s55, s26, s30
	v_mfma_f32_16x16x32_bf16 v[114:117], v[158:161], v[166:169], v[114:117]
	v_mfma_f32_16x16x32_bf16 v[102:105], v[150:153], v[174:177], v[102:105]
	v_mfma_f32_16x16x32_bf16 v[98:101], v[158:161], v[174:177], v[98:101]
	v_mfma_f32_16x16x32_bf16 v[86:89], v[150:153], v[182:185], v[86:89]
	v_mfma_f32_16x16x32_bf16 v[80:83], v[158:161], v[182:185], v[80:83]
	v_mfma_f32_16x16x32_bf16 v[68:71], v[150:153], v[190:193], v[68:71]
	v_mfma_f32_16x16x32_bf16 v[64:67], v[158:161], v[190:193], v[64:67]
	s_setprio 0
	s_barrier
	s_add_i32 s59, s50, s33
	v_lshl_add_u64 v[194:195], s[30:31], 0, v[212:213]
	s_mov_b32 m0, s59
	ds_read_b128 v[162:165], v241 offset:16384
	ds_read_b128 v[166:169], v246 offset:16384
	ds_read_b128 v[170:173], v241 offset:18432
	ds_read_b128 v[174:177], v246 offset:18432
	ds_read_b128 v[178:181], v241 offset:20480
	ds_read_b128 v[182:185], v246 offset:20480
	ds_read_b128 v[186:189], v241 offset:22528
	ds_read_b128 v[190:193], v246 offset:22528
	global_load_lds_dwordx4 v[194:195], off
	s_add_i32 m0, s59, 0x2000
	s_add_u32 s60, s30, 0x40000
	v_lshl_add_u64 v[196:197], s[30:31], 0, v[216:217]
	s_addc_u32 s61, s31, 0
	s_add_i32 s59, s51, s33
	global_load_lds_dwordx4 v[196:197], off
	v_lshl_add_u64 v[84:85], s[60:61], 0, v[212:213]
	s_mov_b32 m0, s59
	v_lshl_add_u64 v[198:199], s[34:35], 0, v[210:211]
	global_load_lds_dwordx4 v[84:85], off
	v_lshl_add_u64 v[84:85], s[60:61], 0, v[216:217]
	s_add_i32 m0, s59, 0x2000
	v_lshl_add_u64 v[200:201], s[34:35], 0, v[214:215]
	global_load_lds_dwordx4 v[84:85], off
	s_mov_b32 m0, s36
	s_nop 0
	global_load_lds_dwordx4 v[198:199], off
	s_mov_b32 m0, s37
	s_nop 0
	global_load_lds_dwordx4 v[200:201], off
	s_waitcnt vmcnt(24)
	s_waitcnt lgkmcnt(0)
	s_barrier
	s_setprio 0
	s_waitcnt lgkmcnt(0)
	v_mfma_f32_16x16x32_bf16 v[60:63], v[130:133], v[162:165], 0
	v_mfma_f32_16x16x32_bf16 v[56:59], v[138:141], v[162:165], 0
	v_mfma_f32_16x16x32_bf16 v[44:47], v[130:133], v[170:173], 0
	v_mfma_f32_16x16x32_bf16 v[40:43], v[138:141], v[170:173], 0
	v_mfma_f32_16x16x32_bf16 v[28:31], v[130:133], v[178:181], 0
	v_mfma_f32_16x16x32_bf16 v[24:27], v[138:141], v[178:181], 0
	v_mfma_f32_16x16x32_bf16 v[12:15], v[130:133], v[186:189], 0
	v_mfma_f32_16x16x32_bf16 v[8:11], v[138:141], v[186:189], 0
	v_mfma_f32_16x16x32_bf16 v[60:63], v[134:137], v[166:169], v[60:63]
	v_mfma_f32_16x16x32_bf16 v[56:59], v[142:145], v[166:169], v[56:59]
	v_mfma_f32_16x16x32_bf16 v[44:47], v[134:137], v[174:177], v[44:47]
	v_mfma_f32_16x16x32_bf16 v[40:43], v[142:145], v[174:177], v[40:43]
	v_mfma_f32_16x16x32_bf16 v[28:31], v[134:137], v[182:185], v[28:31]
	v_mfma_f32_16x16x32_bf16 v[24:27], v[142:145], v[182:185], v[24:27]
	v_mfma_f32_16x16x32_bf16 v[12:15], v[134:137], v[190:193], v[12:15]
	v_mfma_f32_16x16x32_bf16 v[8:11], v[142:145], v[190:193], v[8:11]
	s_setprio 0
	s_setprio 0
	v_mfma_f32_16x16x32_bf16 v[52:55], v[146:149], v[162:165], 0
	v_mfma_f32_16x16x32_bf16 v[48:51], v[154:157], v[162:165], 0
	v_mfma_f32_16x16x32_bf16 v[36:39], v[146:149], v[170:173], 0
	v_mfma_f32_16x16x32_bf16 v[32:35], v[154:157], v[170:173], 0
	v_mfma_f32_16x16x32_bf16 v[20:23], v[146:149], v[178:181], 0
	v_mfma_f32_16x16x32_bf16 v[16:19], v[154:157], v[178:181], 0
	v_mfma_f32_16x16x32_bf16 v[4:7], v[146:149], v[186:189], 0
	v_mfma_f32_16x16x32_bf16 v[0:3], v[154:157], v[186:189], 0
	v_mfma_f32_16x16x32_bf16 v[52:55], v[150:153], v[166:169], v[52:55]
	v_mfma_f32_16x16x32_bf16 v[48:51], v[158:161], v[166:169], v[48:51]
	v_mfma_f32_16x16x32_bf16 v[36:39], v[150:153], v[174:177], v[36:39]
	v_mfma_f32_16x16x32_bf16 v[32:35], v[158:161], v[174:177], v[32:35]
	v_mfma_f32_16x16x32_bf16 v[20:23], v[150:153], v[182:185], v[20:23]
	v_mfma_f32_16x16x32_bf16 v[16:19], v[158:161], v[182:185], v[16:19]
	v_mfma_f32_16x16x32_bf16 v[4:7], v[150:153], v[190:193], v[4:7]
	v_mfma_f32_16x16x32_bf16 v[0:3], v[158:161], v[190:193], v[0:3]
	s_setprio 0
	s_barrier
	s_add_i32 s59, 0, 0x18000
	v_add_u32_e32 v84, s59, v237
	v_add_u32_e32 v250, s59, v247
	s_add_i32 s60, 0, 0x1c000
	ds_read_b128 v[130:133], v84
	ds_read_b128 v[134:137], v250
	ds_read_b128 v[138:141], v84 offset:2048
	ds_read_b128 v[142:145], v250 offset:2048
	v_add_u32_e32 v84, s60, v237
	v_add_u32_e32 v251, s60, v247
	ds_read_b128 v[146:149], v84
	ds_read_b128 v[150:153], v251
	ds_read_b128 v[154:157], v84 offset:2048
	ds_read_b128 v[158:161], v251 offset:2048
	s_add_u32 s34, s34, 0x40000
	s_addc_u32 s35, s35, 0
	s_mov_b32 m0, s38
	v_lshl_add_u64 v[84:85], s[34:35], 0, v[210:211]
	ds_read_b128 v[162:165], v241 offset:32768
	ds_read_b128 v[166:169], v246 offset:32768
	ds_read_b128 v[170:173], v241 offset:34816
	ds_read_b128 v[174:177], v246 offset:34816
	ds_read_b128 v[178:181], v241 offset:36864
	ds_read_b128 v[182:185], v246 offset:36864
	ds_read_b128 v[186:189], v241 offset:38912
	ds_read_b128 v[190:193], v246 offset:38912
	global_load_lds_dwordx4 v[84:85], off
	v_lshl_add_u64 v[84:85], s[34:35], 0, v[214:215]
	s_mov_b32 m0, s39
	s_nop 0
	global_load_lds_dwordx4 v[84:85], off
	s_waitcnt vmcnt(8)
	s_waitcnt lgkmcnt(0)
	s_barrier
	s_setprio 0
	s_waitcnt lgkmcnt(0)
	v_mfma_f32_16x16x32_bf16 v[126:129], v[130:133], v[162:165], v[126:129]
	v_mfma_f32_16x16x32_bf16 v[122:125], v[138:141], v[162:165], v[122:125]
	v_mfma_f32_16x16x32_bf16 v[110:113], v[130:133], v[170:173], v[110:113]
	v_mfma_f32_16x16x32_bf16 v[106:109], v[138:141], v[170:173], v[106:109]
	v_mfma_f32_16x16x32_bf16 v[94:97], v[130:133], v[178:181], v[94:97]
	v_mfma_f32_16x16x32_bf16 v[90:93], v[138:141], v[178:181], v[90:93]
	v_mfma_f32_16x16x32_bf16 v[76:79], v[130:133], v[186:189], v[76:79]
	v_mfma_f32_16x16x32_bf16 v[72:75], v[138:141], v[186:189], v[72:75]
	v_mfma_f32_16x16x32_bf16 v[126:129], v[134:137], v[166:169], v[126:129]
	v_mfma_f32_16x16x32_bf16 v[122:125], v[142:145], v[166:169], v[122:125]
	v_mfma_f32_16x16x32_bf16 v[110:113], v[134:137], v[174:177], v[110:113]
	v_mfma_f32_16x16x32_bf16 v[106:109], v[142:145], v[174:177], v[106:109]
	v_mfma_f32_16x16x32_bf16 v[94:97], v[134:137], v[182:185], v[94:97]
	v_mfma_f32_16x16x32_bf16 v[90:93], v[142:145], v[182:185], v[90:93]
	v_mfma_f32_16x16x32_bf16 v[76:79], v[134:137], v[190:193], v[76:79]
	v_mfma_f32_16x16x32_bf16 v[72:75], v[142:145], v[190:193], v[72:75]
	s_setprio 0
	s_setprio 0
	v_mfma_f32_16x16x32_bf16 v[118:121], v[146:149], v[162:165], v[118:121]
	v_mfma_f32_16x16x32_bf16 v[114:117], v[154:157], v[162:165], v[114:117]
	v_mfma_f32_16x16x32_bf16 v[102:105], v[146:149], v[170:173], v[102:105]
	v_mfma_f32_16x16x32_bf16 v[98:101], v[154:157], v[170:173], v[98:101]
	v_mfma_f32_16x16x32_bf16 v[84:87], v[146:149], v[178:181], v[86:89]
	v_mfma_f32_16x16x32_bf16 v[80:83], v[154:157], v[178:181], v[80:83]
	v_mfma_f32_16x16x32_bf16 v[68:71], v[146:149], v[186:189], v[68:71]
	v_mfma_f32_16x16x32_bf16 v[64:67], v[154:157], v[186:189], v[64:67]
	v_mfma_f32_16x16x32_bf16 v[118:121], v[150:153], v[166:169], v[118:121]
	v_mfma_f32_16x16x32_bf16 v[114:117], v[158:161], v[166:169], v[114:117]
	v_mfma_f32_16x16x32_bf16 v[102:105], v[150:153], v[174:177], v[102:105]
	v_mfma_f32_16x16x32_bf16 v[98:101], v[158:161], v[174:177], v[98:101]
	v_mfma_f32_16x16x32_bf16 v[86:89], v[150:153], v[182:185], v[84:87]
	v_mfma_f32_16x16x32_bf16 v[82:85], v[158:161], v[182:185], v[80:83]
	v_mfma_f32_16x16x32_bf16 v[68:71], v[150:153], v[190:193], v[68:71]
	v_mfma_f32_16x16x32_bf16 v[64:67], v[158:161], v[190:193], v[64:67]
	s_setprio 0
	s_barrier
	s_add_i32 s34, s59, s33
	v_lshl_add_u64 v[80:81], v[194:195], 0, s[16:17]
	s_mov_b32 m0, s34
	ds_read_b128 v[162:165], v241 offset:49152
	ds_read_b128 v[166:169], v246 offset:49152
	ds_read_b128 v[170:173], v241 offset:51200
	ds_read_b128 v[174:177], v246 offset:51200
	ds_read_b128 v[178:181], v241 offset:53248
	ds_read_b128 v[182:185], v246 offset:53248
	ds_read_b128 v[186:189], v241 offset:55296
	ds_read_b128 v[190:193], v246 offset:55296
	global_load_lds_dwordx4 v[80:81], off
	s_add_i32 m0, s34, 0x2000
	s_add_u32 s30, s30, 0x40080
	v_lshl_add_u64 v[80:81], v[196:197], 0, s[16:17]
	s_addc_u32 s31, s31, 0
	s_add_i32 s34, s60, s33
	global_load_lds_dwordx4 v[80:81], off
	v_lshl_add_u64 v[80:81], s[30:31], 0, v[212:213]
	s_mov_b32 m0, s34
	s_nop 0
	global_load_lds_dwordx4 v[80:81], off
	v_lshl_add_u64 v[80:81], s[30:31], 0, v[216:217]
	s_add_i32 m0, s34, 0x2000
	s_nop 0
	global_load_lds_dwordx4 v[80:81], off
	v_lshl_add_u64 v[80:81], v[198:199], 0, s[16:17]
	s_mov_b32 m0, s47
	s_nop 0
	global_load_lds_dwordx4 v[80:81], off
	v_lshl_add_u64 v[80:81], v[200:201], 0, s[16:17]
	s_mov_b32 m0, s48
	s_nop 0
	global_load_lds_dwordx4 v[80:81], off
	s_waitcnt vmcnt(8)
	s_waitcnt lgkmcnt(0)
	s_barrier
	s_setprio 0
	s_waitcnt lgkmcnt(0)
	v_mfma_f32_16x16x32_bf16 v[60:63], v[130:133], v[162:165], v[60:63]
	v_mfma_f32_16x16x32_bf16 v[56:59], v[138:141], v[162:165], v[56:59]
	v_mfma_f32_16x16x32_bf16 v[44:47], v[130:133], v[170:173], v[44:47]
	v_mfma_f32_16x16x32_bf16 v[40:43], v[138:141], v[170:173], v[40:43]
	v_mfma_f32_16x16x32_bf16 v[28:31], v[130:133], v[178:181], v[28:31]
	v_mfma_f32_16x16x32_bf16 v[24:27], v[138:141], v[178:181], v[24:27]
	v_mfma_f32_16x16x32_bf16 v[12:15], v[130:133], v[186:189], v[12:15]
	v_mfma_f32_16x16x32_bf16 v[8:11], v[138:141], v[186:189], v[8:11]
	v_mfma_f32_16x16x32_bf16 v[60:63], v[134:137], v[166:169], v[60:63]
	v_mfma_f32_16x16x32_bf16 v[56:59], v[142:145], v[166:169], v[56:59]
	v_mfma_f32_16x16x32_bf16 v[44:47], v[134:137], v[174:177], v[44:47]
	v_mfma_f32_16x16x32_bf16 v[40:43], v[142:145], v[174:177], v[40:43]
	v_mfma_f32_16x16x32_bf16 v[28:31], v[134:137], v[182:185], v[28:31]
	v_mfma_f32_16x16x32_bf16 v[24:27], v[142:145], v[182:185], v[24:27]
	v_mfma_f32_16x16x32_bf16 v[12:15], v[134:137], v[190:193], v[12:15]
	v_mfma_f32_16x16x32_bf16 v[8:11], v[142:145], v[190:193], v[8:11]
	s_setprio 0
	s_setprio 0
	v_mfma_f32_16x16x32_bf16 v[52:55], v[146:149], v[162:165], v[52:55]
	v_mfma_f32_16x16x32_bf16 v[48:51], v[154:157], v[162:165], v[48:51]
	v_mfma_f32_16x16x32_bf16 v[36:39], v[146:149], v[170:173], v[36:39]
	v_mfma_f32_16x16x32_bf16 v[32:35], v[154:157], v[170:173], v[32:35]
	v_mfma_f32_16x16x32_bf16 v[20:23], v[146:149], v[178:181], v[20:23]
	v_mfma_f32_16x16x32_bf16 v[16:19], v[154:157], v[178:181], v[16:19]
	v_mfma_f32_16x16x32_bf16 v[4:7], v[146:149], v[186:189], v[4:7]
	v_mfma_f32_16x16x32_bf16 v[0:3], v[154:157], v[186:189], v[0:3]
	v_mfma_f32_16x16x32_bf16 v[52:55], v[150:153], v[166:169], v[52:55]
	v_mfma_f32_16x16x32_bf16 v[48:51], v[158:161], v[166:169], v[48:51]
	v_mfma_f32_16x16x32_bf16 v[36:39], v[150:153], v[174:177], v[36:39]
	v_mfma_f32_16x16x32_bf16 v[32:35], v[158:161], v[174:177], v[32:35]
	v_mfma_f32_16x16x32_bf16 v[20:23], v[150:153], v[182:185], v[20:23]
	v_mfma_f32_16x16x32_bf16 v[16:19], v[158:161], v[182:185], v[16:19]
	v_mfma_f32_16x16x32_bf16 v[4:7], v[150:153], v[190:193], v[4:7]
	v_mfma_f32_16x16x32_bf16 v[0:3], v[158:161], v[190:193], v[0:3]
	s_setprio 0
	s_barrier
	s_add_i32 s58, s58, 2
	s_add_u32 s28, s28, 0x100
	s_addc_u32 s29, s29, 0
	s_add_u32 s56, s56, 0x100
	s_addc_u32 s57, s57, 0
	s_cmp_gt_u32 s58, 13

.LBB0_1016:
	s_add_u32 s44, s82, 0x15000
	s_addc_u32 s45, s83, 0
	v_readlane_b32 s48, v254, 3
	s_add_u32 s10, s82, 0x16000000
	v_readlane_b32 s56, v254, 11
	v_readlane_b32 s57, v254, 12
	s_addc_u32 s11, s83, 0
	s_mov_b64 s[12:13], s[56:57]
	s_add_u32 s12, s12, 0x2000
	s_addc_u32 s13, s13, 0
	s_add_u32 s46, s82, 0x17000
	s_addc_u32 s47, s83, 0
	s_add_u32 s14, s82, 0x2f00000
	s_addc_u32 s15, s83, 0
	s_lshl_b32 s1, s1, 5
	s_mov_b64 s[16:17], 0x80
	v_readlane_b32 s49, v254, 4
	s_and_b32 s20, s1, 0x60
	s_add_i32 m0, s31, 0x18000
	v_lshl_add_u64 v[6:7], v[6:7], 0, s[16:17]
	s_lshl_b32 s19, s0, 13
	s_lshl_b32 s1, s20, 7
	s_waitcnt vmcnt(2)
	s_barrier
	global_load_lds_dwordx4 v[6:7], off
	v_lshl_add_u64 v[4:5], v[4:5], 0, s[16:17]
	s_add_i32 m0, s31, 0x1a000
	s_add_i32 s48, s31, 0x8000
	s_add_i32 s49, s31, 0xa000
	global_load_lds_dwordx4 v[4:5], off
	v_lshl_add_u64 v[0:1], v[0:1], 0, s[16:17]
	s_mov_b32 m0, s48
	s_add_u32 s6, s36, 0x40080
	global_load_lds_dwordx4 v[0:1], off
	v_lshl_add_u64 v[0:1], v[2:3], 0, s[16:17]
	s_mov_b32 m0, s49
	s_addc_u32 s7, s37, 0
	global_load_lds_dwordx4 v[0:1], off
	s_add_i32 m0, s31, 0x1c000
	v_lshl_add_u64 v[0:1], s[6:7], 0, v[138:139]
	global_load_lds_dwordx4 v[0:1], off
	v_lshl_add_u64 v[0:1], s[6:7], 0, v[142:143]
	s_add_i32 m0, s31, 0x1e000
	v_readlane_b32 s53, v254, 8
	global_load_lds_dwordx4 v[0:1], off
	v_bfe_u32 v1, v8, 4, 2
	v_and_b32_e32 v0, 15, v8
	v_lshlrev_b32_e32 v2, 4, v1
	v_lshl_or_b32 v184, s0, 6, v0
	v_lshl_or_b32 v0, v0, 6, v2
	v_lshlrev_b32_e32 v2, 2, v8
	v_and_b32_e32 v2, 32, v2
	v_bitop3_b32 v3, v0, s19, v2 bitop3:0xde
	v_bitop3_b32 v185, v0, s1, v2 bitop3:0xde
	v_lshlrev_b32_e32 v0, 14, v9
	v_and_b32_e32 v0, 0xffff8000, v0
	v_cmp_eq_u32_e64 s[0:1], 0, v1
	v_lshl_or_b32 v186, v1, 3, s20
	v_lshl_add_u32 v0, v10, 11, v0
	v_and_b32_e32 v1, 1, v9
	v_lshl_or_b32 v0, v1, 6, v0
	v_lshl_add_u32 v144, v11, 1, v0
	v_lshlrev_b32_e32 v0, 14, v12
	v_and_b32_e32 v0, 0xffff8000, v0
	v_lshl_add_u32 v0, v13, 11, v0
	v_and_b32_e32 v1, 1, v12
	v_readlane_b32 s54, v254, 9
	s_waitcnt vmcnt(6)
	s_cmpk_lt_u32 s18, 0x100
	v_lshl_or_b32 v0, v1, 6, v0
	v_readlane_b32 s50, v254, 5
	v_readlane_b32 s51, v254, 6
	v_readlane_b32 s52, v254, 7
	s_cselect_b64 s[18:19], -1, 0
	v_lshl_add_u32 v146, v14, 1, v0
	s_add_i32 s53, 0, 0x10000
	s_add_i32 s54, 0, 0x14000
	v_mbcnt_lo_u32_b32 v0, -1, 0
	s_ashr_i32 s50, s86, 31
	s_mov_b32 s51, s86
	s_ashr_i32 s52, s96, 31
	v_mov_b32_e32 v145, v139
	v_mov_b32_e32 v147, v139
	v_mov_b64_e32 v[148:149], 0x200
	v_mov_b64_e32 v[150:151], 0x1ff
	v_add_u32_e32 v187, s53, v185
	v_add_u32_e32 v188, s54, v185
	v_add_u32_e32 v189, 0, v3
	v_mbcnt_hi_u32_b32 v190, -1, v0
	v_readlane_b32 s55, v254, 10
	v_readlane_b32 s58, v254, 13
	v_readlane_b32 s59, v254, 14
	v_readlane_b32 s60, v254, 15
	v_readlane_b32 s61, v254, 16
	v_readlane_b32 s62, v254, 17
	v_readlane_b32 s63, v254, 18
	s_barrier
	v_sub_u32_e32 v144, v144, v252
	v_add_u32_e32 v144, v144, v136
	v_sub_u32_e32 v146, v146, v253
	v_add_u32_e32 v146, v146, v140
	v_and_b32_e32 v250, 63, v236
	v_and_b32_e32 v251, 15, v250
	v_lshrrev_b32_e32 v252, 4, v250
	v_and_b32_e32 v253, 7, v251
	v_xor_b32_e32 v252, v252, v253
	v_lshlrev_b32_e32 v252, 4, v252
	v_lshl_add_u32 v252, v251, 7, v252
	v_lshrrev_b32_e32 v250, 6, v236
	v_lshrrev_b32_e32 v251, 2, v250
	v_lshl_add_u32 v189, v251, 13, v252
	v_and_b32_e32 v251, 3, v250
	v_lshl_add_u32 v185, v251, 12, v252
	v_add_u32_e32 v187, s53, v185
	v_add_u32_e32 v188, s54, v185
	s_add_i32 s43, s43, 1
	s_mul_i32 s6, s43, s50
	s_mul_hi_u32 s7, s43, s51
	s_add_i32 s7, s7, s6
	s_mul_i32 s6, s43, s51
	s_add_u32 s24, s6, s96
	s_addc_u32 s25, s7, s52
	v_cmp_gt_i64_e32 vcc, s[24:25], v[150:151]
	v_cmp_lt_i64_e64 s[6:7], s[24:25], v[148:149]
	s_cbranch_vccnz .Lfu_1025
	s_ashr_i32 s20, s24, 31
	s_lshr_b32 s20, s20, 29
	s_add_i32 s22, s24, s20
	s_and_b32 s20, s22, -8
	s_sub_i32 s23, s24, s20
	s_cmp_gt_i32 s23, -1
	s_mov_b64 s[20:21], -1
	s_cbranch_scc0 .Lfu_1022
	s_lshl_b32 s24, s23, 6
	s_mov_b64 s[20:21], 0

.Lfu_1025:
	s_ashr_i32 s23, s22, 31
	s_lshl_b64 s[24:25], s[22:23], 19
	s_add_u32 s24, s90, s24
	s_addc_u32 s25, s91, s25
	s_and_b64 s[26:27], s[6:7], exec
	s_cselect_b32 s23, s25, s35
	s_cselect_b32 s29, s24, s34
	s_ashr_i32 s21, s20, 31
	s_lshl_b64 s[26:27], s[20:21], 19
	s_add_u32 s26, s2, s26
	s_addc_u32 s27, s3, s27
	s_and_b64 s[38:39], s[6:7], exec
	s_cselect_b32 s21, s27, s37
	s_cselect_b32 s55, s26, s36
	s_add_u32 s34, s34, 0x40080
	s_addc_u32 s35, s35, 0
	s_add_u32 s56, s36, 0x100
	v_mov_b32_e32 v0, 0
	s_addc_u32 s57, s37, 0
	s_mov_b32 s58, -2
	s_waitcnt lgkmcnt(0)
	v_mov_b32_e32 v1, v0
	v_mov_b32_e32 v2, v0
	v_mov_b32_e32 v3, v0
	v_mov_b32_e32 v4, v0
	v_mov_b32_e32 v5, v0
	v_mov_b32_e32 v6, v0
	v_mov_b32_e32 v7, v0
	v_mov_b32_e32 v16, v0
	v_mov_b32_e32 v17, v0
	v_mov_b32_e32 v18, v0
	v_mov_b32_e32 v19, v0
	v_mov_b32_e32 v20, v0
	v_mov_b32_e32 v21, v0
	v_mov_b32_e32 v22, v0
	v_mov_b32_e32 v23, v0
	v_mov_b32_e32 v32, v0
	v_mov_b32_e32 v33, v0
	v_mov_b32_e32 v34, v0
	v_mov_b32_e32 v35, v0
	v_mov_b32_e32 v36, v0
	v_mov_b32_e32 v37, v0
	v_mov_b32_e32 v38, v0
	v_mov_b32_e32 v39, v0
	v_mov_b32_e32 v48, v0
	v_mov_b32_e32 v49, v0
	v_mov_b32_e32 v50, v0
	v_mov_b32_e32 v51, v0
	v_mov_b32_e32 v52, v0
	v_mov_b32_e32 v53, v0
	v_mov_b32_e32 v54, v0
	v_mov_b32_e32 v55, v0
	v_mov_b32_e32 v8, v0
	v_mov_b32_e32 v9, v0
	v_mov_b32_e32 v10, v0
	v_mov_b32_e32 v11, v0
	v_mov_b32_e32 v12, v0
	v_mov_b32_e32 v13, v0
	v_mov_b32_e32 v14, v0
	v_mov_b32_e32 v15, v0
	v_mov_b32_e32 v24, v0
	v_mov_b32_e32 v25, v0
	v_mov_b32_e32 v26, v0
	v_mov_b32_e32 v27, v0
	v_mov_b32_e32 v28, v0
	v_mov_b32_e32 v29, v0
	v_mov_b32_e32 v30, v0
	v_mov_b32_e32 v31, v0
	v_mov_b32_e32 v40, v0
	v_mov_b32_e32 v41, v0
	v_mov_b32_e32 v42, v0
	v_mov_b32_e32 v43, v0
	v_mov_b32_e32 v44, v0
	v_mov_b32_e32 v45, v0
	v_mov_b32_e32 v46, v0
	v_mov_b32_e32 v47, v0
	v_mov_b32_e32 v56, v0
	v_mov_b32_e32 v57, v0
	v_mov_b32_e32 v58, v0
	v_mov_b32_e32 v59, v0
	v_mov_b32_e32 v60, v0
	v_mov_b32_e32 v61, v0
	v_mov_b32_e32 v62, v0
	v_mov_b32_e32 v63, v0
	v_mov_b32_e32 v64, v0
	v_mov_b32_e32 v65, v0
	v_mov_b32_e32 v66, v0
	v_mov_b32_e32 v67, v0
	v_mov_b32_e32 v68, v0
	v_mov_b32_e32 v69, v0
	v_mov_b32_e32 v70, v0
	v_mov_b32_e32 v71, v0
	v_mov_b32_e32 v80, v0
	v_mov_b32_e32 v81, v0
	v_mov_b32_e32 v82, v0
	v_mov_b32_e32 v83, v0
	v_mov_b32_e32 v84, v0
	v_mov_b32_e32 v85, v0
	v_mov_b32_e32 v86, v0
	v_mov_b32_e32 v87, v0
	v_mov_b32_e32 v96, v0
	v_mov_b32_e32 v97, v0
	v_mov_b32_e32 v98, v0
	v_mov_b32_e32 v99, v0
	v_mov_b32_e32 v100, v0
	v_mov_b32_e32 v101, v0
	v_mov_b32_e32 v102, v0
	v_mov_b32_e32 v103, v0
	v_mov_b32_e32 v112, v0
	v_mov_b32_e32 v113, v0
	v_mov_b32_e32 v114, v0
	v_mov_b32_e32 v115, v0
	v_mov_b32_e32 v116, v0
	v_mov_b32_e32 v117, v0
	v_mov_b32_e32 v118, v0
	v_mov_b32_e32 v119, v0
	v_mov_b32_e32 v72, v0
	s_waitcnt vmcnt(0)
	v_mov_b32_e32 v73, v0
	v_mov_b32_e32 v74, v0
	v_mov_b32_e32 v75, v0
	v_mov_b32_e32 v76, v0
	v_mov_b32_e32 v77, v0
	v_mov_b32_e32 v78, v0
	v_mov_b32_e32 v79, v0
	v_mov_b32_e32 v88, v0
	v_mov_b32_e32 v89, v0
	v_mov_b32_e32 v90, v0
	v_mov_b32_e32 v91, v0
	v_mov_b32_e32 v92, v0
	v_mov_b32_e32 v93, v0
	v_mov_b32_e32 v94, v0
	v_mov_b32_e32 v95, v0
	v_mov_b32_e32 v104, v0
	v_mov_b32_e32 v105, v0
	v_mov_b32_e32 v106, v0
	v_mov_b32_e32 v107, v0
	v_mov_b32_e32 v108, v0
	v_mov_b32_e32 v109, v0
	v_mov_b32_e32 v110, v0
	v_mov_b32_e32 v111, v0
	v_mov_b32_e32 v120, v0
	v_mov_b32_e32 v121, v0
	v_mov_b32_e32 v122, v0
	v_mov_b32_e32 v123, v0
	v_mov_b32_e32 v124, v0
	v_mov_b32_e32 v125, v0
	v_mov_b32_e32 v126, v0
	v_mov_b32_e32 v127, v0
	v_xor_b32_e32 v246, 64, v189
	v_xor_b32_e32 v247, 64, v185
	v_add_u32_e32 v248, s53, v247
	v_add_u32_e32 v249, s54, v247
	s_branch .LBB0_1026

.LBB0_1025:
	s_ashr_i32 s23, s22, 31
	s_lshl_b64 s[24:25], s[22:23], 19
	s_add_u32 s24, s90, s24
	s_addc_u32 s25, s91, s25
	s_and_b64 s[26:27], s[6:7], exec
	s_cselect_b32 s23, s25, s35
	s_cselect_b32 s29, s24, s34
	s_ashr_i32 s21, s20, 31
	s_lshl_b64 s[26:27], s[20:21], 19
	s_add_u32 s26, s2, s26
	s_addc_u32 s27, s3, s27
	s_and_b64 s[38:39], s[6:7], exec
	s_cselect_b32 s21, s27, s37
	s_cselect_b32 s55, s26, s36
	s_add_u32 s34, s34, 0x40080
	s_addc_u32 s35, s35, 0
	s_add_u32 s56, s36, 0x100
	s_addc_u32 s57, s37, 0
	s_mov_b32 s58, -2
	s_waitcnt lgkmcnt(0)
	s_waitcnt vmcnt(0)
	v_xor_b32_e32 v246, 64, v189
	v_xor_b32_e32 v247, 64, v185
	v_add_u32_e32 v248, s53, v247
	v_add_u32_e32 v249, s54, v247
	ds_read_b128 v[128:131], v187
	ds_read_b128 v[132:135], v248
	ds_read_b128 v[152:155], v187 offset:2048
	ds_read_b128 v[156:159], v248 offset:2048
	ds_read_b128 v[160:163], v188
	ds_read_b128 v[164:167], v249
	ds_read_b128 v[168:171], v188 offset:2048
	ds_read_b128 v[172:175], v249 offset:2048
	s_add_u32 s36, s34, 0xfffc0080
	s_addc_u32 s37, s35, -1
	s_cmp_eq_u32 s58, 12
	s_cselect_b32 s39, s23, s37
	s_cselect_b32 s38, s29, s36
	s_cselect_b32 s37, s21, s57
	s_cselect_b32 s36, s55, s56
	v_lshl_add_u64 v[216:217], s[34:35], 0, v[144:145]
	s_add_i32 m0, s31, 0xc000
	ds_read_b128 v[176:179], v189
	ds_read_b128 v[180:183], v246
	ds_read_b128 v[192:195], v189 offset:2048
	ds_read_b128 v[196:199], v246 offset:2048
	ds_read_b128 v[200:203], v189 offset:4096
	ds_read_b128 v[204:207], v246 offset:4096
	ds_read_b128 v[208:211], v189 offset:6144
	ds_read_b128 v[212:215], v246 offset:6144
	global_load_lds_dwordx4 v[216:217], off
	v_lshl_add_u64 v[216:217], s[34:35], 0, v[146:147]
	s_add_i32 m0, s31, 0xe000
	s_nop 0
	global_load_lds_dwordx4 v[216:217], off
	s_waitcnt vmcnt(40)
	s_waitcnt lgkmcnt(0)
	s_barrier
	s_setprio 0
	s_waitcnt lgkmcnt(0)
	v_mfma_f32_16x16x32_bf16 v[124:127], v[128:131], v[176:179], 0
	v_mfma_f32_16x16x32_bf16 v[120:123], v[152:155], v[176:179], 0
	v_mfma_f32_16x16x32_bf16 v[108:111], v[128:131], v[192:195], 0
	v_mfma_f32_16x16x32_bf16 v[104:107], v[152:155], v[192:195], 0
	v_mfma_f32_16x16x32_bf16 v[92:95], v[128:131], v[200:203], 0
	v_mfma_f32_16x16x32_bf16 v[88:91], v[152:155], v[200:203], 0
	v_mfma_f32_16x16x32_bf16 v[76:79], v[128:131], v[208:211], 0
	v_mfma_f32_16x16x32_bf16 v[72:75], v[152:155], v[208:211], 0
	v_mfma_f32_16x16x32_bf16 v[124:127], v[132:135], v[180:183], v[124:127]
	v_mfma_f32_16x16x32_bf16 v[120:123], v[156:159], v[180:183], v[120:123]
	v_mfma_f32_16x16x32_bf16 v[108:111], v[132:135], v[196:199], v[108:111]
	v_mfma_f32_16x16x32_bf16 v[104:107], v[156:159], v[196:199], v[104:107]
	v_mfma_f32_16x16x32_bf16 v[92:95], v[132:135], v[204:207], v[92:95]
	v_mfma_f32_16x16x32_bf16 v[88:91], v[156:159], v[204:207], v[88:91]
	v_mfma_f32_16x16x32_bf16 v[76:79], v[132:135], v[212:215], v[76:79]
	v_mfma_f32_16x16x32_bf16 v[72:75], v[156:159], v[212:215], v[72:75]
	s_setprio 0
	s_setprio 0
	v_mfma_f32_16x16x32_bf16 v[116:119], v[160:163], v[176:179], 0
	v_mfma_f32_16x16x32_bf16 v[112:115], v[168:171], v[176:179], 0
	v_mfma_f32_16x16x32_bf16 v[100:103], v[160:163], v[192:195], 0
	v_mfma_f32_16x16x32_bf16 v[96:99], v[168:171], v[192:195], 0
	v_mfma_f32_16x16x32_bf16 v[84:87], v[160:163], v[200:203], 0
	v_mfma_f32_16x16x32_bf16 v[80:83], v[168:171], v[200:203], 0
	v_mfma_f32_16x16x32_bf16 v[68:71], v[160:163], v[208:211], 0
	v_mfma_f32_16x16x32_bf16 v[64:67], v[168:171], v[208:211], 0
	v_mfma_f32_16x16x32_bf16 v[116:119], v[164:167], v[180:183], v[116:119]
	v_mfma_f32_16x16x32_bf16 v[112:115], v[172:175], v[180:183], v[112:115]
	v_mfma_f32_16x16x32_bf16 v[100:103], v[164:167], v[196:199], v[100:103]
	v_mfma_f32_16x16x32_bf16 v[96:99], v[172:175], v[196:199], v[96:99]
	v_mfma_f32_16x16x32_bf16 v[84:87], v[164:167], v[204:207], v[84:87]
	v_mfma_f32_16x16x32_bf16 v[80:83], v[172:175], v[204:207], v[80:83]
	v_mfma_f32_16x16x32_bf16 v[68:71], v[164:167], v[212:215], v[68:71]
	v_mfma_f32_16x16x32_bf16 v[64:67], v[172:175], v[212:215], v[64:67]
	s_setprio 0
	s_barrier
	s_add_i32 s59, s53, s33
	v_lshl_add_u64 v[216:217], s[36:37], 0, v[138:139]
	s_mov_b32 m0, s59
	ds_read_b128 v[176:179], v189 offset:16384
	ds_read_b128 v[180:183], v246 offset:16384
	ds_read_b128 v[192:195], v189 offset:18432
	ds_read_b128 v[196:199], v246 offset:18432
	ds_read_b128 v[200:203], v189 offset:20480
	ds_read_b128 v[204:207], v246 offset:20480
	ds_read_b128 v[208:211], v189 offset:22528
	ds_read_b128 v[212:215], v246 offset:22528
	global_load_lds_dwordx4 v[216:217], off
	s_add_i32 m0, s59, 0x2000
	s_add_u32 s60, s36, 0x40000
	v_lshl_add_u64 v[218:219], s[36:37], 0, v[142:143]
	s_addc_u32 s61, s37, 0
	s_add_i32 s59, s54, s33
	global_load_lds_dwordx4 v[218:219], off
	v_lshl_add_u64 v[220:221], s[60:61], 0, v[138:139]
	s_mov_b32 m0, s59
	v_lshl_add_u64 v[222:223], s[38:39], 0, v[140:141]
	global_load_lds_dwordx4 v[220:221], off
	v_lshl_add_u64 v[220:221], s[60:61], 0, v[142:143]
	s_add_i32 m0, s59, 0x2000
	s_nop 0
	global_load_lds_dwordx4 v[220:221], off
	v_lshl_add_u64 v[220:221], s[38:39], 0, v[136:137]
	s_mov_b32 m0, s31
	s_nop 0
	global_load_lds_dwordx4 v[220:221], off
	s_mov_b32 m0, s40
	s_nop 0
	global_load_lds_dwordx4 v[222:223], off
	s_waitcnt vmcnt(40)
	s_waitcnt lgkmcnt(0)
	s_barrier
	s_setprio 0
	s_waitcnt lgkmcnt(0)
	v_mfma_f32_16x16x32_bf16 v[60:63], v[128:131], v[176:179], 0
	v_mfma_f32_16x16x32_bf16 v[56:59], v[152:155], v[176:179], 0
	v_mfma_f32_16x16x32_bf16 v[44:47], v[128:131], v[192:195], 0
	v_mfma_f32_16x16x32_bf16 v[40:43], v[152:155], v[192:195], 0
	v_mfma_f32_16x16x32_bf16 v[28:31], v[128:131], v[200:203], 0
	v_mfma_f32_16x16x32_bf16 v[24:27], v[152:155], v[200:203], 0
	v_mfma_f32_16x16x32_bf16 v[12:15], v[128:131], v[208:211], 0
	v_mfma_f32_16x16x32_bf16 v[8:11], v[152:155], v[208:211], 0
	v_mfma_f32_16x16x32_bf16 v[60:63], v[132:135], v[180:183], v[60:63]
	v_mfma_f32_16x16x32_bf16 v[56:59], v[156:159], v[180:183], v[56:59]
	v_mfma_f32_16x16x32_bf16 v[44:47], v[132:135], v[196:199], v[44:47]
	v_mfma_f32_16x16x32_bf16 v[40:43], v[156:159], v[196:199], v[40:43]
	v_mfma_f32_16x16x32_bf16 v[28:31], v[132:135], v[204:207], v[28:31]
	v_mfma_f32_16x16x32_bf16 v[24:27], v[156:159], v[204:207], v[24:27]
	v_mfma_f32_16x16x32_bf16 v[12:15], v[132:135], v[212:215], v[12:15]
	v_mfma_f32_16x16x32_bf16 v[8:11], v[156:159], v[212:215], v[8:11]
	s_setprio 0
	s_setprio 0
	v_mfma_f32_16x16x32_bf16 v[52:55], v[160:163], v[176:179], 0
	v_mfma_f32_16x16x32_bf16 v[48:51], v[168:171], v[176:179], 0
	v_mfma_f32_16x16x32_bf16 v[36:39], v[160:163], v[192:195], 0
	v_mfma_f32_16x16x32_bf16 v[32:35], v[168:171], v[192:195], 0
	v_mfma_f32_16x16x32_bf16 v[20:23], v[160:163], v[200:203], 0
	v_mfma_f32_16x16x32_bf16 v[16:19], v[168:171], v[200:203], 0
	v_mfma_f32_16x16x32_bf16 v[4:7], v[160:163], v[208:211], 0
	v_mfma_f32_16x16x32_bf16 v[0:3], v[168:171], v[208:211], 0
	v_mfma_f32_16x16x32_bf16 v[52:55], v[164:167], v[180:183], v[52:55]
	v_mfma_f32_16x16x32_bf16 v[48:51], v[172:175], v[180:183], v[48:51]
	v_mfma_f32_16x16x32_bf16 v[36:39], v[164:167], v[196:199], v[36:39]
	v_mfma_f32_16x16x32_bf16 v[32:35], v[172:175], v[196:199], v[32:35]
	v_mfma_f32_16x16x32_bf16 v[20:23], v[164:167], v[204:207], v[20:23]
	v_mfma_f32_16x16x32_bf16 v[16:19], v[172:175], v[204:207], v[16:19]
	v_mfma_f32_16x16x32_bf16 v[4:7], v[164:167], v[212:215], v[4:7]
	v_mfma_f32_16x16x32_bf16 v[0:3], v[172:175], v[212:215], v[0:3]
	s_setprio 0
	s_barrier
	s_add_i32 s59, 0, 0x18000
	s_add_i32 s60, 0, 0x1c000
	v_add_u32_e32 v156, s59, v185
	v_add_u32_e32 v250, s59, v247
	v_add_u32_e32 v172, s60, v185
	v_add_u32_e32 v251, s60, v247
	ds_read_b128 v[128:131], v156
	ds_read_b128 v[132:135], v250
	ds_read_b128 v[152:155], v156 offset:2048
	ds_read_b128 v[156:159], v250 offset:2048
	ds_read_b128 v[160:163], v172
	ds_read_b128 v[164:167], v251
	ds_read_b128 v[168:171], v172 offset:2048
	ds_read_b128 v[172:175], v251 offset:2048
	s_add_u32 s38, s38, 0x40000
	s_addc_u32 s39, s39, 0
	s_mov_b32 m0, s41
	v_lshl_add_u64 v[224:225], s[38:39], 0, v[136:137]
	ds_read_b128 v[176:179], v189 offset:32768
	ds_read_b128 v[180:183], v246 offset:32768
	ds_read_b128 v[192:195], v189 offset:34816
	ds_read_b128 v[196:199], v246 offset:34816
	ds_read_b128 v[200:203], v189 offset:36864
	ds_read_b128 v[204:207], v246 offset:36864
	ds_read_b128 v[208:211], v189 offset:38912
	ds_read_b128 v[212:215], v246 offset:38912
	global_load_lds_dwordx4 v[224:225], off
	v_lshl_add_u64 v[224:225], s[38:39], 0, v[140:141]
	s_mov_b32 m0, s42
	s_nop 0
	global_load_lds_dwordx4 v[224:225], off
	s_waitcnt vmcnt(8)
	s_waitcnt lgkmcnt(0)
	s_barrier
	s_setprio 0
	s_waitcnt lgkmcnt(0)
	v_mfma_f32_16x16x32_bf16 v[124:127], v[128:131], v[176:179], v[124:127]
	v_mfma_f32_16x16x32_bf16 v[120:123], v[152:155], v[176:179], v[120:123]
	v_mfma_f32_16x16x32_bf16 v[108:111], v[128:131], v[192:195], v[108:111]
	v_mfma_f32_16x16x32_bf16 v[104:107], v[152:155], v[192:195], v[104:107]
	v_mfma_f32_16x16x32_bf16 v[92:95], v[128:131], v[200:203], v[92:95]
	v_mfma_f32_16x16x32_bf16 v[88:91], v[152:155], v[200:203], v[88:91]
	v_mfma_f32_16x16x32_bf16 v[76:79], v[128:131], v[208:211], v[76:79]
	v_mfma_f32_16x16x32_bf16 v[72:75], v[152:155], v[208:211], v[72:75]
	v_mfma_f32_16x16x32_bf16 v[124:127], v[132:135], v[180:183], v[124:127]
	v_mfma_f32_16x16x32_bf16 v[120:123], v[156:159], v[180:183], v[120:123]
	v_mfma_f32_16x16x32_bf16 v[108:111], v[132:135], v[196:199], v[108:111]
	v_mfma_f32_16x16x32_bf16 v[104:107], v[156:159], v[196:199], v[104:107]
	v_mfma_f32_16x16x32_bf16 v[92:95], v[132:135], v[204:207], v[92:95]
	v_mfma_f32_16x16x32_bf16 v[88:91], v[156:159], v[204:207], v[88:91]
	v_mfma_f32_16x16x32_bf16 v[76:79], v[132:135], v[212:215], v[76:79]
	v_mfma_f32_16x16x32_bf16 v[72:75], v[156:159], v[212:215], v[72:75]
	s_setprio 0
	s_setprio 0
	v_mfma_f32_16x16x32_bf16 v[116:119], v[160:163], v[176:179], v[116:119]
	v_mfma_f32_16x16x32_bf16 v[112:115], v[168:171], v[176:179], v[112:115]
	v_mfma_f32_16x16x32_bf16 v[100:103], v[160:163], v[192:195], v[100:103]
	v_mfma_f32_16x16x32_bf16 v[96:99], v[168:171], v[192:195], v[96:99]
	v_mfma_f32_16x16x32_bf16 v[84:87], v[160:163], v[200:203], v[84:87]
	v_mfma_f32_16x16x32_bf16 v[80:83], v[168:171], v[200:203], v[80:83]
	v_mfma_f32_16x16x32_bf16 v[68:71], v[160:163], v[208:211], v[68:71]
	v_mfma_f32_16x16x32_bf16 v[64:67], v[168:171], v[208:211], v[64:67]
	v_mfma_f32_16x16x32_bf16 v[116:119], v[164:167], v[180:183], v[116:119]
	v_mfma_f32_16x16x32_bf16 v[112:115], v[172:175], v[180:183], v[112:115]
	v_mfma_f32_16x16x32_bf16 v[100:103], v[164:167], v[196:199], v[100:103]
	v_mfma_f32_16x16x32_bf16 v[96:99], v[172:175], v[196:199], v[96:99]
	v_mfma_f32_16x16x32_bf16 v[84:87], v[164:167], v[204:207], v[84:87]
	v_mfma_f32_16x16x32_bf16 v[80:83], v[172:175], v[204:207], v[80:83]
	v_mfma_f32_16x16x32_bf16 v[68:71], v[164:167], v[212:215], v[68:71]
	v_mfma_f32_16x16x32_bf16 v[64:67], v[172:175], v[212:215], v[64:67]
	s_setprio 0
	s_barrier
	s_add_i32 s38, s59, s33
	v_lshl_add_u64 v[216:217], v[216:217], 0, s[16:17]
	s_mov_b32 m0, s38
	ds_read_b128 v[176:179], v189 offset:49152
	ds_read_b128 v[180:183], v246 offset:49152
	ds_read_b128 v[192:195], v189 offset:51200
	ds_read_b128 v[196:199], v246 offset:51200
	ds_read_b128 v[200:203], v189 offset:53248
	ds_read_b128 v[204:207], v246 offset:53248
	ds_read_b128 v[208:211], v189 offset:55296
	ds_read_b128 v[212:215], v246 offset:55296
	global_load_lds_dwordx4 v[216:217], off
	s_add_i32 m0, s38, 0x2000
	s_add_u32 s36, s36, 0x40080
	v_lshl_add_u64 v[216:217], v[218:219], 0, s[16:17]
	s_addc_u32 s37, s37, 0
	s_add_i32 s38, s60, s33
	global_load_lds_dwordx4 v[216:217], off
	v_lshl_add_u64 v[216:217], s[36:37], 0, v[138:139]
	s_mov_b32 m0, s38
	s_nop 0
	global_load_lds_dwordx4 v[216:217], off
	v_lshl_add_u64 v[216:217], s[36:37], 0, v[142:143]
	s_add_i32 m0, s38, 0x2000
	s_nop 0
	global_load_lds_dwordx4 v[216:217], off
	v_lshl_add_u64 v[216:217], v[220:221], 0, s[16:17]
	s_mov_b32 m0, s48
	s_nop 0
	global_load_lds_dwordx4 v[216:217], off
	v_lshl_add_u64 v[216:217], v[222:223], 0, s[16:17]
	s_mov_b32 m0, s49
	s_nop 0
	global_load_lds_dwordx4 v[216:217], off
	s_waitcnt vmcnt(8)
	s_waitcnt lgkmcnt(0)
	s_barrier
	s_setprio 0
	s_waitcnt lgkmcnt(0)
	v_mfma_f32_16x16x32_bf16 v[60:63], v[128:131], v[176:179], v[60:63]
	v_mfma_f32_16x16x32_bf16 v[56:59], v[152:155], v[176:179], v[56:59]
	v_mfma_f32_16x16x32_bf16 v[44:47], v[128:131], v[192:195], v[44:47]
	v_mfma_f32_16x16x32_bf16 v[40:43], v[152:155], v[192:195], v[40:43]
	v_mfma_f32_16x16x32_bf16 v[28:31], v[128:131], v[200:203], v[28:31]
	v_mfma_f32_16x16x32_bf16 v[24:27], v[152:155], v[200:203], v[24:27]
	v_mfma_f32_16x16x32_bf16 v[12:15], v[128:131], v[208:211], v[12:15]
	v_mfma_f32_16x16x32_bf16 v[8:11], v[152:155], v[208:211], v[8:11]
	v_mfma_f32_16x16x32_bf16 v[60:63], v[132:135], v[180:183], v[60:63]
	v_mfma_f32_16x16x32_bf16 v[56:59], v[156:159], v[180:183], v[56:59]
	v_mfma_f32_16x16x32_bf16 v[44:47], v[132:135], v[196:199], v[44:47]
	v_mfma_f32_16x16x32_bf16 v[40:43], v[156:159], v[196:199], v[40:43]
	v_mfma_f32_16x16x32_bf16 v[28:31], v[132:135], v[204:207], v[28:31]
	v_mfma_f32_16x16x32_bf16 v[24:27], v[156:159], v[204:207], v[24:27]
	v_mfma_f32_16x16x32_bf16 v[12:15], v[132:135], v[212:215], v[12:15]
	v_mfma_f32_16x16x32_bf16 v[8:11], v[156:159], v[212:215], v[8:11]
	s_setprio 0
	s_setprio 0
	v_mfma_f32_16x16x32_bf16 v[52:55], v[160:163], v[176:179], v[52:55]
	v_mfma_f32_16x16x32_bf16 v[48:51], v[168:171], v[176:179], v[48:51]
	v_mfma_f32_16x16x32_bf16 v[36:39], v[160:163], v[192:195], v[36:39]
	v_mfma_f32_16x16x32_bf16 v[32:35], v[168:171], v[192:195], v[32:35]
	v_mfma_f32_16x16x32_bf16 v[20:23], v[160:163], v[200:203], v[20:23]
	v_mfma_f32_16x16x32_bf16 v[16:19], v[168:171], v[200:203], v[16:19]
	v_mfma_f32_16x16x32_bf16 v[4:7], v[160:163], v[208:211], v[4:7]
	v_mfma_f32_16x16x32_bf16 v[0:3], v[168:171], v[208:211], v[0:3]
	v_mfma_f32_16x16x32_bf16 v[52:55], v[164:167], v[180:183], v[52:55]
	v_mfma_f32_16x16x32_bf16 v[48:51], v[172:175], v[180:183], v[48:51]
	v_mfma_f32_16x16x32_bf16 v[36:39], v[164:167], v[196:199], v[36:39]
	v_mfma_f32_16x16x32_bf16 v[32:35], v[172:175], v[196:199], v[32:35]
	v_mfma_f32_16x16x32_bf16 v[20:23], v[164:167], v[204:207], v[20:23]
	v_mfma_f32_16x16x32_bf16 v[16:19], v[172:175], v[204:207], v[16:19]
	v_mfma_f32_16x16x32_bf16 v[4:7], v[164:167], v[212:215], v[4:7]
	v_mfma_f32_16x16x32_bf16 v[0:3], v[172:175], v[212:215], v[0:3]
	s_setprio 0
	s_barrier
	s_add_i32 s58, s58, 2
	s_add_u32 s34, s34, 0x100
	s_addc_u32 s35, s35, 0
	s_add_u32 s56, s56, 0x100
	s_addc_u32 s57, s57, 0
	s_cmp_gt_u32 s58, 13

.LBB0_1107:
	s_add_u32 s8, s82, 0x2f00000
	s_addc_u32 s9, s83, 0
	s_add_u32 s40, s82, 0x2f40000
	s_addc_u32 s41, s83, 0
	s_lshl_b32 s10, s10, 5
	s_and_b32 s16, s10, 0x60
	s_mov_b64 s[10:11], 0x80
	s_add_i32 m0, s23, 0x18000
	v_lshl_add_u64 v[6:7], v[6:7], 0, s[10:11]
	s_ashr_i32 s42, s86, 31
	s_lshl_b32 s13, s12, 13
	s_lshl_b32 s17, s16, 7
	s_waitcnt vmcnt(2)
	s_barrier
	global_load_lds_dwordx4 v[6:7], off
	v_lshl_add_u64 v[4:5], v[4:5], 0, s[10:11]
	s_add_i32 m0, s23, 0x1a000
	s_add_i32 s43, s23, 0x8000
	s_add_i32 s44, s23, 0xa000
	global_load_lds_dwordx4 v[4:5], off
	v_lshl_add_u64 v[0:1], v[0:1], 0, s[10:11]
	s_mov_b32 m0, s43
	s_add_u32 s14, s26, 0x40080
	global_load_lds_dwordx4 v[0:1], off
	v_lshl_add_u64 v[0:1], v[2:3], 0, s[10:11]
	s_mov_b32 m0, s44
	s_addc_u32 s15, s27, 0
	global_load_lds_dwordx4 v[0:1], off
	s_add_i32 m0, s23, 0x1c000
	v_lshl_add_u64 v[0:1], s[14:15], 0, v[148:149]
	global_load_lds_dwordx4 v[0:1], off
	v_lshl_add_u64 v[0:1], s[14:15], 0, v[144:145]
	s_add_i32 m0, s23, 0x1e000
	s_cmpk_lt_u32 s1, 0x100
	global_load_lds_dwordx4 v[0:1], off
	v_lshrrev_b32_e32 v0, 1, v9
	v_and_b32_e32 v0, 24, v0
	v_and_b32_e32 v1, 15, v9
	v_lshlrev_b32_e32 v2, 1, v0
	v_lshl_or_b32 v161, s12, 6, v1
	v_lshl_or_b32 v1, v1, 6, v2
	v_lshlrev_b32_e32 v2, 2, v9
	v_and_b32_e32 v2, 32, v2
	v_bitop3_b32 v3, v1, s13, v2 bitop3:0xde
	v_bitop3_b32 v167, v1, s17, v2 bitop3:0xde
	v_lshlrev_b32_e32 v1, 14, v13
	v_and_b32_e32 v1, 0xffff8000, v1
	v_lshl_add_u32 v1, v12, 11, v1
	v_and_b32_e32 v2, 1, v13
	v_lshl_or_b32 v1, v2, 6, v1
	v_lshl_add_u32 v152, v14, 1, v1
	v_lshlrev_b32_e32 v1, 14, v8
	v_and_b32_e32 v1, 0xffff8000, v1
	s_waitcnt vmcnt(6)
	v_lshl_add_u32 v1, v10, 11, v1
	v_and_b32_e32 v2, 1, v8
	s_cselect_b64 s[12:13], -1, 0
	v_lshl_or_b32 v1, v2, 6, v1
	s_add_i32 s46, 0, 0x10000
	s_add_i32 s47, 0, 0x14000
	s_sext_i32_i16 s50, s0
	s_mov_b32 s45, s86
	v_or_b32_e32 v169, s16, v0
	v_mov_b32_e32 v153, v149
	v_lshl_add_u32 v154, v11, 1, v1
	v_mov_b32_e32 v155, v149
	v_mov_b64_e32 v[156:157], 0xb00
	v_mov_b64_e32 v[158:159], 0xaff
	v_add_u32_e32 v171, s46, v167
	v_add_u32_e32 v175, s47, v167
	v_add_u32_e32 v179, 0, v3
	s_lshl_b32 s48, s16, 2
	v_lshlrev_b32_e32 v180, 2, v0
	v_mov_b32_e32 v181, 0x358637bd
	s_movk_i32 s49, 0x1600
	s_barrier
	v_sub_u32_e32 v152, v152, v252
	v_add_u32_e32 v152, v152, v150
	v_sub_u32_e32 v154, v154, v253
	v_add_u32_e32 v154, v154, v146
	v_and_b32_e32 v250, 63, v236
	v_and_b32_e32 v251, 15, v250
	v_lshrrev_b32_e32 v252, 4, v250
	v_and_b32_e32 v253, 7, v251
	v_xor_b32_e32 v252, v252, v253
	v_lshlrev_b32_e32 v252, 4, v252
	v_lshl_add_u32 v252, v251, 7, v252
	v_lshrrev_b32_e32 v250, 6, v236
	v_lshrrev_b32_e32 v251, 2, v250
	v_lshl_add_u32 v179, v251, 13, v252
	v_and_b32_e32 v251, 3, v250
	v_lshl_add_u32 v167, v251, 12, v252
	v_add_u32_e32 v171, s46, v167
	v_add_u32_e32 v175, s47, v167
	s_add_i32 s39, s39, 1
	s_mul_i32 s0, s39, s42
	s_mul_hi_u32 s1, s39, s45
	s_add_i32 s1, s1, s0
	s_mul_i32 s0, s39, s45
	s_add_u32 s18, s0, s96
	s_addc_u32 s19, s1, s34
	v_cmp_gt_i64_e32 vcc, s[18:19], v[158:159]
	v_cmp_lt_i64_e64 s[0:1], s[18:19], v[156:157]
	s_cbranch_vccnz .Lfu_1112
	s_ashr_i32 s14, s18, 31
	s_lshr_b32 s14, s14, 29
	s_add_i32 s14, s18, s14
	s_ashr_i32 s15, s14, 3
	s_and_b32 s14, s14, -8
	s_sub_i32 s14, s18, s14
	s_cmp_lt_i32 s14, 0
	s_cselect_b32 s16, s35, 0x160
	s_mul_i32 s14, s14, s16
	s_add_i32 s14, s14, s15
	s_mul_hi_i32 s15, s14, 0x2e8ba2e9
	s_lshr_b32 s16, s15, 31
	s_ashr_i32 s15, s15, 5
	s_add_i32 s15, s15, s16
	s_lshl_b32 s16, s15, 3
	s_sub_i32 s17, 0x80, s16
	s_min_i32 s17, s17, 8
	s_abs_i32 s18, s17
	v_cvt_f32_u32_e32 v0, s18
	s_sub_i32 s20, 0, s18
	s_mulk_i32 s15, 0xb0
	s_sub_i32 s15, s14, s15
	v_rcp_iflag_f32_e32 v0, v0
	s_abs_i32 s14, s15
	s_xor_b32 s19, s15, s17
	s_ashr_i32 s19, s19, 31
	v_mul_f32_e32 v0, 0x4f7ffffe, v0
	v_cvt_u32_f32_e32 v0, v0
	s_nop 0
	v_readfirstlane_b32 s21, v0
	s_mul_i32 s20, s20, s21
	s_mul_hi_u32 s20, s21, s20
	s_add_i32 s21, s21, s20
	s_mul_hi_u32 s20, s14, s21
	s_mul_i32 s21, s20, s18
	s_sub_i32 s14, s14, s21
	s_add_i32 s28, s20, 1
	s_sub_i32 s21, s14, s18
	s_cmp_ge_u32 s14, s18
	s_cselect_b32 s20, s28, s20
	s_cselect_b32 s14, s21, s14
	s_add_i32 s21, s20, 1
	s_cmp_ge_u32 s14, s18
	s_cselect_b32 s14, s21, s20
	s_xor_b32 s14, s14, s19
	s_sub_i32 s14, s14, s19
	s_mul_i32 s17, s14, s17
	s_sub_i32 s15, s15, s17
	s_add_i32 s16, s16, s15
.Lfu_1112:
	s_ashr_i32 s17, s16, 31
	s_lshl_b64 s[18:19], s[16:17], 19
	s_add_u32 s18, s2, s18
	s_addc_u32 s19, s3, s19
	s_and_b64 s[20:21], s[0:1], exec
	s_cselect_b32 s17, s19, s25
	s_cselect_b32 s51, s18, s24
	s_ashr_i32 s15, s14, 31
	s_lshl_b64 s[20:21], s[14:15], 19
	s_add_u32 s20, s30, s20
	s_addc_u32 s21, s31, s21
	s_and_b64 s[28:29], s[0:1], exec
	s_cselect_b32 s15, s21, s27
	s_cselect_b32 s52, s20, s26
	s_add_u32 s24, s24, 0x40080
	s_addc_u32 s25, s25, 0
	s_add_u32 s53, s26, 0x100
	v_mov_b32_e32 v0, 0
	s_addc_u32 s54, s27, 0
	s_mov_b32 s55, -2
	v_mov_b32_e32 v1, v0
	v_mov_b32_e32 v2, v0
	v_mov_b32_e32 v3, v0
	v_mov_b32_e32 v4, v0
	v_mov_b32_e32 v5, v0
	v_mov_b32_e32 v6, v0
	v_mov_b32_e32 v7, v0
	v_mov_b32_e32 v16, v0
	v_mov_b32_e32 v17, v0
	v_mov_b32_e32 v18, v0
	v_mov_b32_e32 v19, v0
	v_mov_b32_e32 v20, v0
	v_mov_b32_e32 v21, v0
	v_mov_b32_e32 v22, v0
	v_mov_b32_e32 v23, v0
	v_mov_b32_e32 v32, v0
	v_mov_b32_e32 v33, v0
	v_mov_b32_e32 v34, v0
	v_mov_b32_e32 v35, v0
	v_mov_b32_e32 v36, v0
	v_mov_b32_e32 v37, v0
	v_mov_b32_e32 v38, v0
	v_mov_b32_e32 v39, v0
	v_mov_b32_e32 v48, v0
	v_mov_b32_e32 v49, v0
	v_mov_b32_e32 v50, v0
	v_mov_b32_e32 v51, v0
	v_mov_b32_e32 v52, v0
	v_mov_b32_e32 v53, v0
	v_mov_b32_e32 v54, v0
	v_mov_b32_e32 v55, v0
	v_mov_b32_e32 v8, v0
	v_mov_b32_e32 v9, v0
	v_mov_b32_e32 v10, v0
	v_mov_b32_e32 v11, v0
	v_mov_b32_e32 v12, v0
	v_mov_b32_e32 v13, v0
	v_mov_b32_e32 v14, v0
	v_mov_b32_e32 v15, v0
	v_mov_b32_e32 v24, v0
	v_mov_b32_e32 v25, v0
	v_mov_b32_e32 v26, v0
	v_mov_b32_e32 v27, v0
	v_mov_b32_e32 v28, v0
	v_mov_b32_e32 v29, v0
	v_mov_b32_e32 v30, v0
	v_mov_b32_e32 v31, v0
	v_mov_b32_e32 v40, v0
	v_mov_b32_e32 v41, v0
	v_mov_b32_e32 v42, v0
	v_mov_b32_e32 v43, v0
	v_mov_b32_e32 v44, v0
	v_mov_b32_e32 v45, v0
	v_mov_b32_e32 v46, v0
	v_mov_b32_e32 v47, v0
	v_mov_b32_e32 v56, v0
	v_mov_b32_e32 v57, v0
	v_mov_b32_e32 v58, v0
	v_mov_b32_e32 v59, v0
	v_mov_b32_e32 v60, v0
	v_mov_b32_e32 v61, v0
	v_mov_b32_e32 v62, v0
	v_mov_b32_e32 v63, v0
	v_mov_b32_e32 v64, v0
	v_mov_b32_e32 v65, v0
	v_mov_b32_e32 v66, v0
	v_mov_b32_e32 v67, v0
	v_mov_b32_e32 v68, v0
	v_mov_b32_e32 v69, v0
	v_mov_b32_e32 v70, v0
	v_mov_b32_e32 v71, v0
	v_mov_b32_e32 v80, v0
	v_mov_b32_e32 v81, v0
	v_mov_b32_e32 v82, v0
	v_mov_b32_e32 v83, v0
	v_mov_b32_e32 v84, v0
	v_mov_b32_e32 v85, v0
	v_mov_b32_e32 v86, v0
	v_mov_b32_e32 v87, v0
	v_mov_b32_e32 v96, v0
	v_mov_b32_e32 v97, v0
	v_mov_b32_e32 v98, v0
	v_mov_b32_e32 v99, v0
	v_mov_b32_e32 v100, v0
	v_mov_b32_e32 v101, v0
	v_mov_b32_e32 v102, v0
	v_mov_b32_e32 v103, v0
	v_mov_b32_e32 v112, v0
	v_mov_b32_e32 v113, v0
	v_mov_b32_e32 v114, v0
	v_mov_b32_e32 v115, v0
	v_mov_b32_e32 v116, v0
	v_mov_b32_e32 v117, v0
	v_mov_b32_e32 v118, v0
	v_mov_b32_e32 v119, v0
	v_mov_b32_e32 v72, v0
	s_waitcnt vmcnt(0)
	v_mov_b32_e32 v73, v0
	v_mov_b32_e32 v74, v0
	v_mov_b32_e32 v75, v0
	v_mov_b32_e32 v76, v0
	v_mov_b32_e32 v77, v0
	v_mov_b32_e32 v78, v0
	v_mov_b32_e32 v79, v0
	v_mov_b32_e32 v88, v0
	v_mov_b32_e32 v89, v0
	v_mov_b32_e32 v90, v0
	v_mov_b32_e32 v91, v0
	v_mov_b32_e32 v92, v0
	v_mov_b32_e32 v93, v0
	v_mov_b32_e32 v94, v0
	v_mov_b32_e32 v95, v0
	v_mov_b32_e32 v104, v0
	v_mov_b32_e32 v105, v0
	v_mov_b32_e32 v106, v0
	v_mov_b32_e32 v107, v0
	v_mov_b32_e32 v108, v0
	v_mov_b32_e32 v109, v0
	v_mov_b32_e32 v110, v0
	v_mov_b32_e32 v111, v0
	v_mov_b32_e32 v120, v0
	v_mov_b32_e32 v121, v0
	v_mov_b32_e32 v122, v0
	v_mov_b32_e32 v123, v0
	v_mov_b32_e32 v128, v0
	v_mov_b32_e32 v129, v0
	v_mov_b32_e32 v130, v0
	v_mov_b32_e32 v131, v0
	v_xor_b32_e32 v246, 64, v179
	v_xor_b32_e32 v247, 64, v167
	v_add_u32_e32 v248, s46, v247
	v_add_u32_e32 v249, s47, v247
	s_branch .LBB0_1113

.LBB0_1110:
	s_add_u32 s24, s24, 0x40080
	s_addc_u32 s25, s25, 0
	s_add_u32 s53, s26, 0x100
	s_addc_u32 s54, s27, 0
	s_mov_b32 s55, -2
	s_waitcnt vmcnt(0)
	v_xor_b32_e32 v246, 64, v179
	v_xor_b32_e32 v247, 64, v167
	v_add_u32_e32 v248, s46, v247
	v_add_u32_e32 v249, s47, v247
	ds_read_b128 v[124:127], v171
	ds_read_b128 v[132:135], v248
	ds_read_b128 v[136:139], v171 offset:2048
	ds_read_b128 v[140:143], v248 offset:2048
	ds_read_b128 v[162:165], v175
	ds_read_b128 v[182:185], v249
	ds_read_b128 v[186:189], v175 offset:2048
	ds_read_b128 v[190:193], v249 offset:2048
	s_add_u32 s26, s24, 0xfffc0080
	s_addc_u32 s27, s25, -1
	s_cmp_eq_u32 s55, 12
	s_cselect_b32 s29, s17, s27
	s_cselect_b32 s28, s51, s26
	s_cselect_b32 s27, s15, s54
	s_cselect_b32 s26, s52, s53
	v_lshl_add_u64 v[172:173], s[24:25], 0, v[152:153]
	s_add_i32 m0, s23, 0xc000
	ds_read_b128 v[194:197], v179
	ds_read_b128 v[198:201], v246
	ds_read_b128 v[202:205], v179 offset:2048
	ds_read_b128 v[206:209], v246 offset:2048
	ds_read_b128 v[210:213], v179 offset:4096
	ds_read_b128 v[214:217], v246 offset:4096
	ds_read_b128 v[218:221], v179 offset:6144
	ds_read_b128 v[222:225], v246 offset:6144
	global_load_lds_dwordx4 v[172:173], off
	v_lshl_add_u64 v[172:173], s[24:25], 0, v[154:155]
	s_add_i32 m0, s23, 0xe000
	s_nop 0
	global_load_lds_dwordx4 v[172:173], off
	s_waitcnt vmcnt(16)
	s_waitcnt lgkmcnt(0)
	s_barrier
	s_setprio 0
	s_waitcnt lgkmcnt(0)
	v_mfma_f32_16x16x32_bf16 v[128:131], v[124:127], v[194:197], 0
	s_add_i32 s39, s39, 1
	s_mul_i32 s0, s39, s42
	s_mul_hi_u32 s1, s39, s45
	v_mfma_f32_16x16x32_bf16 v[120:123], v[136:139], v[194:197], 0
	s_add_i32 s1, s1, s0
	s_mul_i32 s0, s39, s45
	s_add_u32 s18, s0, s96
	v_mfma_f32_16x16x32_bf16 v[108:111], v[124:127], v[202:205], 0
	s_addc_u32 s19, s1, s34
	v_cmp_lt_i64_e64 s[0:1], s[18:19], v[156:157]
	s_ashr_i32 s14, s18, 31
	v_mfma_f32_16x16x32_bf16 v[104:107], v[136:139], v[202:205], 0
	s_lshr_b32 s14, s14, 29
	s_add_i32 s14, s18, s14
	s_ashr_i32 s15, s14, 3
	v_mfma_f32_16x16x32_bf16 v[92:95], v[124:127], v[210:213], 0
	s_and_b32 s14, s14, -8
	s_sub_i32 s14, s18, s14
	s_cmp_lt_i32 s14, 0
	v_mfma_f32_16x16x32_bf16 v[88:91], v[136:139], v[210:213], 0
	s_cselect_b32 s16, s35, 0x160
	s_mul_i32 s14, s14, s16
	s_add_i32 s14, s14, s15
	v_mfma_f32_16x16x32_bf16 v[76:79], v[124:127], v[218:221], 0
	s_mul_hi_i32 s15, s14, 0x2e8ba2e9
	s_lshr_b32 s16, s15, 31
	s_ashr_i32 s15, s15, 5
	v_mfma_f32_16x16x32_bf16 v[72:75], v[136:139], v[218:221], 0
	s_add_i32 s15, s15, s16
	s_lshl_b32 s16, s15, 3
	s_sub_i32 s17, 0x80, s16
	v_mfma_f32_16x16x32_bf16 v[128:131], v[132:135], v[198:201], v[128:131]
	s_min_i32 s17, s17, 8
	s_abs_i32 s18, s17
	v_cvt_f32_u32_e32 v252, s18
	v_mfma_f32_16x16x32_bf16 v[120:123], v[140:143], v[198:201], v[120:123]
	s_sub_i32 s20, 0, s18
	s_mulk_i32 s15, 0xb0
	s_sub_i32 s15, s14, s15
	v_mfma_f32_16x16x32_bf16 v[108:111], v[132:135], v[206:209], v[108:111]
	v_rcp_iflag_f32_e32 v252, v252
	s_abs_i32 s14, s15
	s_xor_b32 s19, s15, s17
	v_mfma_f32_16x16x32_bf16 v[104:107], v[140:143], v[206:209], v[104:107]
	s_ashr_i32 s19, s19, 31
	v_mul_f32_e32 v252, 0x4f7ffffe, v252
	v_cvt_u32_f32_e32 v252, v252
	v_mfma_f32_16x16x32_bf16 v[92:95], v[132:135], v[214:217], v[92:95]
	s_nop 0
	v_readfirstlane_b32 s21, v252
	s_mul_i32 s20, s20, s21
	v_mfma_f32_16x16x32_bf16 v[88:91], v[140:143], v[214:217], v[88:91]
	s_mul_hi_u32 s20, s21, s20
	s_add_i32 s21, s21, s20
	s_mul_hi_u32 s20, s14, s21
	v_mfma_f32_16x16x32_bf16 v[76:79], v[132:135], v[222:225], v[76:79]
	s_mul_i32 s21, s20, s18
	s_sub_i32 s14, s14, s21
	s_add_i32 s98, s20, 1
	v_mfma_f32_16x16x32_bf16 v[72:75], v[140:143], v[222:225], v[72:75]
	s_sub_i32 s21, s14, s18
	s_cmp_ge_u32 s14, s18
	s_cselect_b32 s20, s98, s20
	s_setprio 0
	s_setprio 0
	v_mfma_f32_16x16x32_bf16 v[116:119], v[162:165], v[194:197], 0
	s_cselect_b32 s14, s21, s14
	s_add_i32 s21, s20, 1
	s_cmp_ge_u32 s14, s18
	v_mfma_f32_16x16x32_bf16 v[112:115], v[186:189], v[194:197], 0
	s_cselect_b32 s14, s21, s20
	s_xor_b32 s14, s14, s19
	s_sub_i32 s14, s14, s19
	v_mfma_f32_16x16x32_bf16 v[100:103], v[162:165], v[202:205], 0
	s_mul_i32 s17, s14, s17
	s_sub_i32 s15, s15, s17
	s_add_i32 s16, s16, s15
	v_mfma_f32_16x16x32_bf16 v[96:99], v[186:189], v[202:205], 0
	s_ashr_i32 s17, s16, 31
	s_lshl_b64 s[18:19], s[16:17], 19
	s_add_u32 s18, s2, s18
	v_mfma_f32_16x16x32_bf16 v[84:87], v[162:165], v[210:213], 0
	s_addc_u32 s19, s3, s19
	s_and_b64 s[20:21], s[0:1], exec
	s_cselect_b32 s17, s19, s25
	v_mfma_f32_16x16x32_bf16 v[80:83], v[186:189], v[210:213], 0
	s_cselect_b32 s51, s18, s24
	s_ashr_i32 s15, s14, 31
	s_lshl_b64 s[20:21], s[14:15], 19
	v_mfma_f32_16x16x32_bf16 v[68:71], v[162:165], v[218:221], 0
	s_add_u32 s20, s30, s20
	s_addc_u32 s21, s31, s21
	s_and_b64 s[98:99], s[0:1], exec
	v_mfma_f32_16x16x32_bf16 v[64:67], v[186:189], v[218:221], 0
	s_cselect_b32 s15, s21, s27
	s_cselect_b32 s52, s20, s26
	v_mfma_f32_16x16x32_bf16 v[116:119], v[182:185], v[198:201], v[116:119]
	v_mfma_f32_16x16x32_bf16 v[112:115], v[190:193], v[198:201], v[112:115]
	v_mfma_f32_16x16x32_bf16 v[100:103], v[182:185], v[206:209], v[100:103]
	v_mfma_f32_16x16x32_bf16 v[96:99], v[190:193], v[206:209], v[96:99]
	v_mfma_f32_16x16x32_bf16 v[84:87], v[182:185], v[214:217], v[84:87]
	v_mfma_f32_16x16x32_bf16 v[80:83], v[190:193], v[214:217], v[80:83]
	v_mfma_f32_16x16x32_bf16 v[68:71], v[182:185], v[222:225], v[68:71]
	v_mfma_f32_16x16x32_bf16 v[64:67], v[190:193], v[222:225], v[64:67]
	s_setprio 0
	s_barrier
	s_add_i32 s56, s46, s33
	v_lshl_add_u64 v[172:173], s[26:27], 0, v[148:149]
	s_mov_b32 m0, s56
	ds_read_b128 v[194:197], v179 offset:16384
	ds_read_b128 v[198:201], v246 offset:16384
	ds_read_b128 v[202:205], v179 offset:18432
	ds_read_b128 v[206:209], v246 offset:18432
	ds_read_b128 v[210:213], v179 offset:20480
	ds_read_b128 v[214:217], v246 offset:20480
	ds_read_b128 v[218:221], v179 offset:22528
	ds_read_b128 v[222:225], v246 offset:22528
	global_load_lds_dwordx4 v[172:173], off
	s_add_i32 m0, s56, 0x2000
	s_add_u32 s56, s26, 0x40000
	v_lshl_add_u64 v[176:177], s[26:27], 0, v[144:145]
	s_addc_u32 s57, s27, 0
	s_add_i32 s58, s47, s33
	global_load_lds_dwordx4 v[176:177], off
	v_lshl_add_u64 v[226:227], s[56:57], 0, v[148:149]
	s_mov_b32 m0, s58
	v_lshl_add_u64 v[228:229], s[28:29], 0, v[146:147]
	global_load_lds_dwordx4 v[226:227], off
	v_lshl_add_u64 v[226:227], s[56:57], 0, v[144:145]
	s_add_i32 m0, s58, 0x2000
	s_nop 0
	global_load_lds_dwordx4 v[226:227], off
	v_lshl_add_u64 v[226:227], s[28:29], 0, v[150:151]
	s_mov_b32 m0, s23
	s_nop 0
	global_load_lds_dwordx4 v[226:227], off
	s_mov_b32 m0, s36
	s_nop 0
	global_load_lds_dwordx4 v[228:229], off
	s_waitcnt vmcnt(16)
	s_waitcnt lgkmcnt(0)
	s_barrier
	s_setprio 0
	s_waitcnt lgkmcnt(0)
	v_mfma_f32_16x16x32_bf16 v[60:63], v[124:127], v[194:197], 0
	v_mfma_f32_16x16x32_bf16 v[56:59], v[136:139], v[194:197], 0
	v_mfma_f32_16x16x32_bf16 v[44:47], v[124:127], v[202:205], 0
	v_mfma_f32_16x16x32_bf16 v[40:43], v[136:139], v[202:205], 0
	v_mfma_f32_16x16x32_bf16 v[28:31], v[124:127], v[210:213], 0
	v_mfma_f32_16x16x32_bf16 v[24:27], v[136:139], v[210:213], 0
	v_mfma_f32_16x16x32_bf16 v[12:15], v[124:127], v[218:221], 0
	v_mfma_f32_16x16x32_bf16 v[8:11], v[136:139], v[218:221], 0
	v_mfma_f32_16x16x32_bf16 v[60:63], v[132:135], v[198:201], v[60:63]
	v_mfma_f32_16x16x32_bf16 v[56:59], v[140:143], v[198:201], v[56:59]
	v_mfma_f32_16x16x32_bf16 v[44:47], v[132:135], v[206:209], v[44:47]
	v_mfma_f32_16x16x32_bf16 v[40:43], v[140:143], v[206:209], v[40:43]
	v_mfma_f32_16x16x32_bf16 v[28:31], v[132:135], v[214:217], v[28:31]
	v_mfma_f32_16x16x32_bf16 v[24:27], v[140:143], v[214:217], v[24:27]
	v_mfma_f32_16x16x32_bf16 v[12:15], v[132:135], v[222:225], v[12:15]
	v_mfma_f32_16x16x32_bf16 v[8:11], v[140:143], v[222:225], v[8:11]
	s_setprio 0
	s_setprio 0
	v_mfma_f32_16x16x32_bf16 v[52:55], v[162:165], v[194:197], 0
	v_mfma_f32_16x16x32_bf16 v[48:51], v[186:189], v[194:197], 0
	v_mfma_f32_16x16x32_bf16 v[36:39], v[162:165], v[202:205], 0
	v_mfma_f32_16x16x32_bf16 v[32:35], v[186:189], v[202:205], 0
	v_mfma_f32_16x16x32_bf16 v[20:23], v[162:165], v[210:213], 0
	v_mfma_f32_16x16x32_bf16 v[16:19], v[186:189], v[210:213], 0
	v_mfma_f32_16x16x32_bf16 v[4:7], v[162:165], v[218:221], 0
	v_mfma_f32_16x16x32_bf16 v[0:3], v[186:189], v[218:221], 0
	v_mfma_f32_16x16x32_bf16 v[52:55], v[182:185], v[198:201], v[52:55]
	v_mfma_f32_16x16x32_bf16 v[48:51], v[190:193], v[198:201], v[48:51]
	v_mfma_f32_16x16x32_bf16 v[36:39], v[182:185], v[206:209], v[36:39]
	v_mfma_f32_16x16x32_bf16 v[32:35], v[190:193], v[206:209], v[32:35]
	v_mfma_f32_16x16x32_bf16 v[20:23], v[182:185], v[214:217], v[20:23]
	v_mfma_f32_16x16x32_bf16 v[16:19], v[190:193], v[214:217], v[16:19]
	v_mfma_f32_16x16x32_bf16 v[4:7], v[182:185], v[222:225], v[4:7]
	v_mfma_f32_16x16x32_bf16 v[0:3], v[190:193], v[222:225], v[0:3]
	s_setprio 0
	s_barrier
	s_add_i32 s56, 0, 0x18000
	s_add_i32 s57, 0, 0x1c000
	v_add_u32_e32 v140, s56, v167
	v_add_u32_e32 v250, s56, v247
	v_add_u32_e32 v160, s57, v167
	v_add_u32_e32 v251, s57, v247
	ds_read_b128 v[124:127], v140
	ds_read_b128 v[132:135], v250
	ds_read_b128 v[136:139], v140 offset:2048
	ds_read_b128 v[140:143], v250 offset:2048
	ds_read_b128 v[162:165], v160
	ds_read_b128 v[182:185], v251
	ds_read_b128 v[186:189], v160 offset:2048
	ds_read_b128 v[190:193], v251 offset:2048
	s_add_u32 s28, s28, 0x40000
	s_addc_u32 s29, s29, 0
	s_mov_b32 m0, s37
	v_lshl_add_u64 v[230:231], s[28:29], 0, v[150:151]
	ds_read_b128 v[194:197], v179 offset:32768
	ds_read_b128 v[198:201], v246 offset:32768
	ds_read_b128 v[202:205], v179 offset:34816
	ds_read_b128 v[206:209], v246 offset:34816
	ds_read_b128 v[210:213], v179 offset:36864
	ds_read_b128 v[214:217], v246 offset:36864
	ds_read_b128 v[218:221], v179 offset:38912
	ds_read_b128 v[222:225], v246 offset:38912
	global_load_lds_dwordx4 v[230:231], off
	v_lshl_add_u64 v[230:231], s[28:29], 0, v[146:147]
	s_mov_b32 m0, s38
	s_nop 0
	global_load_lds_dwordx4 v[230:231], off
	s_waitcnt vmcnt(8)
	s_waitcnt lgkmcnt(0)
	s_barrier
	s_setprio 0
	s_waitcnt lgkmcnt(0)
	v_mfma_f32_16x16x32_bf16 v[128:131], v[124:127], v[194:197], v[128:131]
	v_mfma_f32_16x16x32_bf16 v[120:123], v[136:139], v[194:197], v[120:123]
	v_mfma_f32_16x16x32_bf16 v[108:111], v[124:127], v[202:205], v[108:111]
	v_mfma_f32_16x16x32_bf16 v[104:107], v[136:139], v[202:205], v[104:107]
	v_mfma_f32_16x16x32_bf16 v[92:95], v[124:127], v[210:213], v[92:95]
	v_mfma_f32_16x16x32_bf16 v[88:91], v[136:139], v[210:213], v[88:91]
	v_mfma_f32_16x16x32_bf16 v[76:79], v[124:127], v[218:221], v[76:79]
	v_mfma_f32_16x16x32_bf16 v[72:75], v[136:139], v[218:221], v[72:75]
	v_mfma_f32_16x16x32_bf16 v[128:131], v[132:135], v[198:201], v[128:131]
	v_mfma_f32_16x16x32_bf16 v[120:123], v[140:143], v[198:201], v[120:123]
	v_mfma_f32_16x16x32_bf16 v[108:111], v[132:135], v[206:209], v[108:111]
	v_mfma_f32_16x16x32_bf16 v[104:107], v[140:143], v[206:209], v[104:107]
	v_mfma_f32_16x16x32_bf16 v[92:95], v[132:135], v[214:217], v[92:95]
	v_mfma_f32_16x16x32_bf16 v[88:91], v[140:143], v[214:217], v[88:91]
	v_mfma_f32_16x16x32_bf16 v[76:79], v[132:135], v[222:225], v[76:79]
	v_mfma_f32_16x16x32_bf16 v[72:75], v[140:143], v[222:225], v[72:75]
	s_setprio 0
	s_setprio 0
	v_mfma_f32_16x16x32_bf16 v[116:119], v[162:165], v[194:197], v[116:119]
	v_mfma_f32_16x16x32_bf16 v[112:115], v[186:189], v[194:197], v[112:115]
	v_mfma_f32_16x16x32_bf16 v[100:103], v[162:165], v[202:205], v[100:103]
	v_mfma_f32_16x16x32_bf16 v[96:99], v[186:189], v[202:205], v[96:99]
	v_mfma_f32_16x16x32_bf16 v[84:87], v[162:165], v[210:213], v[84:87]
	v_mfma_f32_16x16x32_bf16 v[80:83], v[186:189], v[210:213], v[80:83]
	v_mfma_f32_16x16x32_bf16 v[68:71], v[162:165], v[218:221], v[68:71]
	v_mfma_f32_16x16x32_bf16 v[64:67], v[186:189], v[218:221], v[64:67]
	v_mfma_f32_16x16x32_bf16 v[116:119], v[182:185], v[198:201], v[116:119]
	v_mfma_f32_16x16x32_bf16 v[112:115], v[190:193], v[198:201], v[112:115]
	v_mfma_f32_16x16x32_bf16 v[100:103], v[182:185], v[206:209], v[100:103]
	v_mfma_f32_16x16x32_bf16 v[96:99], v[190:193], v[206:209], v[96:99]
	v_mfma_f32_16x16x32_bf16 v[84:87], v[182:185], v[214:217], v[84:87]
	v_mfma_f32_16x16x32_bf16 v[80:83], v[190:193], v[214:217], v[80:83]
	v_mfma_f32_16x16x32_bf16 v[68:71], v[182:185], v[222:225], v[68:71]
	v_mfma_f32_16x16x32_bf16 v[64:67], v[190:193], v[222:225], v[64:67]
	s_setprio 0
	s_barrier
	s_add_i32 s28, s56, s33
	v_lshl_add_u64 v[172:173], v[172:173], 0, s[10:11]
	s_mov_b32 m0, s28
	ds_read_b128 v[194:197], v179 offset:49152
	ds_read_b128 v[198:201], v246 offset:49152
	ds_read_b128 v[202:205], v179 offset:51200
	ds_read_b128 v[206:209], v246 offset:51200
	ds_read_b128 v[210:213], v179 offset:53248
	ds_read_b128 v[214:217], v246 offset:53248
	ds_read_b128 v[218:221], v179 offset:55296
	ds_read_b128 v[222:225], v246 offset:55296
	global_load_lds_dwordx4 v[172:173], off
	s_add_i32 m0, s28, 0x2000
	s_add_u32 s26, s26, 0x40080
	v_lshl_add_u64 v[172:173], v[176:177], 0, s[10:11]
	s_addc_u32 s27, s27, 0
	s_add_i32 s28, s57, s33
	global_load_lds_dwordx4 v[172:173], off
	v_lshl_add_u64 v[172:173], s[26:27], 0, v[148:149]
	s_mov_b32 m0, s28
	s_nop 0
	global_load_lds_dwordx4 v[172:173], off
	v_lshl_add_u64 v[172:173], s[26:27], 0, v[144:145]
	s_add_i32 m0, s28, 0x2000
	s_nop 0
	global_load_lds_dwordx4 v[172:173], off
	v_lshl_add_u64 v[172:173], v[226:227], 0, s[10:11]
	s_mov_b32 m0, s43
	s_nop 0
	global_load_lds_dwordx4 v[172:173], off
	v_lshl_add_u64 v[172:173], v[228:229], 0, s[10:11]
	s_mov_b32 m0, s44
	s_nop 0
	global_load_lds_dwordx4 v[172:173], off
	s_waitcnt vmcnt(8)
	s_waitcnt lgkmcnt(0)
	s_barrier
	s_setprio 0
	s_waitcnt lgkmcnt(0)
	v_mfma_f32_16x16x32_bf16 v[60:63], v[124:127], v[194:197], v[60:63]
	v_mfma_f32_16x16x32_bf16 v[56:59], v[136:139], v[194:197], v[56:59]
	v_mfma_f32_16x16x32_bf16 v[44:47], v[124:127], v[202:205], v[44:47]
	v_mfma_f32_16x16x32_bf16 v[40:43], v[136:139], v[202:205], v[40:43]
	v_mfma_f32_16x16x32_bf16 v[28:31], v[124:127], v[210:213], v[28:31]
	v_mfma_f32_16x16x32_bf16 v[24:27], v[136:139], v[210:213], v[24:27]
	v_mfma_f32_16x16x32_bf16 v[12:15], v[124:127], v[218:221], v[12:15]
	v_mfma_f32_16x16x32_bf16 v[8:11], v[136:139], v[218:221], v[8:11]
	v_mfma_f32_16x16x32_bf16 v[60:63], v[132:135], v[198:201], v[60:63]
	v_mfma_f32_16x16x32_bf16 v[56:59], v[140:143], v[198:201], v[56:59]
	v_mfma_f32_16x16x32_bf16 v[44:47], v[132:135], v[206:209], v[44:47]
	v_mfma_f32_16x16x32_bf16 v[40:43], v[140:143], v[206:209], v[40:43]
	v_mfma_f32_16x16x32_bf16 v[28:31], v[132:135], v[214:217], v[28:31]
	v_mfma_f32_16x16x32_bf16 v[24:27], v[140:143], v[214:217], v[24:27]
	v_mfma_f32_16x16x32_bf16 v[12:15], v[132:135], v[222:225], v[12:15]
	v_mfma_f32_16x16x32_bf16 v[8:11], v[140:143], v[222:225], v[8:11]
	s_setprio 0
	s_setprio 0
	v_mfma_f32_16x16x32_bf16 v[52:55], v[162:165], v[194:197], v[52:55]
	v_mfma_f32_16x16x32_bf16 v[48:51], v[186:189], v[194:197], v[48:51]
	v_mfma_f32_16x16x32_bf16 v[36:39], v[162:165], v[202:205], v[36:39]
	v_mfma_f32_16x16x32_bf16 v[32:35], v[186:189], v[202:205], v[32:35]
	v_mfma_f32_16x16x32_bf16 v[20:23], v[162:165], v[210:213], v[20:23]
	v_mfma_f32_16x16x32_bf16 v[16:19], v[186:189], v[210:213], v[16:19]
	v_mfma_f32_16x16x32_bf16 v[4:7], v[162:165], v[218:221], v[4:7]
	v_mfma_f32_16x16x32_bf16 v[0:3], v[186:189], v[218:221], v[0:3]
	v_mfma_f32_16x16x32_bf16 v[52:55], v[182:185], v[198:201], v[52:55]
	v_mfma_f32_16x16x32_bf16 v[48:51], v[190:193], v[198:201], v[48:51]
	v_mfma_f32_16x16x32_bf16 v[36:39], v[182:185], v[206:209], v[36:39]
	v_mfma_f32_16x16x32_bf16 v[32:35], v[190:193], v[206:209], v[32:35]
	v_mfma_f32_16x16x32_bf16 v[20:23], v[182:185], v[214:217], v[20:23]
	v_mfma_f32_16x16x32_bf16 v[16:19], v[190:193], v[214:217], v[16:19]
	v_mfma_f32_16x16x32_bf16 v[4:7], v[182:185], v[222:225], v[4:7]
	v_mfma_f32_16x16x32_bf16 v[0:3], v[190:193], v[222:225], v[0:3]
	s_setprio 0
	s_barrier
	s_add_i32 s55, s55, 2
	s_add_u32 s24, s24, 0x100
	s_addc_u32 s25, s25, 0
	s_add_u32 s53, s53, 0x100
	s_addc_u32 s54, s54, 0
	s_cmp_gt_u32 s55, 13

.LBB0_1182:
	s_add_u32 s29, s82, 0x18000
	s_addc_u32 s30, s83, 0
	s_lshl_b32 s8, s8, 5
	s_and_b32 s18, s8, 0x60
	s_mov_b64 s[8:9], 0x80
	s_add_i32 m0, s24, 0x18000
	v_lshl_add_u64 v[6:7], v[6:7], 0, s[8:9]
	s_lshl_b32 s12, s0, 13
	s_lshl_b32 s13, s18, 7
	s_waitcnt vmcnt(2)
	s_barrier
	global_load_lds_dwordx4 v[6:7], off
	v_lshl_add_u64 v[4:5], v[4:5], 0, s[8:9]
	s_add_i32 m0, s24, 0x1a000
	s_add_i32 s31, s24, 0x8000
	s_add_i32 s33, s24, 0xa000
	global_load_lds_dwordx4 v[4:5], off
	v_lshl_add_u64 v[0:1], v[0:1], 0, s[8:9]
	s_mov_b32 m0, s31
	s_add_u32 s10, s16, 0xb0080
	global_load_lds_dwordx4 v[0:1], off
	v_lshl_add_u64 v[0:1], v[2:3], 0, s[8:9]
	s_mov_b32 m0, s33
	s_addc_u32 s11, s17, 0
	global_load_lds_dwordx4 v[0:1], off
	s_add_i32 m0, s24, 0x1c000
	v_lshl_add_u64 v[0:1], s[10:11], 0, v[130:131]
	global_load_lds_dwordx4 v[0:1], off
	v_lshl_add_u64 v[0:1], s[10:11], 0, v[134:135]
	s_add_i32 m0, s24, 0x1e000
	s_sext_i32_i8 s40, s5
	global_load_lds_dwordx4 v[0:1], off
	v_lshrrev_b32_e32 v1, 1, v236
	v_and_b32_e32 v1, 24, v1
	v_and_b32_e32 v0, 15, v236
	v_lshlrev_b32_e32 v2, 1, v1
	v_lshl_or_b32 v168, s0, 6, v0
	v_lshl_or_b32 v0, v0, 6, v2
	v_lshlrev_b32_e32 v2, 2, v236
	v_and_b32_e32 v2, 32, v2
	v_bitop3_b32 v3, v0, s12, v2 bitop3:0xde
	v_bitop3_b32 v169, v0, s13, v2 bitop3:0xde
	v_or_b32_e32 v170, s18, v1
	v_lshrrev_b32_e32 v1, 1, v8
	v_mul_lo_u32 v0, v10, s1
	s_mov_b32 s0, 0xb000
	s_cmpk_lt_u32 s4, 0x100
	v_mad_u64_u32 v[0:1], s[4:5], v1, s0, v[0:1]
	v_or_b32_e32 v0, v0, v9
	s_mov_b64 s[12:13], 0xb0080
	v_add_lshl_u32 v0, v0, v11, 1
	v_mov_b32_e32 v1, v131
	v_lshl_add_u64 v[136:137], v[0:1], 0, s[12:13]
	v_lshrrev_b32_e32 v1, 1, v12
	v_mul_lo_u32 v0, v13, s1
	v_mad_u64_u32 v[0:1], s[0:1], v1, s0, v[0:1]
	s_waitcnt vmcnt(6)
	v_or_b32_e32 v0, v0, v14
	s_cselect_b64 s[10:11], -1, 0
	v_add_lshl_u32 v0, v0, v15, 1
	v_mov_b32_e32 v1, v131
	s_add_i32 s35, 0, 0x10000
	s_add_i32 s36, 0, 0x14000
	s_ashr_i32 s34, s86, 31
	v_lshl_add_u64 v[138:139], v[0:1], 0, s[12:13]
	v_mov_b64_e32 v[140:141], 0x200
	v_mov_b64_e32 v[142:143], 0x1ff
	v_add_u32_e32 v171, s35, v169
	v_add_u32_e32 v172, s36, v169
	v_add_u32_e32 v173, 0, v3
	s_barrier
	v_sub_u32_e32 v136, v136, v252
	v_add_u32_e32 v136, v136, v128
	v_sub_u32_e32 v138, v138, v253
	v_add_u32_e32 v138, v138, v132
	v_and_b32_e32 v250, 63, v236
	v_and_b32_e32 v251, 15, v250
	v_lshrrev_b32_e32 v252, 4, v250
	v_and_b32_e32 v253, 7, v251
	v_xor_b32_e32 v252, v252, v253
	v_lshlrev_b32_e32 v252, 4, v252
	v_lshl_add_u32 v252, v251, 7, v252
	v_lshrrev_b32_e32 v250, 6, v236
	v_lshrrev_b32_e32 v251, 2, v250
	v_lshl_add_u32 v173, v251, 13, v252
	v_and_b32_e32 v251, 3, v250
	v_lshl_add_u32 v169, v251, 12, v252
	v_add_u32_e32 v171, s35, v169
	v_add_u32_e32 v172, s36, v169
	s_add_i32 s28, s28, 1
	s_mul_i32 s0, s28, s34
	s_mul_hi_u32 s1, s28, s86
	s_add_i32 s1, s1, s0
	s_mul_i32 s0, s28, s86
	s_add_u32 s0, s0, s96
	s_addc_u32 s1, s1, s2
	v_cmp_gt_i64_e32 vcc, s[0:1], v[142:143]
	v_cmp_lt_i64_e64 s[4:5], s[0:1], v[140:141]
	s_cbranch_vccnz .Lfu_1191
	s_ashr_i32 s1, s0, 31
	s_lshr_b32 s1, s1, 29
	s_add_i32 s12, s0, s1
	s_and_b32 s1, s12, -8
	s_sub_i32 s13, s0, s1
	s_cmp_gt_i32 s13, -1
	s_mov_b64 s[0:1], -1
	s_cbranch_scc0 .Lfu_1188
	s_lshl_b32 s18, s13, 6
	s_mov_b64 s[0:1], 0

.Lfu_1195:
	s_add_u32 s41, s16, 0x100
	v_mov_b32_e32 v0, 0
	s_addc_u32 s42, s17, 0
	s_mov_b32 s43, -2
	v_mov_b32_e32 v1, v0
	v_mov_b32_e32 v2, v0
	v_mov_b32_e32 v3, v0
	v_mov_b32_e32 v4, v0
	v_mov_b32_e32 v5, v0
	v_mov_b32_e32 v6, v0
	v_mov_b32_e32 v7, v0
	v_mov_b32_e32 v12, v0
	v_mov_b32_e32 v13, v0
	v_mov_b32_e32 v14, v0
	v_mov_b32_e32 v15, v0
	v_mov_b32_e32 v20, v0
	v_mov_b32_e32 v21, v0
	v_mov_b32_e32 v22, v0
	v_mov_b32_e32 v23, v0
	v_mov_b32_e32 v28, v0
	v_mov_b32_e32 v29, v0
	v_mov_b32_e32 v30, v0
	v_mov_b32_e32 v31, v0
	v_mov_b32_e32 v36, v0
	v_mov_b32_e32 v37, v0
	v_mov_b32_e32 v38, v0
	v_mov_b32_e32 v39, v0
	v_mov_b32_e32 v44, v0
	v_mov_b32_e32 v45, v0
	v_mov_b32_e32 v46, v0
	v_mov_b32_e32 v47, v0
	v_mov_b32_e32 v52, v0
	v_mov_b32_e32 v53, v0
	v_mov_b32_e32 v54, v0
	v_mov_b32_e32 v55, v0
	v_mov_b32_e32 v8, v0
	v_mov_b32_e32 v9, v0
	v_mov_b32_e32 v10, v0
	v_mov_b32_e32 v11, v0
	v_mov_b32_e32 v16, v0
	v_mov_b32_e32 v17, v0
	v_mov_b32_e32 v18, v0
	v_mov_b32_e32 v19, v0
	v_mov_b32_e32 v24, v0
	v_mov_b32_e32 v25, v0
	v_mov_b32_e32 v26, v0
	v_mov_b32_e32 v27, v0
	v_mov_b32_e32 v32, v0
	v_mov_b32_e32 v33, v0
	v_mov_b32_e32 v34, v0
	v_mov_b32_e32 v35, v0
	v_mov_b32_e32 v40, v0
	v_mov_b32_e32 v41, v0
	v_mov_b32_e32 v42, v0
	v_mov_b32_e32 v43, v0
	v_mov_b32_e32 v48, v0
	v_mov_b32_e32 v49, v0
	v_mov_b32_e32 v50, v0
	v_mov_b32_e32 v51, v0
	v_mov_b32_e32 v56, v0
	v_mov_b32_e32 v57, v0
	v_mov_b32_e32 v58, v0
	v_mov_b32_e32 v59, v0
	v_mov_b32_e32 v60, v0
	v_mov_b32_e32 v61, v0
	v_mov_b32_e32 v62, v0
	v_mov_b32_e32 v63, v0
	v_mov_b32_e32 v64, v0
	v_mov_b32_e32 v65, v0
	v_mov_b32_e32 v66, v0
	v_mov_b32_e32 v67, v0
	v_mov_b32_e32 v68, v0
	v_mov_b32_e32 v69, v0
	v_mov_b32_e32 v70, v0
	v_mov_b32_e32 v71, v0
	v_mov_b32_e32 v76, v0
	v_mov_b32_e32 v77, v0
	v_mov_b32_e32 v78, v0
	v_mov_b32_e32 v79, v0
	v_mov_b32_e32 v84, v0
	v_mov_b32_e32 v85, v0
	v_mov_b32_e32 v86, v0
	v_mov_b32_e32 v87, v0
	v_mov_b32_e32 v92, v0
	v_mov_b32_e32 v93, v0
	v_mov_b32_e32 v94, v0
	v_mov_b32_e32 v95, v0
	v_mov_b32_e32 v100, v0
	v_mov_b32_e32 v101, v0
	v_mov_b32_e32 v102, v0
	v_mov_b32_e32 v103, v0
	v_mov_b32_e32 v108, v0
	v_mov_b32_e32 v109, v0
	v_mov_b32_e32 v110, v0
	v_mov_b32_e32 v111, v0
	v_mov_b32_e32 v116, v0
	v_mov_b32_e32 v117, v0
	v_mov_b32_e32 v118, v0
	v_mov_b32_e32 v119, v0
	v_mov_b32_e32 v72, v0
	s_waitcnt vmcnt(0)
	v_mov_b32_e32 v73, v0
	v_mov_b32_e32 v74, v0
	v_mov_b32_e32 v75, v0
	v_mov_b32_e32 v80, v0
	v_mov_b32_e32 v81, v0
	v_mov_b32_e32 v82, v0
	v_mov_b32_e32 v83, v0
	v_mov_b32_e32 v88, v0
	v_mov_b32_e32 v89, v0
	v_mov_b32_e32 v90, v0
	v_mov_b32_e32 v91, v0
	v_mov_b32_e32 v96, v0
	v_mov_b32_e32 v97, v0
	v_mov_b32_e32 v98, v0
	v_mov_b32_e32 v99, v0
	v_mov_b32_e32 v104, v0
	v_mov_b32_e32 v105, v0
	v_mov_b32_e32 v106, v0
	v_mov_b32_e32 v107, v0
	v_mov_b32_e32 v112, v0
	v_mov_b32_e32 v113, v0
	v_mov_b32_e32 v114, v0
	v_mov_b32_e32 v115, v0
	v_mov_b32_e32 v120, v0
	v_mov_b32_e32 v121, v0
	v_mov_b32_e32 v122, v0
	v_mov_b32_e32 v123, v0
	v_mov_b32_e32 v124, v0
	v_mov_b32_e32 v125, v0
	v_mov_b32_e32 v126, v0
	v_mov_b32_e32 v127, v0
	v_xor_b32_e32 v246, 64, v173
	v_xor_b32_e32 v247, 64, v169
	v_add_u32_e32 v248, s35, v247
	v_add_u32_e32 v249, s36, v247
	s_branch .LBB0_1196

.LBB0_1195:
	s_add_u32 s41, s16, 0x100
	s_addc_u32 s42, s17, 0
	s_mov_b32 s43, -2
	s_waitcnt vmcnt(0)
	v_xor_b32_e32 v246, 64, v173
	v_xor_b32_e32 v247, 64, v169
	v_add_u32_e32 v248, s35, v247
	v_add_u32_e32 v249, s36, v247
	ds_read_b128 v[144:147], v171
	ds_read_b128 v[148:151], v248
	ds_read_b128 v[152:155], v171 offset:2048
	ds_read_b128 v[156:159], v248 offset:2048
	ds_read_b128 v[160:163], v172
	ds_read_b128 v[164:167], v249
	ds_read_b128 v[174:177], v172 offset:2048
	ds_read_b128 v[178:181], v249 offset:2048
	s_add_u32 s16, s14, 0x100
	s_addc_u32 s17, s15, 0
	s_cmp_eq_u32 s43, 40
	s_cselect_b32 s21, s5, s17
	s_cselect_b32 s20, s4, s16
	s_cselect_b32 s19, s13, s42
	s_cselect_b32 s18, s12, s41
	v_lshl_add_u64 v[214:215], s[14:15], 0, v[136:137]
	s_add_i32 m0, s24, 0xc000
	ds_read_b128 v[182:185], v173
	ds_read_b128 v[186:189], v246
	ds_read_b128 v[190:193], v173 offset:2048
	ds_read_b128 v[194:197], v246 offset:2048
	ds_read_b128 v[198:201], v173 offset:4096
	ds_read_b128 v[202:205], v246 offset:4096
	ds_read_b128 v[206:209], v173 offset:6144
	ds_read_b128 v[210:213], v246 offset:6144
	global_load_lds_dwordx4 v[214:215], off
	v_lshl_add_u64 v[214:215], s[14:15], 0, v[138:139]
	s_add_i32 m0, s24, 0xe000
	s_nop 0
	global_load_lds_dwordx4 v[214:215], off
	s_waitcnt vmcnt(40)
	s_waitcnt lgkmcnt(0)
	s_barrier
	s_setprio 0
	s_waitcnt lgkmcnt(0)
	v_mfma_f32_16x16x32_bf16 v[124:127], v[144:147], v[182:185], 0
	v_mfma_f32_16x16x32_bf16 v[120:123], v[152:155], v[182:185], 0
	v_mfma_f32_16x16x32_bf16 v[112:115], v[144:147], v[190:193], 0
	v_mfma_f32_16x16x32_bf16 v[104:107], v[152:155], v[190:193], 0
	v_mfma_f32_16x16x32_bf16 v[96:99], v[144:147], v[198:201], 0
	v_mfma_f32_16x16x32_bf16 v[88:91], v[152:155], v[198:201], 0
	v_mfma_f32_16x16x32_bf16 v[80:83], v[144:147], v[206:209], 0
	v_mfma_f32_16x16x32_bf16 v[72:75], v[152:155], v[206:209], 0
	v_mfma_f32_16x16x32_bf16 v[124:127], v[148:151], v[186:189], v[124:127]
	v_mfma_f32_16x16x32_bf16 v[120:123], v[156:159], v[186:189], v[120:123]
	v_mfma_f32_16x16x32_bf16 v[112:115], v[148:151], v[194:197], v[112:115]
	v_mfma_f32_16x16x32_bf16 v[104:107], v[156:159], v[194:197], v[104:107]
	v_mfma_f32_16x16x32_bf16 v[96:99], v[148:151], v[202:205], v[96:99]
	v_mfma_f32_16x16x32_bf16 v[88:91], v[156:159], v[202:205], v[88:91]
	v_mfma_f32_16x16x32_bf16 v[80:83], v[148:151], v[210:213], v[80:83]
	v_mfma_f32_16x16x32_bf16 v[72:75], v[156:159], v[210:213], v[72:75]
	s_setprio 0
	s_setprio 0
	v_mfma_f32_16x16x32_bf16 v[116:119], v[160:163], v[182:185], 0
	v_mfma_f32_16x16x32_bf16 v[108:111], v[174:177], v[182:185], 0
	v_mfma_f32_16x16x32_bf16 v[100:103], v[160:163], v[190:193], 0
	v_mfma_f32_16x16x32_bf16 v[92:95], v[174:177], v[190:193], 0
	v_mfma_f32_16x16x32_bf16 v[84:87], v[160:163], v[198:201], 0
	v_mfma_f32_16x16x32_bf16 v[76:79], v[174:177], v[198:201], 0
	v_mfma_f32_16x16x32_bf16 v[68:71], v[160:163], v[206:209], 0
	v_mfma_f32_16x16x32_bf16 v[64:67], v[174:177], v[206:209], 0
	v_mfma_f32_16x16x32_bf16 v[116:119], v[164:167], v[186:189], v[116:119]
	v_mfma_f32_16x16x32_bf16 v[108:111], v[178:181], v[186:189], v[108:111]
	v_mfma_f32_16x16x32_bf16 v[100:103], v[164:167], v[194:197], v[100:103]
	v_mfma_f32_16x16x32_bf16 v[92:95], v[178:181], v[194:197], v[92:95]
	v_mfma_f32_16x16x32_bf16 v[84:87], v[164:167], v[202:205], v[84:87]
	v_mfma_f32_16x16x32_bf16 v[76:79], v[178:181], v[202:205], v[76:79]
	v_mfma_f32_16x16x32_bf16 v[68:71], v[164:167], v[210:213], v[68:71]
	v_mfma_f32_16x16x32_bf16 v[64:67], v[178:181], v[210:213], v[64:67]
	s_setprio 0
	s_barrier
	s_add_i32 s14, s35, s23
	v_lshl_add_u64 v[214:215], s[18:19], 0, v[130:131]
	s_mov_b32 m0, s14
	ds_read_b128 v[182:185], v173 offset:16384
	ds_read_b128 v[186:189], v246 offset:16384
	ds_read_b128 v[190:193], v173 offset:18432
	ds_read_b128 v[194:197], v246 offset:18432
	ds_read_b128 v[198:201], v173 offset:20480
	ds_read_b128 v[202:205], v246 offset:20480
	ds_read_b128 v[206:209], v173 offset:22528
	ds_read_b128 v[210:213], v246 offset:22528
	global_load_lds_dwordx4 v[214:215], off
	s_add_i32 m0, s14, 0x2000
	s_add_u32 s14, s18, 0xb0000
	v_lshl_add_u64 v[216:217], s[18:19], 0, v[134:135]
	s_addc_u32 s15, s19, 0
	s_add_i32 s44, s36, s23
	global_load_lds_dwordx4 v[216:217], off
	v_lshl_add_u64 v[218:219], s[14:15], 0, v[130:131]
	s_mov_b32 m0, s44
	v_lshl_add_u64 v[220:221], s[20:21], 0, v[132:133]
	global_load_lds_dwordx4 v[218:219], off
	v_lshl_add_u64 v[218:219], s[14:15], 0, v[134:135]
	s_add_i32 m0, s44, 0x2000
	s_nop 0
	global_load_lds_dwordx4 v[218:219], off
	v_lshl_add_u64 v[218:219], s[20:21], 0, v[128:129]
	s_mov_b32 m0, s24
	s_nop 0
	global_load_lds_dwordx4 v[218:219], off
	s_mov_b32 m0, s25
	s_nop 0
	global_load_lds_dwordx4 v[220:221], off
	s_waitcnt vmcnt(40)
	s_waitcnt lgkmcnt(0)
	s_barrier
	s_setprio 0
	s_waitcnt lgkmcnt(0)
	v_mfma_f32_16x16x32_bf16 v[60:63], v[144:147], v[182:185], 0
	v_mfma_f32_16x16x32_bf16 v[56:59], v[152:155], v[182:185], 0
	v_mfma_f32_16x16x32_bf16 v[48:51], v[144:147], v[190:193], 0
	v_mfma_f32_16x16x32_bf16 v[40:43], v[152:155], v[190:193], 0
	v_mfma_f32_16x16x32_bf16 v[32:35], v[144:147], v[198:201], 0
	v_mfma_f32_16x16x32_bf16 v[24:27], v[152:155], v[198:201], 0
	v_mfma_f32_16x16x32_bf16 v[16:19], v[144:147], v[206:209], 0
	v_mfma_f32_16x16x32_bf16 v[8:11], v[152:155], v[206:209], 0
	v_mfma_f32_16x16x32_bf16 v[60:63], v[148:151], v[186:189], v[60:63]
	v_mfma_f32_16x16x32_bf16 v[56:59], v[156:159], v[186:189], v[56:59]
	v_mfma_f32_16x16x32_bf16 v[48:51], v[148:151], v[194:197], v[48:51]
	v_mfma_f32_16x16x32_bf16 v[40:43], v[156:159], v[194:197], v[40:43]
	v_mfma_f32_16x16x32_bf16 v[32:35], v[148:151], v[202:205], v[32:35]
	v_mfma_f32_16x16x32_bf16 v[24:27], v[156:159], v[202:205], v[24:27]
	v_mfma_f32_16x16x32_bf16 v[16:19], v[148:151], v[210:213], v[16:19]
	v_mfma_f32_16x16x32_bf16 v[8:11], v[156:159], v[210:213], v[8:11]
	s_setprio 0
	s_setprio 0
	v_mfma_f32_16x16x32_bf16 v[52:55], v[160:163], v[182:185], 0
	v_mfma_f32_16x16x32_bf16 v[44:47], v[174:177], v[182:185], 0
	v_mfma_f32_16x16x32_bf16 v[36:39], v[160:163], v[190:193], 0
	v_mfma_f32_16x16x32_bf16 v[28:31], v[174:177], v[190:193], 0
	v_mfma_f32_16x16x32_bf16 v[20:23], v[160:163], v[198:201], 0
	v_mfma_f32_16x16x32_bf16 v[12:15], v[174:177], v[198:201], 0
	v_mfma_f32_16x16x32_bf16 v[4:7], v[160:163], v[206:209], 0
	v_mfma_f32_16x16x32_bf16 v[0:3], v[174:177], v[206:209], 0
	v_mfma_f32_16x16x32_bf16 v[52:55], v[164:167], v[186:189], v[52:55]
	v_mfma_f32_16x16x32_bf16 v[44:47], v[178:181], v[186:189], v[44:47]
	v_mfma_f32_16x16x32_bf16 v[36:39], v[164:167], v[194:197], v[36:39]
	v_mfma_f32_16x16x32_bf16 v[28:31], v[178:181], v[194:197], v[28:31]
	v_mfma_f32_16x16x32_bf16 v[20:23], v[164:167], v[202:205], v[20:23]
	v_mfma_f32_16x16x32_bf16 v[12:15], v[178:181], v[202:205], v[12:15]
	v_mfma_f32_16x16x32_bf16 v[4:7], v[164:167], v[210:213], v[4:7]
	v_mfma_f32_16x16x32_bf16 v[0:3], v[178:181], v[210:213], v[0:3]
	s_setprio 0
	s_barrier
	s_add_i32 s44, 0, 0x18000
	s_add_i32 s45, 0, 0x1c000
	v_add_u32_e32 v156, s44, v169
	v_add_u32_e32 v250, s44, v247
	v_add_u32_e32 v178, s45, v169
	v_add_u32_e32 v251, s45, v247
	ds_read_b128 v[144:147], v156
	ds_read_b128 v[148:151], v250
	ds_read_b128 v[152:155], v156 offset:2048
	ds_read_b128 v[156:159], v250 offset:2048
	ds_read_b128 v[160:163], v178
	ds_read_b128 v[164:167], v251
	ds_read_b128 v[174:177], v178 offset:2048
	ds_read_b128 v[178:181], v251 offset:2048
	s_add_u32 s14, s20, 0xb0000
	s_addc_u32 s15, s21, 0
	s_mov_b32 m0, s26
	v_lshl_add_u64 v[222:223], s[14:15], 0, v[128:129]
	ds_read_b128 v[182:185], v173 offset:32768
	ds_read_b128 v[186:189], v246 offset:32768
	ds_read_b128 v[190:193], v173 offset:34816
	ds_read_b128 v[194:197], v246 offset:34816
	ds_read_b128 v[198:201], v173 offset:36864
	ds_read_b128 v[202:205], v246 offset:36864
	ds_read_b128 v[206:209], v173 offset:38912
	ds_read_b128 v[210:213], v246 offset:38912
	global_load_lds_dwordx4 v[222:223], off
	v_lshl_add_u64 v[222:223], s[14:15], 0, v[132:133]
	s_mov_b32 m0, s27
	s_nop 0
	global_load_lds_dwordx4 v[222:223], off
	s_waitcnt vmcnt(8)
	s_waitcnt lgkmcnt(0)
	s_barrier
	s_setprio 0
	s_waitcnt lgkmcnt(0)
	v_mfma_f32_16x16x32_bf16 v[124:127], v[144:147], v[182:185], v[124:127]
	v_mfma_f32_16x16x32_bf16 v[120:123], v[152:155], v[182:185], v[120:123]
	v_mfma_f32_16x16x32_bf16 v[112:115], v[144:147], v[190:193], v[112:115]
	v_mfma_f32_16x16x32_bf16 v[104:107], v[152:155], v[190:193], v[104:107]
	v_mfma_f32_16x16x32_bf16 v[96:99], v[144:147], v[198:201], v[96:99]
	v_mfma_f32_16x16x32_bf16 v[88:91], v[152:155], v[198:201], v[88:91]
	v_mfma_f32_16x16x32_bf16 v[80:83], v[144:147], v[206:209], v[80:83]
	v_mfma_f32_16x16x32_bf16 v[72:75], v[152:155], v[206:209], v[72:75]
	v_mfma_f32_16x16x32_bf16 v[124:127], v[148:151], v[186:189], v[124:127]
	v_mfma_f32_16x16x32_bf16 v[120:123], v[156:159], v[186:189], v[120:123]
	v_mfma_f32_16x16x32_bf16 v[112:115], v[148:151], v[194:197], v[112:115]
	v_mfma_f32_16x16x32_bf16 v[104:107], v[156:159], v[194:197], v[104:107]
	v_mfma_f32_16x16x32_bf16 v[96:99], v[148:151], v[202:205], v[96:99]
	v_mfma_f32_16x16x32_bf16 v[88:91], v[156:159], v[202:205], v[88:91]
	v_mfma_f32_16x16x32_bf16 v[80:83], v[148:151], v[210:213], v[80:83]
	v_mfma_f32_16x16x32_bf16 v[72:75], v[156:159], v[210:213], v[72:75]
	s_setprio 0
	s_setprio 0
	v_mfma_f32_16x16x32_bf16 v[116:119], v[160:163], v[182:185], v[116:119]
	v_mfma_f32_16x16x32_bf16 v[108:111], v[174:177], v[182:185], v[108:111]
	v_mfma_f32_16x16x32_bf16 v[100:103], v[160:163], v[190:193], v[100:103]
	v_mfma_f32_16x16x32_bf16 v[92:95], v[174:177], v[190:193], v[92:95]
	v_mfma_f32_16x16x32_bf16 v[84:87], v[160:163], v[198:201], v[84:87]
	v_mfma_f32_16x16x32_bf16 v[76:79], v[174:177], v[198:201], v[76:79]
	v_mfma_f32_16x16x32_bf16 v[68:71], v[160:163], v[206:209], v[68:71]
	v_mfma_f32_16x16x32_bf16 v[64:67], v[174:177], v[206:209], v[64:67]
	v_mfma_f32_16x16x32_bf16 v[116:119], v[164:167], v[186:189], v[116:119]
	v_mfma_f32_16x16x32_bf16 v[108:111], v[178:181], v[186:189], v[108:111]
	v_mfma_f32_16x16x32_bf16 v[100:103], v[164:167], v[194:197], v[100:103]
	v_mfma_f32_16x16x32_bf16 v[92:95], v[178:181], v[194:197], v[92:95]
	v_mfma_f32_16x16x32_bf16 v[84:87], v[164:167], v[202:205], v[84:87]
	v_mfma_f32_16x16x32_bf16 v[76:79], v[178:181], v[202:205], v[76:79]
	v_mfma_f32_16x16x32_bf16 v[68:71], v[164:167], v[210:213], v[68:71]
	v_mfma_f32_16x16x32_bf16 v[64:67], v[178:181], v[210:213], v[64:67]
	s_setprio 0
	s_barrier
	s_add_i32 s14, s44, s23
	v_lshl_add_u64 v[214:215], v[214:215], 0, s[8:9]
	s_mov_b32 m0, s14
	ds_read_b128 v[182:185], v173 offset:49152
	ds_read_b128 v[186:189], v246 offset:49152
	ds_read_b128 v[190:193], v173 offset:51200
	ds_read_b128 v[194:197], v246 offset:51200
	ds_read_b128 v[198:201], v173 offset:53248
	ds_read_b128 v[202:205], v246 offset:53248
	ds_read_b128 v[206:209], v173 offset:55296
	ds_read_b128 v[210:213], v246 offset:55296
	global_load_lds_dwordx4 v[214:215], off
	s_add_i32 m0, s14, 0x2000
	s_add_u32 s14, s18, 0xb0080
	v_lshl_add_u64 v[214:215], v[216:217], 0, s[8:9]
	s_addc_u32 s15, s19, 0
	s_add_i32 s18, s45, s23
	global_load_lds_dwordx4 v[214:215], off
	v_lshl_add_u64 v[214:215], s[14:15], 0, v[130:131]
	s_mov_b32 m0, s18
	s_nop 0
	global_load_lds_dwordx4 v[214:215], off
	v_lshl_add_u64 v[214:215], s[14:15], 0, v[134:135]
	s_add_i32 m0, s18, 0x2000
	s_nop 0
	global_load_lds_dwordx4 v[214:215], off
	v_lshl_add_u64 v[214:215], v[218:219], 0, s[8:9]
	s_mov_b32 m0, s31
	s_nop 0
	global_load_lds_dwordx4 v[214:215], off
	v_lshl_add_u64 v[214:215], v[220:221], 0, s[8:9]
	s_mov_b32 m0, s33
	s_nop 0
	global_load_lds_dwordx4 v[214:215], off
	s_waitcnt vmcnt(8)
	s_waitcnt lgkmcnt(0)
	s_barrier
	s_setprio 0
	s_waitcnt lgkmcnt(0)
	v_mfma_f32_16x16x32_bf16 v[60:63], v[144:147], v[182:185], v[60:63]
	v_mfma_f32_16x16x32_bf16 v[56:59], v[152:155], v[182:185], v[56:59]
	v_mfma_f32_16x16x32_bf16 v[48:51], v[144:147], v[190:193], v[48:51]
	v_mfma_f32_16x16x32_bf16 v[40:43], v[152:155], v[190:193], v[40:43]
	v_mfma_f32_16x16x32_bf16 v[32:35], v[144:147], v[198:201], v[32:35]
	v_mfma_f32_16x16x32_bf16 v[24:27], v[152:155], v[198:201], v[24:27]
	v_mfma_f32_16x16x32_bf16 v[16:19], v[144:147], v[206:209], v[16:19]
	v_mfma_f32_16x16x32_bf16 v[8:11], v[152:155], v[206:209], v[8:11]
	v_mfma_f32_16x16x32_bf16 v[60:63], v[148:151], v[186:189], v[60:63]
	v_mfma_f32_16x16x32_bf16 v[56:59], v[156:159], v[186:189], v[56:59]
	v_mfma_f32_16x16x32_bf16 v[48:51], v[148:151], v[194:197], v[48:51]
	v_mfma_f32_16x16x32_bf16 v[40:43], v[156:159], v[194:197], v[40:43]
	v_mfma_f32_16x16x32_bf16 v[32:35], v[148:151], v[202:205], v[32:35]
	v_mfma_f32_16x16x32_bf16 v[24:27], v[156:159], v[202:205], v[24:27]
	v_mfma_f32_16x16x32_bf16 v[16:19], v[148:151], v[210:213], v[16:19]
	v_mfma_f32_16x16x32_bf16 v[8:11], v[156:159], v[210:213], v[8:11]
	s_setprio 0
	s_setprio 0
	v_mfma_f32_16x16x32_bf16 v[52:55], v[160:163], v[182:185], v[52:55]
	v_mfma_f32_16x16x32_bf16 v[44:47], v[174:177], v[182:185], v[44:47]
	v_mfma_f32_16x16x32_bf16 v[36:39], v[160:163], v[190:193], v[36:39]
	v_mfma_f32_16x16x32_bf16 v[28:31], v[174:177], v[190:193], v[28:31]
	v_mfma_f32_16x16x32_bf16 v[20:23], v[160:163], v[198:201], v[20:23]
	v_mfma_f32_16x16x32_bf16 v[12:15], v[174:177], v[198:201], v[12:15]
	v_mfma_f32_16x16x32_bf16 v[4:7], v[160:163], v[206:209], v[4:7]
	v_mfma_f32_16x16x32_bf16 v[0:3], v[174:177], v[206:209], v[0:3]
	v_mfma_f32_16x16x32_bf16 v[52:55], v[164:167], v[186:189], v[52:55]
	v_mfma_f32_16x16x32_bf16 v[44:47], v[178:181], v[186:189], v[44:47]
	v_mfma_f32_16x16x32_bf16 v[36:39], v[164:167], v[194:197], v[36:39]
	v_mfma_f32_16x16x32_bf16 v[28:31], v[178:181], v[194:197], v[28:31]
	v_mfma_f32_16x16x32_bf16 v[20:23], v[164:167], v[202:205], v[20:23]
	v_mfma_f32_16x16x32_bf16 v[12:15], v[178:181], v[202:205], v[12:15]
	v_mfma_f32_16x16x32_bf16 v[4:7], v[164:167], v[210:213], v[4:7]
	v_mfma_f32_16x16x32_bf16 v[0:3], v[178:181], v[210:213], v[0:3]
	s_setprio 0
	s_barrier
	s_add_i32 s43, s43, 2
	s_add_u32 s41, s41, 0x100
	s_addc_u32 s42, s42, 0
	s_cmp_gt_u32 s43, 41
	s_mov_b64 s[14:15], s[16:17]
